# 4-phase GEMM loops + ds_reads issued before the LDS-DMA stagings in phases 1,2,4 where register-safe
# baseline (speedup 1.0000x reference)
; #define PG8_STAGE(bufoff, gbase, voff) do { _Pragma("unroll") for (int _i = 0; _i < 2; ++_i) \
;         __builtin_amdgcn_global_load_lds((const unsigned*)((const char*)(gbase) + (voff)[_i]), (LAS unsigned*)(lds + (bufoff) + ldsw + _i * 8192), 16, 0, 0); } while (0)
; #define PG8_LDA(dst, b, h) do { _Pragma("unroll") for (int m = 0; m < 4; ++m) _Pragma("unroll") for (int k = 0; k < 2; ++k) dst[m][k] = *(const LAS bf16x8*)(lds + PG8_SA(b, h) + aoff + m * 2048 + k * 1024); } while (0)
; #define PG8_LDB(dst, b, h) do { _Pragma("unroll") for (int n = 0; n < 2; ++n) _Pragma("unroll") for (int k = 0; k < 2; ++k) dst[n][k] = *(const LAS bf16x8*)(lds + PG8_SB(b, h) + boff + n * 2048 + k * 1024); } while (0)
; #define PG8_MMA(ai, bj, At, Bt) do { __builtin_amdgcn_s_setprio(1); _Pragma("unroll") for (int m = 0; m < 4; ++m) _Pragma("unroll") for (int n = 0; n < 2; ++n) _Pragma("unroll") for (int k = 0; k < 2; ++k) \
;         acc[ai][bj][m][n] = __builtin_amdgcn_mfma_f32_16x16x32_bf16(Bt[n][k], At[m][k], acc[ai][bj][m][n], 0, 0, 0); __builtin_amdgcn_s_setprio(0); } while (0)
; #define PG8_WAIT_L(n) asm volatile("s_waitcnt lgkmcnt(" #n ")" ::: "memory")
; #define PG8_BAR __builtin_amdgcn_s_barrier()
; #define PG8_SCHED __builtin_amdgcn_sched_barrier(0)
; template <class Epi, class Sched>
; __device__ __forceinline__ void gemm_phase(LAS unsigned char* lds, const Gemm g, const Sched& S, const Epi& E) {
;     ...
;             const bool last = (t == nt - 2);
;             const char* a1 = cA + (size_t)(t + 1) * kstep;
;             const char* a2 = last ? nA : cA + (size_t)(t + 2) * kstep; const char* b2 = last ? nB : cB + (size_t)(t + 2) * kstep;
;             const char* a3 = a2 + kstep; const char* b3 = b2 + kstep;
;             PG8_LDB(B0, 0, 0); PG8_SCHED; PG8_LDA(At, 0, 0); PG8_STAGE(PG8_SA(1, 1), a1 + hstep, voffA);
;             PG8_WAIT_L(8); PG8_BAR; PG8_WAIT_L(0); PG8_MMA(0, 0, At, B0); PG8_BAR; PG8_SCHED;
;             PG8_LDB(B1, 0, 1); PG8_STAGE(PG8_SB(0, 0), b2, voffB);
;             PG8_BAR; PG8_WAIT_L(0); PG8_MMA(0, 1, At, B1); PG8_BAR;
;             PG8_LDA(At, 0, 1); PG8_STAGE(PG8_SA(0, 0), a2, voffA);
;             PG8_BAR; PG8_WAIT_L(0); PG8_MMA(1, 0, At, B0); PG8_BAR; PG8_SCHED;
.LBB0_44:
	s_add_i32 s38, 0, 0x10000
	v_add_u32_e32 v78, s38, v163
	ds_read_b128 v[66:69], v78
	ds_read_b128 v[70:73], v78 offset:1024
	ds_read_b128 v[74:77], v78 offset:2048
	ds_read_b128 v[78:81], v78 offset:3072
	ds_read_b128 v[152:155], v165
	ds_read_b128 v[166:169], v165 offset:1024
	ds_read_b128 v[170:173], v165 offset:2048
	ds_read_b128 v[174:177], v165 offset:3072
	ds_read_b128 v[178:181], v165 offset:4096
	ds_read_b128 v[182:185], v165 offset:5120
	ds_read_b128 v[186:189], v165 offset:6144
	ds_read_b128 v[190:193], v165 offset:7168
	s_add_i32 s39, 0, 0x14000
	v_add_u32_e32 v156, s39, v163
	ds_read_b128 v[194:197], v156
	ds_read_b128 v[198:201], v156 offset:1024
	ds_read_b128 v[202:205], v156 offset:2048
	ds_read_b128 v[210:213], v156 offset:3072
	s_add_u32 s50, s28, 0x100
	s_addc_u32 s51, s29, 0
	s_cmpk_eq_i32 s75, 0x7c
	s_cselect_b32 s55, s27, s51
	s_cselect_b32 s54, s71, s50
	s_cselect_b32 s53, s25, s74
	s_cselect_b32 s52, s72, s73
	v_lshl_add_u64 v[156:157], s[28:29], 0, v[150:151]
	s_add_i32 m0, s9, 0xc000
	s_nop 0
	global_load_lds_dwordx4 v[156:157], off
	v_lshl_add_u64 v[156:157], s[28:29], 0, v[148:149]
	s_add_i32 m0, s9, 0xe000
	s_nop 0
	global_load_lds_dwordx4 v[156:157], off
	s_waitcnt lgkmcnt(4)
	s_barrier
	s_waitcnt lgkmcnt(0)
	s_setprio 1
	v_mfma_f32_16x16x32_bf16 v[142:145], v[66:69], v[152:155], v[142:145]
	v_mfma_f32_16x16x32_bf16 v[138:141], v[74:77], v[152:155], v[138:141]
	v_mfma_f32_16x16x32_bf16 v[126:129], v[66:69], v[170:173], v[126:129]
	v_mfma_f32_16x16x32_bf16 v[122:125], v[74:77], v[170:173], v[122:125]
	v_mfma_f32_16x16x32_bf16 v[110:113], v[66:69], v[178:181], v[110:113]
	v_mfma_f32_16x16x32_bf16 v[106:109], v[74:77], v[178:181], v[106:109]
	v_mfma_f32_16x16x32_bf16 v[102:105], v[66:69], v[186:189], v[102:105]
	v_mfma_f32_16x16x32_bf16 v[98:101], v[74:77], v[186:189], v[98:101]
	v_mfma_f32_16x16x32_bf16 v[142:145], v[70:73], v[166:169], v[142:145]
	v_mfma_f32_16x16x32_bf16 v[138:141], v[78:81], v[166:169], v[138:141]
	v_mfma_f32_16x16x32_bf16 v[126:129], v[70:73], v[174:177], v[126:129]
	v_mfma_f32_16x16x32_bf16 v[122:125], v[78:81], v[174:177], v[122:125]
	v_mfma_f32_16x16x32_bf16 v[110:113], v[70:73], v[182:185], v[110:113]
	v_mfma_f32_16x16x32_bf16 v[106:109], v[78:81], v[182:185], v[106:109]
	v_mfma_f32_16x16x32_bf16 v[102:105], v[70:73], v[190:193], v[102:105]
	v_mfma_f32_16x16x32_bf16 v[98:101], v[78:81], v[190:193], v[98:101]
	v_mfma_f32_16x16x32_bf16 v[134:137], v[194:197], v[152:155], v[134:137]
	v_mfma_f32_16x16x32_bf16 v[130:133], v[202:205], v[152:155], v[130:133]
	v_mfma_f32_16x16x32_bf16 v[118:121], v[194:197], v[170:173], v[118:121]
	v_mfma_f32_16x16x32_bf16 v[114:117], v[202:205], v[170:173], v[114:117]
	v_mfma_f32_16x16x32_bf16 v[94:97], v[194:197], v[178:181], v[94:97]
	v_mfma_f32_16x16x32_bf16 v[90:93], v[202:205], v[178:181], v[90:93]
	v_mfma_f32_16x16x32_bf16 v[86:89], v[194:197], v[186:189], v[86:89]
	v_mfma_f32_16x16x32_bf16 v[82:85], v[202:205], v[186:189], v[82:85]
	v_mfma_f32_16x16x32_bf16 v[134:137], v[198:201], v[166:169], v[134:137]
	v_mfma_f32_16x16x32_bf16 v[130:133], v[210:213], v[166:169], v[130:133]
	v_mfma_f32_16x16x32_bf16 v[118:121], v[198:201], v[174:177], v[118:121]
	v_mfma_f32_16x16x32_bf16 v[114:117], v[210:213], v[174:177], v[114:117]
	v_mfma_f32_16x16x32_bf16 v[94:97], v[198:201], v[182:185], v[94:97]
	v_mfma_f32_16x16x32_bf16 v[90:93], v[210:213], v[182:185], v[90:93]
	v_mfma_f32_16x16x32_bf16 v[86:89], v[198:201], v[190:193], v[86:89]
	v_mfma_f32_16x16x32_bf16 v[82:85], v[210:213], v[190:193], v[82:85]
	s_setprio 0
	s_barrier
	ds_read_b128 v[152:155], v165 offset:16384
	ds_read_b128 v[166:169], v165 offset:17408
	ds_read_b128 v[170:173], v165 offset:18432
	ds_read_b128 v[174:177], v165 offset:19456
	ds_read_b128 v[178:181], v165 offset:20480
	ds_read_b128 v[182:185], v165 offset:21504
	ds_read_b128 v[186:189], v165 offset:22528
	ds_read_b128 v[190:193], v165 offset:23552
	s_add_i32 s28, s38, s60
	v_lshl_add_u64 v[156:157], s[52:53], 0, v[0:1]
	s_mov_b32 m0, s28
	v_lshl_add_u64 v[160:161], s[52:53], 0, v[146:147]
	global_load_lds_dwordx4 v[156:157], off
	s_add_i32 m0, s28, 0x2000
	s_nop 0
	global_load_lds_dwordx4 v[160:161], off
	s_mov_b32 m0, s9
	v_lshl_add_u64 v[206:207], s[54:55], 0, v[0:1]
	global_load_lds_dwordx4 v[206:207], off
	v_lshl_add_u64 v[214:215], s[54:55], 0, v[146:147]
	s_mov_b32 m0, s61
	s_nop 0
	global_load_lds_dwordx4 v[214:215], off
	s_waitcnt vmcnt(4)
	s_waitcnt lgkmcnt(0)
	s_barrier
	s_setprio 1
	v_mfma_f32_16x16x32_bf16 v[62:65], v[66:69], v[152:155], v[62:65]
	v_mfma_f32_16x16x32_bf16 v[58:61], v[74:77], v[152:155], v[58:61]
	v_mfma_f32_16x16x32_bf16 v[46:49], v[66:69], v[170:173], v[46:49]
	v_mfma_f32_16x16x32_bf16 v[42:45], v[74:77], v[170:173], v[42:45]
	v_mfma_f32_16x16x32_bf16 v[30:33], v[66:69], v[178:181], v[30:33]
	v_mfma_f32_16x16x32_bf16 v[26:29], v[74:77], v[178:181], v[26:29]
	v_mfma_f32_16x16x32_bf16 v[22:25], v[66:69], v[186:189], v[22:25]
	v_mfma_f32_16x16x32_bf16 v[14:17], v[74:77], v[186:189], v[14:17]
	v_mfma_f32_16x16x32_bf16 v[62:65], v[70:73], v[166:169], v[62:65]
	v_mfma_f32_16x16x32_bf16 v[58:61], v[78:81], v[166:169], v[58:61]
	v_mfma_f32_16x16x32_bf16 v[46:49], v[70:73], v[174:177], v[46:49]
	v_mfma_f32_16x16x32_bf16 v[42:45], v[78:81], v[174:177], v[42:45]
	v_mfma_f32_16x16x32_bf16 v[30:33], v[70:73], v[182:185], v[30:33]
	v_mfma_f32_16x16x32_bf16 v[26:29], v[78:81], v[182:185], v[26:29]
	v_mfma_f32_16x16x32_bf16 v[22:25], v[70:73], v[190:193], v[22:25]
	v_mfma_f32_16x16x32_bf16 v[14:17], v[78:81], v[190:193], v[14:17]
	v_mfma_f32_16x16x32_bf16 v[54:57], v[194:197], v[152:155], v[54:57]
	v_mfma_f32_16x16x32_bf16 v[50:53], v[202:205], v[152:155], v[50:53]
	v_mfma_f32_16x16x32_bf16 v[38:41], v[194:197], v[170:173], v[38:41]
	v_mfma_f32_16x16x32_bf16 v[34:37], v[202:205], v[170:173], v[34:37]
	v_mfma_f32_16x16x32_bf16 v[18:21], v[194:197], v[178:181], v[18:21]
	v_mfma_f32_16x16x32_bf16 v[10:13], v[202:205], v[178:181], v[10:13]
	v_mfma_f32_16x16x32_bf16 v[6:9], v[194:197], v[186:189], v[6:9]
	v_mfma_f32_16x16x32_bf16 v[2:5], v[202:205], v[186:189], v[2:5]
	v_mfma_f32_16x16x32_bf16 v[54:57], v[198:201], v[166:169], v[54:57]
	v_mfma_f32_16x16x32_bf16 v[50:53], v[210:213], v[166:169], v[50:53]
	v_mfma_f32_16x16x32_bf16 v[38:41], v[198:201], v[174:177], v[38:41]
	v_mfma_f32_16x16x32_bf16 v[34:37], v[210:213], v[174:177], v[34:37]
	v_mfma_f32_16x16x32_bf16 v[18:21], v[198:201], v[182:185], v[18:21]
	v_mfma_f32_16x16x32_bf16 v[10:13], v[210:213], v[182:185], v[10:13]
	v_mfma_f32_16x16x32_bf16 v[6:9], v[198:201], v[190:193], v[6:9]
	v_mfma_f32_16x16x32_bf16 v[2:5], v[210:213], v[190:193], v[2:5]
	s_setprio 0
	s_barrier
; #define PG8_STAGE(bufoff, gbase, voff) do { _Pragma("unroll") for (int _i = 0; _i < 2; ++_i) \
;         __builtin_amdgcn_global_load_lds((const unsigned*)((const char*)(gbase) + (voff)[_i]), (LAS unsigned*)(lds + (bufoff) + ldsw + _i * 8192), 16, 0, 0); } while (0)
; #define PG8_LDA(dst, b, h) do { _Pragma("unroll") for (int m = 0; m < 4; ++m) _Pragma("unroll") for (int k = 0; k < 2; ++k) dst[m][k] = *(const LAS bf16x8*)(lds + PG8_SA(b, h) + aoff + m * 2048 + k * 1024); } while (0)
; #define PG8_LDB(dst, b, h) do { _Pragma("unroll") for (int n = 0; n < 2; ++n) _Pragma("unroll") for (int k = 0; k < 2; ++k) dst[n][k] = *(const LAS bf16x8*)(lds + PG8_SB(b, h) + boff + n * 2048 + k * 1024); } while (0)
; #define PG8_MMA(ai, bj, At, Bt) do { __builtin_amdgcn_s_setprio(1); _Pragma("unroll") for (int m = 0; m < 4; ++m) _Pragma("unroll") for (int n = 0; n < 2; ++n) _Pragma("unroll") for (int k = 0; k < 2; ++k) \
;         acc[ai][bj][m][n] = __builtin_amdgcn_mfma_f32_16x16x32_bf16(Bt[n][k], At[m][k], acc[ai][bj][m][n], 0, 0, 0); __builtin_amdgcn_s_setprio(0); } while (0)
; #define PG8_WAIT_V(n) asm volatile("s_waitcnt vmcnt(" #n ")" ::: "memory")
; #define PG8_WAIT_L(n) asm volatile("s_waitcnt lgkmcnt(" #n ")" ::: "memory")
; #define PG8_BAR __builtin_amdgcn_s_barrier()
; #define PG8_SCHED __builtin_amdgcn_sched_barrier(0)
; template <class Epi, class Sched>
; __device__ __forceinline__ void gemm_phase(LAS unsigned char* lds, const Gemm g, const Sched& S, const Epi& E) {
;     ...
;             PG8_STAGE(PG8_SB(0, 1), b2 + hstep, voffB);
;             PG8_WAIT_V(6); PG8_BAR; PG8_MMA(1, 1, At, B1); PG8_BAR;
;             PG8_LDB(B0, 1, 0); PG8_SCHED; PG8_LDA(At, 1, 0); PG8_STAGE(PG8_SA(0, 1), a2 + hstep, voffA);
;             PG8_WAIT_L(8); PG8_BAR; PG8_WAIT_L(0); PG8_MMA(0, 0, At, B0); PG8_BAR; PG8_SCHED;
	s_add_u32 s28, s52, 0x200000
	s_addc_u32 s29, s53, 0
	s_add_i32 s38, s39, s60
	v_lshl_add_u64 v[66:67], s[28:29], 0, v[0:1]
	s_mov_b32 m0, s38
	s_nop 0
	global_load_lds_dwordx4 v[66:67], off
	v_lshl_add_u64 v[66:67], s[28:29], 0, v[146:147]
	s_add_i32 m0, s38, 0x2000
	s_nop 0
	global_load_lds_dwordx4 v[66:67], off
	s_add_u32 s28, s54, 0x200000
	s_addc_u32 s29, s55, 0
	s_mov_b32 m0, s62
	v_lshl_add_u64 v[194:195], s[28:29], 0, v[0:1]
	global_load_lds_dwordx4 v[194:195], off
	v_lshl_add_u64 v[194:195], s[28:29], 0, v[146:147]
	s_mov_b32 m0, s63
	s_nop 0
	global_load_lds_dwordx4 v[194:195], off
	s_add_i32 s38, 0, 0x18000
	v_add_u32_e32 v78, s38, v163
	ds_read_b128 v[66:69], v78
	ds_read_b128 v[70:73], v78 offset:1024
	ds_read_b128 v[74:77], v78 offset:2048
	ds_read_b128 v[78:81], v78 offset:3072
	ds_read_b128 v[152:155], v165 offset:32768
	ds_read_b128 v[166:169], v165 offset:33792
	ds_read_b128 v[170:173], v165 offset:34816
	ds_read_b128 v[174:177], v165 offset:35840
	ds_read_b128 v[178:181], v165 offset:36864
	ds_read_b128 v[182:185], v165 offset:37888
	ds_read_b128 v[186:189], v165 offset:38912
	ds_read_b128 v[190:193], v165 offset:39936
	s_add_i32 s39, 0, 0x1c000
	v_add_u32_e32 v210, s39, v163
	ds_read_b128 v[194:197], v210
	ds_read_b128 v[198:201], v210 offset:1024
	ds_read_b128 v[202:205], v210 offset:2048
	ds_read_b128 v[210:213], v210 offset:3072
	s_waitcnt lgkmcnt(4)
	s_barrier
	s_waitcnt lgkmcnt(0)
	s_setprio 1
	v_mfma_f32_16x16x32_bf16 v[142:145], v[66:69], v[152:155], v[142:145]
	v_mfma_f32_16x16x32_bf16 v[138:141], v[74:77], v[152:155], v[138:141]
	v_mfma_f32_16x16x32_bf16 v[126:129], v[66:69], v[170:173], v[126:129]
	v_mfma_f32_16x16x32_bf16 v[122:125], v[74:77], v[170:173], v[122:125]
	v_mfma_f32_16x16x32_bf16 v[110:113], v[66:69], v[178:181], v[110:113]
	v_mfma_f32_16x16x32_bf16 v[106:109], v[74:77], v[178:181], v[106:109]
	v_mfma_f32_16x16x32_bf16 v[102:105], v[66:69], v[186:189], v[102:105]
	v_mfma_f32_16x16x32_bf16 v[98:101], v[74:77], v[186:189], v[98:101]
	v_mfma_f32_16x16x32_bf16 v[142:145], v[70:73], v[166:169], v[142:145]
	v_mfma_f32_16x16x32_bf16 v[138:141], v[78:81], v[166:169], v[138:141]
	v_mfma_f32_16x16x32_bf16 v[126:129], v[70:73], v[174:177], v[126:129]
	v_mfma_f32_16x16x32_bf16 v[122:125], v[78:81], v[174:177], v[122:125]
	v_mfma_f32_16x16x32_bf16 v[110:113], v[70:73], v[182:185], v[110:113]
	v_mfma_f32_16x16x32_bf16 v[106:109], v[78:81], v[182:185], v[106:109]
	v_mfma_f32_16x16x32_bf16 v[102:105], v[70:73], v[190:193], v[102:105]
	v_mfma_f32_16x16x32_bf16 v[98:101], v[78:81], v[190:193], v[98:101]
	v_mfma_f32_16x16x32_bf16 v[134:137], v[194:197], v[152:155], v[134:137]
	v_mfma_f32_16x16x32_bf16 v[130:133], v[202:205], v[152:155], v[130:133]
	v_mfma_f32_16x16x32_bf16 v[118:121], v[194:197], v[170:173], v[118:121]
	v_mfma_f32_16x16x32_bf16 v[114:117], v[202:205], v[170:173], v[114:117]
	v_mfma_f32_16x16x32_bf16 v[94:97], v[194:197], v[178:181], v[94:97]
	v_mfma_f32_16x16x32_bf16 v[90:93], v[202:205], v[178:181], v[90:93]
	v_mfma_f32_16x16x32_bf16 v[86:89], v[194:197], v[186:189], v[86:89]
	v_mfma_f32_16x16x32_bf16 v[82:85], v[202:205], v[186:189], v[82:85]
	v_mfma_f32_16x16x32_bf16 v[134:137], v[198:201], v[166:169], v[134:137]
	v_mfma_f32_16x16x32_bf16 v[130:133], v[210:213], v[166:169], v[130:133]
	v_mfma_f32_16x16x32_bf16 v[118:121], v[198:201], v[174:177], v[118:121]
	v_mfma_f32_16x16x32_bf16 v[114:117], v[210:213], v[174:177], v[114:117]
	v_mfma_f32_16x16x32_bf16 v[94:97], v[198:201], v[182:185], v[94:97]
	v_mfma_f32_16x16x32_bf16 v[90:93], v[210:213], v[182:185], v[90:93]
	v_mfma_f32_16x16x32_bf16 v[86:89], v[198:201], v[190:193], v[86:89]
	v_mfma_f32_16x16x32_bf16 v[82:85], v[210:213], v[190:193], v[82:85]
	s_setprio 0
	s_barrier
; #define PG8_STAGE(bufoff, gbase, voff) do { _Pragma("unroll") for (int _i = 0; _i < 2; ++_i) \
;         __builtin_amdgcn_global_load_lds((const unsigned*)((const char*)(gbase) + (voff)[_i]), (LAS unsigned*)(lds + (bufoff) + ldsw + _i * 8192), 16, 0, 0); } while (0)
; #define PG8_LDA(dst, b, h) do { _Pragma("unroll") for (int m = 0; m < 4; ++m) _Pragma("unroll") for (int k = 0; k < 2; ++k) dst[m][k] = *(const LAS bf16x8*)(lds + PG8_SA(b, h) + aoff + m * 2048 + k * 1024); } while (0)
; #define PG8_LDB(dst, b, h) do { _Pragma("unroll") for (int n = 0; n < 2; ++n) _Pragma("unroll") for (int k = 0; k < 2; ++k) dst[n][k] = *(const LAS bf16x8*)(lds + PG8_SB(b, h) + boff + n * 2048 + k * 1024); } while (0)
; #define PG8_MMA(ai, bj, At, Bt) do { __builtin_amdgcn_s_setprio(1); _Pragma("unroll") for (int m = 0; m < 4; ++m) _Pragma("unroll") for (int n = 0; n < 2; ++n) _Pragma("unroll") for (int k = 0; k < 2; ++k) \
;         acc[ai][bj][m][n] = __builtin_amdgcn_mfma_f32_16x16x32_bf16(Bt[n][k], At[m][k], acc[ai][bj][m][n], 0, 0, 0); __builtin_amdgcn_s_setprio(0); } while (0)
; #define PG8_WAIT_V(n) asm volatile("s_waitcnt vmcnt(" #n ")" ::: "memory")
; #define PG8_WAIT_L(n) asm volatile("s_waitcnt lgkmcnt(" #n ")" ::: "memory")
; #define PG8_BAR __builtin_amdgcn_s_barrier()
; #define PG8_SCHED __builtin_amdgcn_sched_barrier(0)
; template <class Epi, class Sched>
; __device__ __forceinline__ void gemm_phase(LAS unsigned char* lds, const Gemm g, const Sched& S, const Epi& E) {
;     ...
;             PG8_LDB(B1, 1, 1); PG8_STAGE(PG8_SB(1, 0), b3, voffB);
;             PG8_BAR; PG8_WAIT_L(0); PG8_MMA(0, 1, At, B1); PG8_BAR;
;             PG8_LDA(At, 1, 1); PG8_STAGE(PG8_SA(1, 0), a3, voffA);
;             PG8_BAR; PG8_WAIT_L(0); PG8_MMA(1, 0, At, B0); PG8_BAR; PG8_SCHED;
;             PG8_STAGE(PG8_SB(1, 1), b3 + hstep, voffB);
;             PG8_WAIT_V(6); PG8_BAR; PG8_MMA(1, 1, At, B1); PG8_BAR;
	ds_read_b128 v[152:155], v165 offset:49152
	ds_read_b128 v[166:169], v165 offset:50176
	ds_read_b128 v[170:173], v165 offset:51200
	ds_read_b128 v[174:177], v165 offset:52224
	ds_read_b128 v[178:181], v165 offset:53248
	ds_read_b128 v[182:185], v165 offset:54272
	ds_read_b128 v[186:189], v165 offset:55296
	ds_read_b128 v[190:193], v165 offset:56320
	s_add_i32 s28, s38, s60
	v_lshl_add_u64 v[156:157], v[156:157], 0, s[36:37]
	s_mov_b32 m0, s28
	s_nop 0
	global_load_lds_dwordx4 v[156:157], off
	v_lshl_add_u64 v[156:157], v[160:161], 0, s[36:37]
	s_add_i32 m0, s28, 0x2000
	s_nop 0
	global_load_lds_dwordx4 v[156:157], off
	s_mov_b32 m0, s66
	v_lshl_add_u64 v[156:157], v[206:207], 0, s[36:37]
	global_load_lds_dwordx4 v[156:157], off
	v_lshl_add_u64 v[156:157], v[214:215], 0, s[36:37]
	s_mov_b32 m0, s67
	s_nop 0
	global_load_lds_dwordx4 v[156:157], off
	s_waitcnt vmcnt(4)
	s_waitcnt lgkmcnt(0)
	s_barrier
	s_setprio 1
	v_mfma_f32_16x16x32_bf16 v[62:65], v[66:69], v[152:155], v[62:65]
	v_mfma_f32_16x16x32_bf16 v[58:61], v[74:77], v[152:155], v[58:61]
	v_mfma_f32_16x16x32_bf16 v[46:49], v[66:69], v[170:173], v[46:49]
	v_mfma_f32_16x16x32_bf16 v[42:45], v[74:77], v[170:173], v[42:45]
	v_mfma_f32_16x16x32_bf16 v[30:33], v[66:69], v[178:181], v[30:33]
	v_mfma_f32_16x16x32_bf16 v[26:29], v[74:77], v[178:181], v[26:29]
	v_mfma_f32_16x16x32_bf16 v[22:25], v[66:69], v[186:189], v[22:25]
	v_mfma_f32_16x16x32_bf16 v[14:17], v[74:77], v[186:189], v[14:17]
	v_mfma_f32_16x16x32_bf16 v[62:65], v[70:73], v[166:169], v[62:65]
	v_mfma_f32_16x16x32_bf16 v[58:61], v[78:81], v[166:169], v[58:61]
	v_mfma_f32_16x16x32_bf16 v[46:49], v[70:73], v[174:177], v[46:49]
	v_mfma_f32_16x16x32_bf16 v[42:45], v[78:81], v[174:177], v[42:45]
	v_mfma_f32_16x16x32_bf16 v[30:33], v[70:73], v[182:185], v[30:33]
	v_mfma_f32_16x16x32_bf16 v[26:29], v[78:81], v[182:185], v[26:29]
	v_mfma_f32_16x16x32_bf16 v[22:25], v[70:73], v[190:193], v[22:25]
	v_mfma_f32_16x16x32_bf16 v[14:17], v[78:81], v[190:193], v[14:17]
	s_add_u32 s28, s52, 0x200080
	s_addc_u32 s29, s53, 0
	s_add_i32 s38, s39, s60
	v_lshl_add_u64 v[66:67], s[28:29], 0, v[0:1]
	s_mov_b32 m0, s38
	s_nop 0
	global_load_lds_dwordx4 v[66:67], off
	v_lshl_add_u64 v[66:67], s[28:29], 0, v[146:147]
	s_add_i32 m0, s38, 0x2000
	s_nop 0
	global_load_lds_dwordx4 v[66:67], off
	v_mfma_f32_16x16x32_bf16 v[54:57], v[194:197], v[152:155], v[54:57]
	v_mfma_f32_16x16x32_bf16 v[50:53], v[202:205], v[152:155], v[50:53]
	v_mfma_f32_16x16x32_bf16 v[38:41], v[194:197], v[170:173], v[38:41]
	v_mfma_f32_16x16x32_bf16 v[34:37], v[202:205], v[170:173], v[34:37]
	v_mfma_f32_16x16x32_bf16 v[18:21], v[194:197], v[178:181], v[18:21]
	v_mfma_f32_16x16x32_bf16 v[10:13], v[202:205], v[178:181], v[10:13]
	v_mfma_f32_16x16x32_bf16 v[6:9], v[194:197], v[186:189], v[6:9]
	v_mfma_f32_16x16x32_bf16 v[2:5], v[202:205], v[186:189], v[2:5]
	v_mfma_f32_16x16x32_bf16 v[54:57], v[198:201], v[166:169], v[54:57]
	v_mfma_f32_16x16x32_bf16 v[50:53], v[210:213], v[166:169], v[50:53]
	v_mfma_f32_16x16x32_bf16 v[38:41], v[198:201], v[174:177], v[38:41]
	v_mfma_f32_16x16x32_bf16 v[34:37], v[210:213], v[174:177], v[34:37]
	v_mfma_f32_16x16x32_bf16 v[18:21], v[198:201], v[182:185], v[18:21]
	v_mfma_f32_16x16x32_bf16 v[10:13], v[210:213], v[182:185], v[10:13]
	v_mfma_f32_16x16x32_bf16 v[6:9], v[198:201], v[190:193], v[6:9]
	v_mfma_f32_16x16x32_bf16 v[2:5], v[210:213], v[190:193], v[2:5]
	s_setprio 0
	s_add_i32 s75, s75, 2
	s_add_u32 s73, s73, 0x100
	s_addc_u32 s74, s74, 0
	s_cmpk_gt_u32 s75, 0x7d
	s_mov_b64 s[28:29], s[50:51]
	s_barrier
	s_cbranch_scc0 .LBB0_44
	s_cmp_lt_i32 s8, 64
	s_cselect_b64 s[50:51], -1, 0
	s_cmp_gt_i32 s8, 63
	s_cbranch_scc0 .LBB0_35
	s_mov_b64 s[52:53], 0x18000
	s_mov_b64 s[28:29], s[46:47]
	s_branch .LBB0_36

; #define PG8_STAGE(bufoff, gbase, voff) do { _Pragma("unroll") for (int _i = 0; _i < 2; ++_i) \
;         __builtin_amdgcn_global_load_lds((const unsigned*)((const char*)(gbase) + (voff)[_i]), (LAS unsigned*)(lds + (bufoff) + ldsw + _i * 8192), 16, 0, 0); } while (0)
; #define PG8_LDA(dst, b, h) do { _Pragma("unroll") for (int m = 0; m < 4; ++m) _Pragma("unroll") for (int k = 0; k < 2; ++k) dst[m][k] = *(const LAS bf16x8*)(lds + PG8_SA(b, h) + aoff + m * 2048 + k * 1024); } while (0)
; #define PG8_LDB(dst, b, h) do { _Pragma("unroll") for (int n = 0; n < 2; ++n) _Pragma("unroll") for (int k = 0; k < 2; ++k) dst[n][k] = *(const LAS bf16x8*)(lds + PG8_SB(b, h) + boff + n * 2048 + k * 1024); } while (0)
; #define PG8_MMA(ai, bj, At, Bt) do { __builtin_amdgcn_s_setprio(1); _Pragma("unroll") for (int m = 0; m < 4; ++m) _Pragma("unroll") for (int n = 0; n < 2; ++n) _Pragma("unroll") for (int k = 0; k < 2; ++k) \
;         acc[ai][bj][m][n] = __builtin_amdgcn_mfma_f32_16x16x32_bf16(Bt[n][k], At[m][k], acc[ai][bj][m][n], 0, 0, 0); __builtin_amdgcn_s_setprio(0); } while (0)
; #define PG8_WAIT_L(n) asm volatile("s_waitcnt lgkmcnt(" #n ")" ::: "memory")
; #define PG8_BAR __builtin_amdgcn_s_barrier()
; #define PG8_SCHED __builtin_amdgcn_sched_barrier(0)
; template <class Epi, class Sched>
; __device__ __forceinline__ void gemm_phase(LAS unsigned char* lds, const Gemm g, const Sched& S, const Epi& E) {
;     ...
;             const bool last = (t == nt - 2);
;             const char* a1 = cA + (size_t)(t + 1) * kstep;
;             const char* a2 = last ? nA : cA + (size_t)(t + 2) * kstep; const char* b2 = last ? nB : cB + (size_t)(t + 2) * kstep;
;             const char* a3 = a2 + kstep; const char* b3 = b2 + kstep;
;             PG8_LDB(B0, 0, 0); PG8_SCHED; PG8_LDA(At, 0, 0); PG8_STAGE(PG8_SA(1, 1), a1 + hstep, voffA);
;             PG8_WAIT_L(8); PG8_BAR; PG8_WAIT_L(0); PG8_MMA(0, 0, At, B0); PG8_BAR; PG8_SCHED;
;             PG8_LDB(B1, 0, 1); PG8_STAGE(PG8_SB(0, 0), b2, voffB);
;             PG8_BAR; PG8_WAIT_L(0); PG8_MMA(0, 1, At, B1); PG8_BAR;
;             PG8_LDA(At, 0, 1); PG8_STAGE(PG8_SA(0, 0), a2, voffA);
;             PG8_BAR; PG8_WAIT_L(0); PG8_MMA(1, 0, At, B0); PG8_BAR; PG8_SCHED;
.LBB0_58:
	s_add_u32 s52, s50, 0x100
	s_addc_u32 s53, s51, 0
	s_cmp_eq_u32 s71, 28
	s_cselect_b32 s57, s11, s53
	s_cselect_b32 s56, s29, s52
	s_cselect_b32 s55, s41, s70
	s_cselect_b32 s54, s43, s69
	v_lshl_add_u64 v[156:157], s[50:51], 0, v[134:135]
	s_add_i32 m0, s25, 0xc000
	s_nop 0
	global_load_lds_dwordx4 v[156:157], off
	v_lshl_add_u64 v[156:157], s[50:51], 0, v[132:133]
	s_add_i32 m0, s25, 0xe000
	s_nop 0
	global_load_lds_dwordx4 v[156:157], off
	s_add_i32 s38, 0, 0x10000
	v_add_u32_e32 v152, s38, v137
	ds_read_b128 v[140:143], v152
	ds_read_b128 v[144:147], v152 offset:1024
	ds_read_b128 v[148:151], v152 offset:2048
	ds_read_b128 v[152:155], v152 offset:3072
	ds_read_b128 v[160:163], v139
	ds_read_b128 v[164:167], v139 offset:1024
	ds_read_b128 v[168:171], v139 offset:2048
	ds_read_b128 v[172:175], v139 offset:3072
	ds_read_b128 v[176:179], v139 offset:4096
	ds_read_b128 v[180:183], v139 offset:5120
	ds_read_b128 v[184:187], v139 offset:6144
	ds_read_b128 v[188:191], v139 offset:7168
	s_add_i32 s50, 0, 0x14000
	v_add_u32_e32 v156, s50, v137
	ds_read_b128 v[192:195], v156
	ds_read_b128 v[196:199], v156 offset:1024
	ds_read_b128 v[200:203], v156 offset:2048
	ds_read_b128 v[204:207], v156 offset:3072
	s_waitcnt lgkmcnt(4)
	s_barrier
	s_waitcnt lgkmcnt(0)
	s_setprio 1
	v_mfma_f32_16x16x32_bf16 v[126:129], v[140:143], v[160:163], v[126:129]
	v_mfma_f32_16x16x32_bf16 v[122:125], v[148:151], v[160:163], v[122:125]
	v_mfma_f32_16x16x32_bf16 v[118:121], v[140:143], v[168:171], v[118:121]
	v_mfma_f32_16x16x32_bf16 v[114:117], v[148:151], v[168:171], v[114:117]
	v_mfma_f32_16x16x32_bf16 v[106:109], v[140:143], v[176:179], v[106:109]
	v_mfma_f32_16x16x32_bf16 v[98:101], v[148:151], v[176:179], v[98:101]
	v_mfma_f32_16x16x32_bf16 v[90:93], v[140:143], v[184:187], v[90:93]
	v_mfma_f32_16x16x32_bf16 v[82:85], v[148:151], v[184:187], v[82:85]
	v_mfma_f32_16x16x32_bf16 v[126:129], v[144:147], v[164:167], v[126:129]
	v_mfma_f32_16x16x32_bf16 v[122:125], v[152:155], v[164:167], v[122:125]
	v_mfma_f32_16x16x32_bf16 v[118:121], v[144:147], v[172:175], v[118:121]
	v_mfma_f32_16x16x32_bf16 v[114:117], v[152:155], v[172:175], v[114:117]
	v_mfma_f32_16x16x32_bf16 v[106:109], v[144:147], v[180:183], v[106:109]
	v_mfma_f32_16x16x32_bf16 v[98:101], v[152:155], v[180:183], v[98:101]
	v_mfma_f32_16x16x32_bf16 v[90:93], v[144:147], v[188:191], v[90:93]
	v_mfma_f32_16x16x32_bf16 v[82:85], v[152:155], v[188:191], v[82:85]
	v_mfma_f32_16x16x32_bf16 v[110:113], v[192:195], v[160:163], v[110:113]
	v_mfma_f32_16x16x32_bf16 v[102:105], v[200:203], v[160:163], v[102:105]
	v_mfma_f32_16x16x32_bf16 v[94:97], v[192:195], v[168:171], v[94:97]
	v_mfma_f32_16x16x32_bf16 v[86:89], v[200:203], v[168:171], v[86:89]
	v_mfma_f32_16x16x32_bf16 v[78:81], v[192:195], v[176:179], v[78:81]
	v_mfma_f32_16x16x32_bf16 v[74:77], v[200:203], v[176:179], v[74:77]
	v_mfma_f32_16x16x32_bf16 v[70:73], v[192:195], v[184:187], v[70:73]
	v_mfma_f32_16x16x32_bf16 v[66:69], v[200:203], v[184:187], v[66:69]
	v_mfma_f32_16x16x32_bf16 v[110:113], v[196:199], v[164:167], v[110:113]
	v_mfma_f32_16x16x32_bf16 v[102:105], v[204:207], v[164:167], v[102:105]
	v_mfma_f32_16x16x32_bf16 v[94:97], v[196:199], v[172:175], v[94:97]
	v_mfma_f32_16x16x32_bf16 v[86:89], v[204:207], v[172:175], v[86:89]
	v_mfma_f32_16x16x32_bf16 v[78:81], v[196:199], v[180:183], v[78:81]
	v_mfma_f32_16x16x32_bf16 v[74:77], v[204:207], v[180:183], v[74:77]
	v_mfma_f32_16x16x32_bf16 v[70:73], v[196:199], v[188:191], v[70:73]
	v_mfma_f32_16x16x32_bf16 v[66:69], v[204:207], v[188:191], v[66:69]
	s_setprio 0
	s_barrier
	ds_read_b128 v[160:163], v139 offset:16384
	ds_read_b128 v[164:167], v139 offset:17408
	ds_read_b128 v[168:171], v139 offset:18432
	ds_read_b128 v[172:175], v139 offset:19456
	ds_read_b128 v[176:179], v139 offset:20480
	ds_read_b128 v[180:183], v139 offset:21504
	ds_read_b128 v[184:187], v139 offset:22528
	ds_read_b128 v[188:191], v139 offset:23552
	s_add_i32 s38, s38, s63
	v_lshl_add_u64 v[156:157], s[54:55], 0, v[0:1]
	s_mov_b32 m0, s38
	v_lshl_add_u64 v[210:211], s[54:55], 0, v[130:131]
	global_load_lds_dwordx4 v[156:157], off
	s_add_i32 m0, s38, 0x2000
	s_nop 0
	global_load_lds_dwordx4 v[210:211], off
	s_mov_b32 m0, s25
	v_lshl_add_u64 v[212:213], s[56:57], 0, v[0:1]
	global_load_lds_dwordx4 v[212:213], off
	v_lshl_add_u64 v[214:215], s[56:57], 0, v[130:131]
	s_mov_b32 m0, s27
	s_nop 0
	global_load_lds_dwordx4 v[214:215], off
	s_waitcnt vmcnt(4)
	s_waitcnt lgkmcnt(0)
	s_barrier
	s_setprio 1
	v_mfma_f32_16x16x32_bf16 v[62:65], v[140:143], v[160:163], v[62:65]
	v_mfma_f32_16x16x32_bf16 v[58:61], v[148:151], v[160:163], v[58:61]
	v_mfma_f32_16x16x32_bf16 v[54:57], v[140:143], v[168:171], v[54:57]
	v_mfma_f32_16x16x32_bf16 v[50:53], v[148:151], v[168:171], v[50:53]
	v_mfma_f32_16x16x32_bf16 v[38:41], v[140:143], v[176:179], v[38:41]
	v_mfma_f32_16x16x32_bf16 v[34:37], v[148:151], v[176:179], v[34:37]
	v_mfma_f32_16x16x32_bf16 v[22:25], v[140:143], v[184:187], v[22:25]
	v_mfma_f32_16x16x32_bf16 v[18:21], v[148:151], v[184:187], v[18:21]
	v_mfma_f32_16x16x32_bf16 v[62:65], v[144:147], v[164:167], v[62:65]
	v_mfma_f32_16x16x32_bf16 v[58:61], v[152:155], v[164:167], v[58:61]
	v_mfma_f32_16x16x32_bf16 v[54:57], v[144:147], v[172:175], v[54:57]
	v_mfma_f32_16x16x32_bf16 v[50:53], v[152:155], v[172:175], v[50:53]
	v_mfma_f32_16x16x32_bf16 v[38:41], v[144:147], v[180:183], v[38:41]
	v_mfma_f32_16x16x32_bf16 v[34:37], v[152:155], v[180:183], v[34:37]
	v_mfma_f32_16x16x32_bf16 v[22:25], v[144:147], v[188:191], v[22:25]
	v_mfma_f32_16x16x32_bf16 v[18:21], v[152:155], v[188:191], v[18:21]
	v_mfma_f32_16x16x32_bf16 v[46:49], v[192:195], v[160:163], v[46:49]
	v_mfma_f32_16x16x32_bf16 v[42:45], v[200:203], v[160:163], v[42:45]
	v_mfma_f32_16x16x32_bf16 v[30:33], v[192:195], v[168:171], v[30:33]
	v_mfma_f32_16x16x32_bf16 v[26:29], v[200:203], v[168:171], v[26:29]
	v_mfma_f32_16x16x32_bf16 v[14:17], v[192:195], v[176:179], v[14:17]
	v_mfma_f32_16x16x32_bf16 v[10:13], v[200:203], v[176:179], v[10:13]
	v_mfma_f32_16x16x32_bf16 v[6:9], v[192:195], v[184:187], v[6:9]
	v_mfma_f32_16x16x32_bf16 v[2:5], v[200:203], v[184:187], v[2:5]
	v_mfma_f32_16x16x32_bf16 v[46:49], v[196:199], v[164:167], v[46:49]
	v_mfma_f32_16x16x32_bf16 v[42:45], v[204:207], v[164:167], v[42:45]
	v_mfma_f32_16x16x32_bf16 v[30:33], v[196:199], v[172:175], v[30:33]
	v_mfma_f32_16x16x32_bf16 v[26:29], v[204:207], v[172:175], v[26:29]
	v_mfma_f32_16x16x32_bf16 v[14:17], v[196:199], v[180:183], v[14:17]
	v_mfma_f32_16x16x32_bf16 v[10:13], v[204:207], v[180:183], v[10:13]
	v_mfma_f32_16x16x32_bf16 v[6:9], v[196:199], v[188:191], v[6:9]
	v_mfma_f32_16x16x32_bf16 v[2:5], v[204:207], v[188:191], v[2:5]
	s_setprio 0
	s_barrier
; #define PG8_STAGE(bufoff, gbase, voff) do { _Pragma("unroll") for (int _i = 0; _i < 2; ++_i) \
;         __builtin_amdgcn_global_load_lds((const unsigned*)((const char*)(gbase) + (voff)[_i]), (LAS unsigned*)(lds + (bufoff) + ldsw + _i * 8192), 16, 0, 0); } while (0)
; #define PG8_LDA(dst, b, h) do { _Pragma("unroll") for (int m = 0; m < 4; ++m) _Pragma("unroll") for (int k = 0; k < 2; ++k) dst[m][k] = *(const LAS bf16x8*)(lds + PG8_SA(b, h) + aoff + m * 2048 + k * 1024); } while (0)
; #define PG8_LDB(dst, b, h) do { _Pragma("unroll") for (int n = 0; n < 2; ++n) _Pragma("unroll") for (int k = 0; k < 2; ++k) dst[n][k] = *(const LAS bf16x8*)(lds + PG8_SB(b, h) + boff + n * 2048 + k * 1024); } while (0)
; #define PG8_MMA(ai, bj, At, Bt) do { __builtin_amdgcn_s_setprio(1); _Pragma("unroll") for (int m = 0; m < 4; ++m) _Pragma("unroll") for (int n = 0; n < 2; ++n) _Pragma("unroll") for (int k = 0; k < 2; ++k) \
;         acc[ai][bj][m][n] = __builtin_amdgcn_mfma_f32_16x16x32_bf16(Bt[n][k], At[m][k], acc[ai][bj][m][n], 0, 0, 0); __builtin_amdgcn_s_setprio(0); } while (0)
; #define PG8_WAIT_V(n) asm volatile("s_waitcnt vmcnt(" #n ")" ::: "memory")
; #define PG8_WAIT_L(n) asm volatile("s_waitcnt lgkmcnt(" #n ")" ::: "memory")
; #define PG8_BAR __builtin_amdgcn_s_barrier()
; #define PG8_SCHED __builtin_amdgcn_sched_barrier(0)
; template <class Epi, class Sched>
; __device__ __forceinline__ void gemm_phase(LAS unsigned char* lds, const Gemm g, const Sched& S, const Epi& E) {
;     ...
;             PG8_STAGE(PG8_SB(0, 1), b2 + hstep, voffB);
;             PG8_WAIT_V(6); PG8_BAR; PG8_MMA(1, 1, At, B1); PG8_BAR;
;             PG8_LDB(B0, 1, 0); PG8_SCHED; PG8_LDA(At, 1, 0); PG8_STAGE(PG8_SA(0, 1), a2 + hstep, voffA);
;             PG8_WAIT_L(8); PG8_BAR; PG8_WAIT_L(0); PG8_MMA(0, 0, At, B0); PG8_BAR; PG8_SCHED;
;             PG8_LDB(B1, 1, 1); PG8_STAGE(PG8_SB(1, 0), b3, voffB);
;             PG8_BAR; PG8_WAIT_L(0); PG8_MMA(0, 1, At, B1); PG8_BAR;
;             PG8_LDA(At, 1, 1); PG8_STAGE(PG8_SA(1, 0), a3, voffA);
	s_add_u32 s38, s54, 0x200000
	s_addc_u32 s39, s55, 0
	s_add_i32 s50, s50, s63
	v_lshl_add_u64 v[140:141], s[38:39], 0, v[0:1]
	s_mov_b32 m0, s50
	s_nop 0
	global_load_lds_dwordx4 v[140:141], off
	v_lshl_add_u64 v[140:141], s[38:39], 0, v[130:131]
	s_add_i32 m0, s50, 0x2000
	s_nop 0
	global_load_lds_dwordx4 v[140:141], off
	s_add_u32 s38, s56, 0x200000
	s_addc_u32 s39, s57, 0
	s_mov_b32 m0, s64
	v_lshl_add_u64 v[192:193], s[38:39], 0, v[0:1]
	global_load_lds_dwordx4 v[192:193], off
	v_lshl_add_u64 v[192:193], s[38:39], 0, v[130:131]
	s_mov_b32 m0, s65
	s_nop 0
	global_load_lds_dwordx4 v[192:193], off
	s_add_i32 s50, 0, 0x18000
	v_add_u32_e32 v152, s50, v137
	ds_read_b128 v[140:143], v152
	ds_read_b128 v[144:147], v152 offset:1024
	ds_read_b128 v[148:151], v152 offset:2048
	ds_read_b128 v[152:155], v152 offset:3072
	ds_read_b128 v[160:163], v139 offset:32768
	ds_read_b128 v[164:167], v139 offset:33792
	ds_read_b128 v[168:171], v139 offset:34816
	ds_read_b128 v[172:175], v139 offset:35840
	ds_read_b128 v[176:179], v139 offset:36864
	ds_read_b128 v[180:183], v139 offset:37888
	ds_read_b128 v[184:187], v139 offset:38912
	ds_read_b128 v[188:191], v139 offset:39936
	s_add_i32 s51, 0, 0x1c000
	v_add_u32_e32 v204, s51, v137
	ds_read_b128 v[192:195], v204
	ds_read_b128 v[196:199], v204 offset:1024
	ds_read_b128 v[200:203], v204 offset:2048
	ds_read_b128 v[204:207], v204 offset:3072
	s_waitcnt lgkmcnt(4)
	s_barrier
	s_waitcnt lgkmcnt(0)
	s_setprio 1
	v_mfma_f32_16x16x32_bf16 v[126:129], v[140:143], v[160:163], v[126:129]
	v_mfma_f32_16x16x32_bf16 v[122:125], v[148:151], v[160:163], v[122:125]
	v_mfma_f32_16x16x32_bf16 v[118:121], v[140:143], v[168:171], v[118:121]
	v_mfma_f32_16x16x32_bf16 v[114:117], v[148:151], v[168:171], v[114:117]
	v_mfma_f32_16x16x32_bf16 v[106:109], v[140:143], v[176:179], v[106:109]
	v_mfma_f32_16x16x32_bf16 v[98:101], v[148:151], v[176:179], v[98:101]
	v_mfma_f32_16x16x32_bf16 v[90:93], v[140:143], v[184:187], v[90:93]
	v_mfma_f32_16x16x32_bf16 v[82:85], v[148:151], v[184:187], v[82:85]
	v_mfma_f32_16x16x32_bf16 v[126:129], v[144:147], v[164:167], v[126:129]
	v_mfma_f32_16x16x32_bf16 v[122:125], v[152:155], v[164:167], v[122:125]
	v_mfma_f32_16x16x32_bf16 v[118:121], v[144:147], v[172:175], v[118:121]
	v_mfma_f32_16x16x32_bf16 v[114:117], v[152:155], v[172:175], v[114:117]
	v_mfma_f32_16x16x32_bf16 v[106:109], v[144:147], v[180:183], v[106:109]
	v_mfma_f32_16x16x32_bf16 v[98:101], v[152:155], v[180:183], v[98:101]
	v_mfma_f32_16x16x32_bf16 v[90:93], v[144:147], v[188:191], v[90:93]
	v_mfma_f32_16x16x32_bf16 v[82:85], v[152:155], v[188:191], v[82:85]
	v_mfma_f32_16x16x32_bf16 v[110:113], v[192:195], v[160:163], v[110:113]
	v_mfma_f32_16x16x32_bf16 v[102:105], v[200:203], v[160:163], v[102:105]
	v_mfma_f32_16x16x32_bf16 v[94:97], v[192:195], v[168:171], v[94:97]
	v_mfma_f32_16x16x32_bf16 v[86:89], v[200:203], v[168:171], v[86:89]
	v_mfma_f32_16x16x32_bf16 v[78:81], v[192:195], v[176:179], v[78:81]
	v_mfma_f32_16x16x32_bf16 v[74:77], v[200:203], v[176:179], v[74:77]
	v_mfma_f32_16x16x32_bf16 v[70:73], v[192:195], v[184:187], v[70:73]
	v_mfma_f32_16x16x32_bf16 v[66:69], v[200:203], v[184:187], v[66:69]
	v_mfma_f32_16x16x32_bf16 v[110:113], v[196:199], v[164:167], v[110:113]
	v_mfma_f32_16x16x32_bf16 v[102:105], v[204:207], v[164:167], v[102:105]
	v_mfma_f32_16x16x32_bf16 v[94:97], v[196:199], v[172:175], v[94:97]
	v_mfma_f32_16x16x32_bf16 v[86:89], v[204:207], v[172:175], v[86:89]
	v_mfma_f32_16x16x32_bf16 v[78:81], v[196:199], v[180:183], v[78:81]
	v_mfma_f32_16x16x32_bf16 v[74:77], v[204:207], v[180:183], v[74:77]
	v_mfma_f32_16x16x32_bf16 v[70:73], v[196:199], v[188:191], v[70:73]
	v_mfma_f32_16x16x32_bf16 v[66:69], v[204:207], v[188:191], v[66:69]
	s_setprio 0
	s_barrier
	ds_read_b128 v[160:163], v139 offset:49152
	ds_read_b128 v[164:167], v139 offset:50176
	ds_read_b128 v[168:171], v139 offset:51200
	ds_read_b128 v[172:175], v139 offset:52224
	ds_read_b128 v[176:179], v139 offset:53248
	ds_read_b128 v[180:183], v139 offset:54272
	ds_read_b128 v[184:187], v139 offset:55296
	ds_read_b128 v[188:191], v139 offset:56320
	s_add_i32 s38, s50, s63
	v_lshl_add_u64 v[156:157], v[156:157], 0, s[36:37]
	s_mov_b32 m0, s38
	s_nop 0
	global_load_lds_dwordx4 v[156:157], off
	v_lshl_add_u64 v[156:157], v[210:211], 0, s[36:37]
	s_add_i32 m0, s38, 0x2000
	s_nop 0
	global_load_lds_dwordx4 v[156:157], off
	s_mov_b32 m0, s66
	v_lshl_add_u64 v[156:157], v[212:213], 0, s[36:37]
	global_load_lds_dwordx4 v[156:157], off
	v_lshl_add_u64 v[156:157], v[214:215], 0, s[36:37]
	s_mov_b32 m0, s67
	s_nop 0
	global_load_lds_dwordx4 v[156:157], off
	s_waitcnt vmcnt(4)
	s_waitcnt lgkmcnt(0)
	s_barrier
; #define PG8_STAGE(bufoff, gbase, voff) do { _Pragma("unroll") for (int _i = 0; _i < 2; ++_i) \
;         __builtin_amdgcn_global_load_lds((const unsigned*)((const char*)(gbase) + (voff)[_i]), (LAS unsigned*)(lds + (bufoff) + ldsw + _i * 8192), 16, 0, 0); } while (0)
; #define PG8_MMA(ai, bj, At, Bt) do { __builtin_amdgcn_s_setprio(1); _Pragma("unroll") for (int m = 0; m < 4; ++m) _Pragma("unroll") for (int n = 0; n < 2; ++n) _Pragma("unroll") for (int k = 0; k < 2; ++k) \
;         acc[ai][bj][m][n] = __builtin_amdgcn_mfma_f32_16x16x32_bf16(Bt[n][k], At[m][k], acc[ai][bj][m][n], 0, 0, 0); __builtin_amdgcn_s_setprio(0); } while (0)
; #define PG8_WAIT_V(n) asm volatile("s_waitcnt vmcnt(" #n ")" ::: "memory")
; #define PG8_WAIT_L(n) asm volatile("s_waitcnt lgkmcnt(" #n ")" ::: "memory")
; #define PG8_BAR __builtin_amdgcn_s_barrier()
; #define PG8_SCHED __builtin_amdgcn_sched_barrier(0)
;     __device__ __forceinline__ void operator()(const f32x4 (&acc)[2][2][4][2], const Unit& u, int wr, int wc, int fr, int fq) const {
;         const int row0 = u.pm * BM + wr * 64 + fr, col0 = u.pn * BM + wc * 32 + 4 * fq;
;         float* base = part + (size_t)u.ks * Mp * ldc;
; #pragma unroll
;         for (int ai = 0; ai < 2; ++ai)
; #pragma unroll
;             for (int m = 0; m < 4; ++m) { float* rowp = base + (size_t)(row0 + ai * HALF + m * 16) * ldc + col0;
; #pragma unroll
;                 for (int bj = 0; bj < 2; ++bj)
; #pragma unroll
;                     for (int n = 0; n < 2; ++n) *(f32x4*)(rowp + bj * HALF + n * 16) = acc[ai][bj][m][n]; }
;     }
; template <class Epi, class Sched>
; __device__ __forceinline__ void gemm_phase(LAS unsigned char* lds, const Gemm g, const Sched& S, const Epi& E) {
;     ...
;             PG8_BAR; PG8_WAIT_L(0); PG8_MMA(1, 0, At, B0); PG8_BAR; PG8_SCHED;
;             PG8_STAGE(PG8_SB(1, 1), b3 + hstep, voffB);
;             PG8_WAIT_V(6); PG8_BAR; PG8_MMA(1, 1, At, B1); PG8_BAR;
;         }
;         E(acc, cur, wr, wc, fr, fq);
;         if (!has_next) break;
	s_setprio 1
	v_mfma_f32_16x16x32_bf16 v[62:65], v[140:143], v[160:163], v[62:65]
	v_mfma_f32_16x16x32_bf16 v[58:61], v[148:151], v[160:163], v[58:61]
	v_mfma_f32_16x16x32_bf16 v[54:57], v[140:143], v[168:171], v[54:57]
	v_mfma_f32_16x16x32_bf16 v[50:53], v[148:151], v[168:171], v[50:53]
	v_mfma_f32_16x16x32_bf16 v[38:41], v[140:143], v[176:179], v[38:41]
	v_mfma_f32_16x16x32_bf16 v[34:37], v[148:151], v[176:179], v[34:37]
	v_mfma_f32_16x16x32_bf16 v[22:25], v[140:143], v[184:187], v[22:25]
	v_mfma_f32_16x16x32_bf16 v[18:21], v[148:151], v[184:187], v[18:21]
	v_mfma_f32_16x16x32_bf16 v[62:65], v[144:147], v[164:167], v[62:65]
	v_mfma_f32_16x16x32_bf16 v[58:61], v[152:155], v[164:167], v[58:61]
	v_mfma_f32_16x16x32_bf16 v[54:57], v[144:147], v[172:175], v[54:57]
	v_mfma_f32_16x16x32_bf16 v[50:53], v[152:155], v[172:175], v[50:53]
	v_mfma_f32_16x16x32_bf16 v[38:41], v[144:147], v[180:183], v[38:41]
	v_mfma_f32_16x16x32_bf16 v[34:37], v[152:155], v[180:183], v[34:37]
	v_mfma_f32_16x16x32_bf16 v[22:25], v[144:147], v[188:191], v[22:25]
	v_mfma_f32_16x16x32_bf16 v[18:21], v[152:155], v[188:191], v[18:21]
	s_add_u32 s38, s54, 0x200080
	s_addc_u32 s39, s55, 0
	s_add_i32 s50, s51, s63
	v_lshl_add_u64 v[140:141], s[38:39], 0, v[0:1]
	s_mov_b32 m0, s50
	s_nop 0
	global_load_lds_dwordx4 v[140:141], off
	v_lshl_add_u64 v[140:141], s[38:39], 0, v[130:131]
	s_add_i32 m0, s50, 0x2000
	s_nop 0
	global_load_lds_dwordx4 v[140:141], off
	v_mfma_f32_16x16x32_bf16 v[46:49], v[192:195], v[160:163], v[46:49]
	v_mfma_f32_16x16x32_bf16 v[42:45], v[200:203], v[160:163], v[42:45]
	v_mfma_f32_16x16x32_bf16 v[30:33], v[192:195], v[168:171], v[30:33]
	v_mfma_f32_16x16x32_bf16 v[26:29], v[200:203], v[168:171], v[26:29]
	v_mfma_f32_16x16x32_bf16 v[14:17], v[192:195], v[176:179], v[14:17]
	v_mfma_f32_16x16x32_bf16 v[10:13], v[200:203], v[176:179], v[10:13]
	v_mfma_f32_16x16x32_bf16 v[6:9], v[192:195], v[184:187], v[6:9]
	v_mfma_f32_16x16x32_bf16 v[2:5], v[200:203], v[184:187], v[2:5]
	v_mfma_f32_16x16x32_bf16 v[46:49], v[196:199], v[164:167], v[46:49]
	v_mfma_f32_16x16x32_bf16 v[42:45], v[204:207], v[164:167], v[42:45]
	v_mfma_f32_16x16x32_bf16 v[30:33], v[196:199], v[172:175], v[30:33]
	v_mfma_f32_16x16x32_bf16 v[26:29], v[204:207], v[172:175], v[26:29]
	v_mfma_f32_16x16x32_bf16 v[14:17], v[196:199], v[180:183], v[14:17]
	v_mfma_f32_16x16x32_bf16 v[10:13], v[204:207], v[180:183], v[10:13]
	v_mfma_f32_16x16x32_bf16 v[6:9], v[196:199], v[188:191], v[6:9]
	v_mfma_f32_16x16x32_bf16 v[2:5], v[204:207], v[188:191], v[2:5]
	s_setprio 0
	s_add_i32 s71, s71, 2
	s_add_u32 s69, s69, 0x100
	s_addc_u32 s70, s70, 0
	s_cmp_gt_u32 s71, 29
	s_mov_b64 s[50:51], s[52:53]
	s_barrier
	s_cbranch_scc0 .LBB0_58
	s_ashr_i32 s11, s10, 31
	s_lshl_b64 s[10:11], s[10:11], 24
	v_lshl_or_b32 v140, s26, 8, v138
	s_add_u32 s10, s8, s10
	v_lshl_add_u32 v142, s24, 8, v136
	s_addc_u32 s11, s9, s11
	v_ashrrev_i32_e32 v141, 31, v140
	v_ashrrev_i32_e32 v143, 31, v142
	v_lshl_add_u64 v[140:141], v[140:141], 2, s[10:11]
	v_lshlrev_b64 v[144:145], 13, v[142:143]
	v_lshl_add_u64 v[144:145], v[140:141], 0, v[144:145]
	global_store_dwordx4 v[144:145], v[126:129], off
	global_store_dwordx4 v[144:145], v[122:125], off offset:64
	global_store_dwordx4 v[144:145], v[110:113], off offset:512
	global_store_dwordx4 v[144:145], v[102:105], off offset:576
	s_mov_b64 s[10:11], 0x100000
	s_mov_b32 s26, s40
	v_or_b32_e32 v102, 16, v142
	v_ashrrev_i32_e32 v103, 31, v102
	v_lshlrev_b64 v[102:103], 13, v[102:103]
	v_lshl_add_u64 v[102:103], v[140:141], 0, v[102:103]
	global_store_dwordx4 v[102:103], v[118:121], off
	global_store_dwordx4 v[102:103], v[114:117], off offset:64
	global_store_dwordx4 v[102:103], v[94:97], off offset:512
	global_store_dwordx4 v[102:103], v[86:89], off offset:576
	s_mov_b32 s24, s42
	s_mov_b64 s[52:53], s[48:49]
	v_or_b32_e32 v86, 32, v142
	v_ashrrev_i32_e32 v87, 31, v86
	v_lshlrev_b64 v[86:87], 13, v[86:87]
	v_lshl_add_u64 v[86:87], v[140:141], 0, v[86:87]
	global_store_dwordx4 v[86:87], v[106:109], off
	global_store_dwordx4 v[86:87], v[98:101], off offset:64
	global_store_dwordx4 v[86:87], v[78:81], off offset:512
	global_store_dwordx4 v[86:87], v[74:77], off offset:576
	s_mov_b64 s[50:51], s[46:47]
	s_nop 0
	v_or_b32_e32 v74, 48, v142
	v_ashrrev_i32_e32 v75, 31, v74
	v_lshlrev_b64 v[74:75], 13, v[74:75]
	v_lshl_add_u64 v[74:75], v[140:141], 0, v[74:75]
	global_store_dwordx4 v[74:75], v[90:93], off
	global_store_dwordx4 v[74:75], v[82:85], off offset:64
	global_store_dwordx4 v[74:75], v[70:73], off offset:512
	global_store_dwordx4 v[74:75], v[66:69], off offset:576
	s_nop 1
	v_add_co_u32_e32 v68, vcc, s93, v144
	v_lshl_add_u64 v[66:67], v[144:145], 0, s[10:11]
	s_nop 0
	v_addc_co_u32_e32 v69, vcc, 0, v145, vcc
	s_mov_b64 s[10:11], 0x120000
	global_store_dwordx4 v[68:69], v[62:65], off
	global_store_dwordx4 v[66:67], v[58:61], off offset:64
	global_store_dwordx4 v[66:67], v[46:49], off offset:512
	global_store_dwordx4 v[66:67], v[42:45], off offset:576
	s_nop 1
	v_lshl_add_u64 v[42:43], v[144:145], 0, s[10:11]
	s_mov_b32 s10, 0x120000
	v_add_co_u32_e32 v44, vcc, s10, v144
	s_mov_b64 s[10:11], 0x140000
	s_nop 0
	v_addc_co_u32_e32 v45, vcc, 0, v145, vcc
	global_store_dwordx4 v[44:45], v[54:57], off
	global_store_dwordx4 v[42:43], v[50:53], off offset:64
	global_store_dwordx4 v[42:43], v[30:33], off offset:512
	global_store_dwordx4 v[42:43], v[26:29], off offset:576
	s_nop 1
	v_lshl_add_u64 v[26:27], v[144:145], 0, s[10:11]
	s_mov_b32 s10, 0x140000
	v_add_co_u32_e32 v28, vcc, s10, v144
	s_mov_b64 s[10:11], 0x160000
	s_nop 0
	v_addc_co_u32_e32 v29, vcc, 0, v145, vcc
	global_store_dwordx4 v[28:29], v[38:41], off
	global_store_dwordx4 v[26:27], v[34:37], off offset:64
	global_store_dwordx4 v[26:27], v[14:17], off offset:512
	global_store_dwordx4 v[26:27], v[10:13], off offset:576
	s_nop 1
	v_add_co_u32_e32 v12, vcc, 0x160000, v144
	v_lshl_add_u64 v[10:11], v[144:145], 0, s[10:11]
	s_nop 0
	v_addc_co_u32_e32 v13, vcc, 0, v145, vcc
	s_and_b64 vcc, exec, s[44:45]
	s_mov_b32 s10, s28
	global_store_dwordx4 v[12:13], v[22:25], off
	global_store_dwordx4 v[10:11], v[18:21], off offset:64
	global_store_dwordx4 v[10:11], v[6:9], off offset:512
	global_store_dwordx4 v[10:11], v[2:5], off offset:576
	s_cbranch_vccz .LBB0_55
	s_waitcnt vmcnt(0)
	s_cmpk_gt_u32 s60, 0xff
	s_cbranch_scc1 .LBB0_62
	s_barrier

; #define PG8_STAGE(bufoff, gbase, voff) do { _Pragma("unroll") for (int _i = 0; _i < 2; ++_i) \
;         __builtin_amdgcn_global_load_lds((const unsigned*)((const char*)(gbase) + (voff)[_i]), (LAS unsigned*)(lds + (bufoff) + ldsw + _i * 8192), 16, 0, 0); } while (0)
; #define PG8_LDA(dst, b, h) do { _Pragma("unroll") for (int m = 0; m < 4; ++m) _Pragma("unroll") for (int k = 0; k < 2; ++k) dst[m][k] = *(const LAS bf16x8*)(lds + PG8_SA(b, h) + aoff + m * 2048 + k * 1024); } while (0)
; #define PG8_LDB(dst, b, h) do { _Pragma("unroll") for (int n = 0; n < 2; ++n) _Pragma("unroll") for (int k = 0; k < 2; ++k) dst[n][k] = *(const LAS bf16x8*)(lds + PG8_SB(b, h) + boff + n * 2048 + k * 1024); } while (0)
; #define PG8_MMA(ai, bj, At, Bt) do { __builtin_amdgcn_s_setprio(1); _Pragma("unroll") for (int m = 0; m < 4; ++m) _Pragma("unroll") for (int n = 0; n < 2; ++n) _Pragma("unroll") for (int k = 0; k < 2; ++k) \
;         acc[ai][bj][m][n] = __builtin_amdgcn_mfma_f32_16x16x32_bf16(Bt[n][k], At[m][k], acc[ai][bj][m][n], 0, 0, 0); __builtin_amdgcn_s_setprio(0); } while (0)
; #define PG8_WAIT_L(n) asm volatile("s_waitcnt lgkmcnt(" #n ")" ::: "memory")
; #define PG8_BAR __builtin_amdgcn_s_barrier()
; #define PG8_SCHED __builtin_amdgcn_sched_barrier(0)
; template <class Epi, class Sched>
; __device__ __forceinline__ void gemm_phase(LAS unsigned char* lds, const Gemm g, const Sched& S, const Epi& E) {
;     ...
;             const bool last = (t == nt - 2);
;             const char* a1 = cA + (size_t)(t + 1) * kstep;
;             const char* a2 = last ? nA : cA + (size_t)(t + 2) * kstep; const char* b2 = last ? nB : cB + (size_t)(t + 2) * kstep;
;             const char* a3 = a2 + kstep; const char* b3 = b2 + kstep;
;             PG8_LDB(B0, 0, 0); PG8_SCHED; PG8_LDA(At, 0, 0); PG8_STAGE(PG8_SA(1, 1), a1 + hstep, voffA);
;             PG8_WAIT_L(8); PG8_BAR; PG8_WAIT_L(0); PG8_MMA(0, 0, At, B0); PG8_BAR; PG8_SCHED;
;             PG8_LDB(B1, 0, 1); PG8_STAGE(PG8_SB(0, 0), b2, voffB);
;             PG8_BAR; PG8_WAIT_L(0); PG8_MMA(0, 1, At, B1); PG8_BAR;
;             PG8_LDA(At, 0, 1); PG8_STAGE(PG8_SA(0, 0), a2, voffA);
;             PG8_BAR; PG8_WAIT_L(0); PG8_MMA(1, 0, At, B0); PG8_BAR; PG8_SCHED;
.LBB0_73:
	s_add_i32 s74, 0, 0x10000
	v_add_u32_e32 v140, s74, v143
	ds_read_b128 v[146:149], v140
	ds_read_b128 v[150:153], v140 offset:1024
	ds_read_b128 v[154:157], v140 offset:2048
	ds_read_b128 v[160:163], v140 offset:3072
	ds_read_b128 v[164:167], v145
	ds_read_b128 v[168:171], v145 offset:1024
	ds_read_b128 v[172:175], v145 offset:2048
	ds_read_b128 v[176:179], v145 offset:3072
	ds_read_b128 v[180:183], v145 offset:4096
	ds_read_b128 v[184:187], v145 offset:5120
	ds_read_b128 v[188:191], v145 offset:6144
	ds_read_b128 v[192:195], v145 offset:7168
	s_add_i32 s75, 0, 0x14000
	v_add_u32_e32 v140, s75, v143
	ds_read_b128 v[196:199], v140
	ds_read_b128 v[200:203], v140 offset:1024
	ds_read_b128 v[204:207], v140 offset:2048
	ds_read_b128 v[210:213], v140 offset:3072
	s_add_u32 s38, s46, 0xfff80080
	s_addc_u32 s39, s47, -1
	s_cmp_eq_u32 s73, 28
	s_cselect_b32 s51, s29, s39
	s_cselect_b32 s50, s69, s38
	s_cselect_b32 s49, s27, s72
	s_cselect_b32 s48, s70, s71
	v_lshl_add_u64 v[140:141], s[46:47], 0, v[138:139]
	s_add_i32 m0, s9, 0xc000
	s_nop 0
	global_load_lds_dwordx4 v[140:141], off
	v_lshl_add_u64 v[140:141], s[46:47], 0, v[136:137]
	s_add_i32 m0, s9, 0xe000
	s_nop 0
	global_load_lds_dwordx4 v[140:141], off
	s_waitcnt lgkmcnt(4)
	s_barrier
	s_waitcnt lgkmcnt(0)
	s_setprio 1
	v_mfma_f32_16x16x32_bf16 v[126:129], v[146:149], v[164:167], v[126:129]
	v_mfma_f32_16x16x32_bf16 v[122:125], v[154:157], v[164:167], v[122:125]
	v_mfma_f32_16x16x32_bf16 v[110:113], v[146:149], v[172:175], v[110:113]
	v_mfma_f32_16x16x32_bf16 v[106:109], v[154:157], v[172:175], v[106:109]
	v_mfma_f32_16x16x32_bf16 v[94:97], v[146:149], v[180:183], v[94:97]
	v_mfma_f32_16x16x32_bf16 v[90:93], v[154:157], v[180:183], v[90:93]
	v_mfma_f32_16x16x32_bf16 v[78:81], v[146:149], v[188:191], v[78:81]
	v_mfma_f32_16x16x32_bf16 v[74:77], v[154:157], v[188:191], v[74:77]
	v_mfma_f32_16x16x32_bf16 v[126:129], v[150:153], v[168:171], v[126:129]
	v_mfma_f32_16x16x32_bf16 v[122:125], v[160:163], v[168:171], v[122:125]
	v_mfma_f32_16x16x32_bf16 v[110:113], v[150:153], v[176:179], v[110:113]
	v_mfma_f32_16x16x32_bf16 v[106:109], v[160:163], v[176:179], v[106:109]
	v_mfma_f32_16x16x32_bf16 v[94:97], v[150:153], v[184:187], v[94:97]
	v_mfma_f32_16x16x32_bf16 v[90:93], v[160:163], v[184:187], v[90:93]
	v_mfma_f32_16x16x32_bf16 v[78:81], v[150:153], v[192:195], v[78:81]
	v_mfma_f32_16x16x32_bf16 v[74:77], v[160:163], v[192:195], v[74:77]
	v_mfma_f32_16x16x32_bf16 v[118:121], v[196:199], v[164:167], v[118:121]
	v_mfma_f32_16x16x32_bf16 v[114:117], v[204:207], v[164:167], v[114:117]
	v_mfma_f32_16x16x32_bf16 v[102:105], v[196:199], v[172:175], v[102:105]
	v_mfma_f32_16x16x32_bf16 v[98:101], v[204:207], v[172:175], v[98:101]
	v_mfma_f32_16x16x32_bf16 v[86:89], v[196:199], v[180:183], v[86:89]
	v_mfma_f32_16x16x32_bf16 v[82:85], v[204:207], v[180:183], v[82:85]
	v_mfma_f32_16x16x32_bf16 v[70:73], v[196:199], v[188:191], v[70:73]
	v_mfma_f32_16x16x32_bf16 v[66:69], v[204:207], v[188:191], v[66:69]
	v_mfma_f32_16x16x32_bf16 v[118:121], v[200:203], v[168:171], v[118:121]
	v_mfma_f32_16x16x32_bf16 v[114:117], v[210:213], v[168:171], v[114:117]
	v_mfma_f32_16x16x32_bf16 v[102:105], v[200:203], v[176:179], v[102:105]
	v_mfma_f32_16x16x32_bf16 v[98:101], v[210:213], v[176:179], v[98:101]
	v_mfma_f32_16x16x32_bf16 v[86:89], v[200:203], v[184:187], v[86:89]
	v_mfma_f32_16x16x32_bf16 v[82:85], v[210:213], v[184:187], v[82:85]
	v_mfma_f32_16x16x32_bf16 v[70:73], v[200:203], v[192:195], v[70:73]
	v_mfma_f32_16x16x32_bf16 v[66:69], v[210:213], v[192:195], v[66:69]
	s_setprio 0
	s_barrier
	ds_read_b128 v[164:167], v145 offset:16384
	ds_read_b128 v[168:171], v145 offset:17408
	ds_read_b128 v[172:175], v145 offset:18432
	ds_read_b128 v[176:179], v145 offset:19456
	ds_read_b128 v[180:183], v145 offset:20480
	ds_read_b128 v[184:187], v145 offset:21504
	ds_read_b128 v[188:191], v145 offset:22528
	ds_read_b128 v[192:195], v145 offset:23552
	s_add_i32 s38, s74, s56
	v_lshl_add_u64 v[140:141], s[48:49], 0, v[0:1]
	s_mov_b32 m0, s38
	v_lshl_add_u64 v[214:215], s[48:49], 0, v[130:131]
	global_load_lds_dwordx4 v[140:141], off
	s_add_i32 m0, s38, 0x2000
	s_nop 0
	global_load_lds_dwordx4 v[214:215], off
	s_mov_b32 m0, s9
	v_lshl_add_u64 v[216:217], s[50:51], 0, v[134:135]
	global_load_lds_dwordx4 v[216:217], off
	v_lshl_add_u64 v[224:225], s[50:51], 0, v[132:133]
	s_mov_b32 m0, s60
	s_nop 0
	global_load_lds_dwordx4 v[224:225], off
	s_waitcnt vmcnt(4)
	s_waitcnt lgkmcnt(0)
	s_barrier
	s_setprio 1
	v_mfma_f32_16x16x32_bf16 v[62:65], v[146:149], v[164:167], v[62:65]
	v_mfma_f32_16x16x32_bf16 v[58:61], v[154:157], v[164:167], v[58:61]
	v_mfma_f32_16x16x32_bf16 v[46:49], v[146:149], v[172:175], v[46:49]
	v_mfma_f32_16x16x32_bf16 v[42:45], v[154:157], v[172:175], v[42:45]
	v_mfma_f32_16x16x32_bf16 v[30:33], v[146:149], v[180:183], v[30:33]
	v_mfma_f32_16x16x32_bf16 v[26:29], v[154:157], v[180:183], v[26:29]
	v_mfma_f32_16x16x32_bf16 v[14:17], v[146:149], v[188:191], v[14:17]
	v_mfma_f32_16x16x32_bf16 v[10:13], v[154:157], v[188:191], v[10:13]
	v_mfma_f32_16x16x32_bf16 v[62:65], v[150:153], v[168:171], v[62:65]
	v_mfma_f32_16x16x32_bf16 v[58:61], v[160:163], v[168:171], v[58:61]
	v_mfma_f32_16x16x32_bf16 v[46:49], v[150:153], v[176:179], v[46:49]
	v_mfma_f32_16x16x32_bf16 v[42:45], v[160:163], v[176:179], v[42:45]
	v_mfma_f32_16x16x32_bf16 v[30:33], v[150:153], v[184:187], v[30:33]
	v_mfma_f32_16x16x32_bf16 v[26:29], v[160:163], v[184:187], v[26:29]
	v_mfma_f32_16x16x32_bf16 v[14:17], v[150:153], v[192:195], v[14:17]
	v_mfma_f32_16x16x32_bf16 v[10:13], v[160:163], v[192:195], v[10:13]
	v_mfma_f32_16x16x32_bf16 v[54:57], v[196:199], v[164:167], v[54:57]
	v_mfma_f32_16x16x32_bf16 v[50:53], v[204:207], v[164:167], v[50:53]
	v_mfma_f32_16x16x32_bf16 v[38:41], v[196:199], v[172:175], v[38:41]
	v_mfma_f32_16x16x32_bf16 v[34:37], v[204:207], v[172:175], v[34:37]
	v_mfma_f32_16x16x32_bf16 v[22:25], v[196:199], v[180:183], v[22:25]
	v_mfma_f32_16x16x32_bf16 v[18:21], v[204:207], v[180:183], v[18:21]
	v_mfma_f32_16x16x32_bf16 v[6:9], v[196:199], v[188:191], v[6:9]
	v_mfma_f32_16x16x32_bf16 v[2:5], v[204:207], v[188:191], v[2:5]
	v_mfma_f32_16x16x32_bf16 v[54:57], v[200:203], v[168:171], v[54:57]
	v_mfma_f32_16x16x32_bf16 v[50:53], v[210:213], v[168:171], v[50:53]
	v_mfma_f32_16x16x32_bf16 v[38:41], v[200:203], v[176:179], v[38:41]
	v_mfma_f32_16x16x32_bf16 v[34:37], v[210:213], v[176:179], v[34:37]
	v_mfma_f32_16x16x32_bf16 v[22:25], v[200:203], v[184:187], v[22:25]
	v_mfma_f32_16x16x32_bf16 v[18:21], v[210:213], v[184:187], v[18:21]
	v_mfma_f32_16x16x32_bf16 v[6:9], v[200:203], v[192:195], v[6:9]
	v_mfma_f32_16x16x32_bf16 v[2:5], v[210:213], v[192:195], v[2:5]
	s_setprio 0
	s_barrier
; #define PG8_STAGE(bufoff, gbase, voff) do { _Pragma("unroll") for (int _i = 0; _i < 2; ++_i) \
;         __builtin_amdgcn_global_load_lds((const unsigned*)((const char*)(gbase) + (voff)[_i]), (LAS unsigned*)(lds + (bufoff) + ldsw + _i * 8192), 16, 0, 0); } while (0)
; #define PG8_LDA(dst, b, h) do { _Pragma("unroll") for (int m = 0; m < 4; ++m) _Pragma("unroll") for (int k = 0; k < 2; ++k) dst[m][k] = *(const LAS bf16x8*)(lds + PG8_SA(b, h) + aoff + m * 2048 + k * 1024); } while (0)
; #define PG8_LDB(dst, b, h) do { _Pragma("unroll") for (int n = 0; n < 2; ++n) _Pragma("unroll") for (int k = 0; k < 2; ++k) dst[n][k] = *(const LAS bf16x8*)(lds + PG8_SB(b, h) + boff + n * 2048 + k * 1024); } while (0)
; #define PG8_MMA(ai, bj, At, Bt) do { __builtin_amdgcn_s_setprio(1); _Pragma("unroll") for (int m = 0; m < 4; ++m) _Pragma("unroll") for (int n = 0; n < 2; ++n) _Pragma("unroll") for (int k = 0; k < 2; ++k) \
;         acc[ai][bj][m][n] = __builtin_amdgcn_mfma_f32_16x16x32_bf16(Bt[n][k], At[m][k], acc[ai][bj][m][n], 0, 0, 0); __builtin_amdgcn_s_setprio(0); } while (0)
; #define PG8_WAIT_V(n) asm volatile("s_waitcnt vmcnt(" #n ")" ::: "memory")
; #define PG8_WAIT_L(n) asm volatile("s_waitcnt lgkmcnt(" #n ")" ::: "memory")
; #define PG8_BAR __builtin_amdgcn_s_barrier()
; #define PG8_SCHED __builtin_amdgcn_sched_barrier(0)
; template <class Epi, class Sched>
; __device__ __forceinline__ void gemm_phase(LAS unsigned char* lds, const Gemm g, const Sched& S, const Epi& E) {
;     ...
;             PG8_STAGE(PG8_SB(0, 1), b2 + hstep, voffB);
;             PG8_WAIT_V(6); PG8_BAR; PG8_MMA(1, 1, At, B1); PG8_BAR;
;             PG8_LDB(B0, 1, 0); PG8_SCHED; PG8_LDA(At, 1, 0); PG8_STAGE(PG8_SA(0, 1), a2 + hstep, voffA);
;             PG8_WAIT_L(8); PG8_BAR; PG8_WAIT_L(0); PG8_MMA(0, 0, At, B0); PG8_BAR; PG8_SCHED;
;             PG8_LDB(B1, 1, 1); PG8_STAGE(PG8_SB(1, 0), b3, voffB);
;             PG8_BAR; PG8_WAIT_L(0); PG8_MMA(0, 1, At, B1); PG8_BAR;
;             PG8_LDA(At, 1, 1); PG8_STAGE(PG8_SA(1, 0), a3, voffA);
	s_add_u32 s38, s48, 0x80000
	s_addc_u32 s39, s49, 0
	s_add_i32 s74, s75, s56
	v_lshl_add_u64 v[146:147], s[38:39], 0, v[0:1]
	s_mov_b32 m0, s74
	s_nop 0
	global_load_lds_dwordx4 v[146:147], off
	v_lshl_add_u64 v[146:147], s[38:39], 0, v[130:131]
	s_add_i32 m0, s74, 0x2000
	s_nop 0
	global_load_lds_dwordx4 v[146:147], off
	s_add_u32 s38, s50, 0x80000
	s_addc_u32 s39, s51, 0
	s_mov_b32 m0, s61
	v_lshl_add_u64 v[196:197], s[38:39], 0, v[134:135]
	global_load_lds_dwordx4 v[196:197], off
	v_lshl_add_u64 v[196:197], s[38:39], 0, v[132:133]
	s_mov_b32 m0, s62
	s_nop 0
	global_load_lds_dwordx4 v[196:197], off
	s_add_i32 s74, 0, 0x18000
	v_add_u32_e32 v160, s74, v143
	ds_read_b128 v[146:149], v160
	ds_read_b128 v[150:153], v160 offset:1024
	ds_read_b128 v[154:157], v160 offset:2048
	ds_read_b128 v[160:163], v160 offset:3072
	ds_read_b128 v[164:167], v145 offset:32768
	ds_read_b128 v[168:171], v145 offset:33792
	ds_read_b128 v[172:175], v145 offset:34816
	ds_read_b128 v[176:179], v145 offset:35840
	ds_read_b128 v[180:183], v145 offset:36864
	ds_read_b128 v[184:187], v145 offset:37888
	ds_read_b128 v[188:191], v145 offset:38912
	ds_read_b128 v[192:195], v145 offset:39936
	s_add_i32 s50, 0, 0x1c000
	v_add_u32_e32 v210, s50, v143
	ds_read_b128 v[196:199], v210
	ds_read_b128 v[200:203], v210 offset:1024
	ds_read_b128 v[204:207], v210 offset:2048
	ds_read_b128 v[210:213], v210 offset:3072
	s_waitcnt lgkmcnt(4)
	s_barrier
	s_waitcnt lgkmcnt(0)
	s_setprio 1
	v_mfma_f32_16x16x32_bf16 v[126:129], v[146:149], v[164:167], v[126:129]
	v_mfma_f32_16x16x32_bf16 v[122:125], v[154:157], v[164:167], v[122:125]
	v_mfma_f32_16x16x32_bf16 v[110:113], v[146:149], v[172:175], v[110:113]
	v_mfma_f32_16x16x32_bf16 v[106:109], v[154:157], v[172:175], v[106:109]
	v_mfma_f32_16x16x32_bf16 v[94:97], v[146:149], v[180:183], v[94:97]
	v_mfma_f32_16x16x32_bf16 v[90:93], v[154:157], v[180:183], v[90:93]
	v_mfma_f32_16x16x32_bf16 v[78:81], v[146:149], v[188:191], v[78:81]
	v_mfma_f32_16x16x32_bf16 v[74:77], v[154:157], v[188:191], v[74:77]
	v_mfma_f32_16x16x32_bf16 v[126:129], v[150:153], v[168:171], v[126:129]
	v_mfma_f32_16x16x32_bf16 v[122:125], v[160:163], v[168:171], v[122:125]
	v_mfma_f32_16x16x32_bf16 v[110:113], v[150:153], v[176:179], v[110:113]
	v_mfma_f32_16x16x32_bf16 v[106:109], v[160:163], v[176:179], v[106:109]
	v_mfma_f32_16x16x32_bf16 v[94:97], v[150:153], v[184:187], v[94:97]
	v_mfma_f32_16x16x32_bf16 v[90:93], v[160:163], v[184:187], v[90:93]
	v_mfma_f32_16x16x32_bf16 v[78:81], v[150:153], v[192:195], v[78:81]
	v_mfma_f32_16x16x32_bf16 v[74:77], v[160:163], v[192:195], v[74:77]
	v_mfma_f32_16x16x32_bf16 v[118:121], v[196:199], v[164:167], v[118:121]
	v_mfma_f32_16x16x32_bf16 v[114:117], v[204:207], v[164:167], v[114:117]
	v_mfma_f32_16x16x32_bf16 v[102:105], v[196:199], v[172:175], v[102:105]
	v_mfma_f32_16x16x32_bf16 v[98:101], v[204:207], v[172:175], v[98:101]
	v_mfma_f32_16x16x32_bf16 v[86:89], v[196:199], v[180:183], v[86:89]
	v_mfma_f32_16x16x32_bf16 v[82:85], v[204:207], v[180:183], v[82:85]
	v_mfma_f32_16x16x32_bf16 v[70:73], v[196:199], v[188:191], v[70:73]
	v_mfma_f32_16x16x32_bf16 v[66:69], v[204:207], v[188:191], v[66:69]
	v_mfma_f32_16x16x32_bf16 v[118:121], v[200:203], v[168:171], v[118:121]
	v_mfma_f32_16x16x32_bf16 v[114:117], v[210:213], v[168:171], v[114:117]
	v_mfma_f32_16x16x32_bf16 v[102:105], v[200:203], v[176:179], v[102:105]
	v_mfma_f32_16x16x32_bf16 v[98:101], v[210:213], v[176:179], v[98:101]
	v_mfma_f32_16x16x32_bf16 v[86:89], v[200:203], v[184:187], v[86:89]
	v_mfma_f32_16x16x32_bf16 v[82:85], v[210:213], v[184:187], v[82:85]
	v_mfma_f32_16x16x32_bf16 v[70:73], v[200:203], v[192:195], v[70:73]
	v_mfma_f32_16x16x32_bf16 v[66:69], v[210:213], v[192:195], v[66:69]
	s_setprio 0
	s_barrier
	ds_read_b128 v[164:167], v145 offset:49152
	ds_read_b128 v[168:171], v145 offset:50176
	ds_read_b128 v[172:175], v145 offset:51200
	ds_read_b128 v[176:179], v145 offset:52224
	ds_read_b128 v[180:183], v145 offset:53248
	ds_read_b128 v[184:187], v145 offset:54272
	ds_read_b128 v[188:191], v145 offset:55296
	ds_read_b128 v[192:195], v145 offset:56320
	s_add_i32 s38, s74, s56
	v_lshl_add_u64 v[140:141], v[140:141], 0, s[36:37]
	s_mov_b32 m0, s38
	s_nop 0
	global_load_lds_dwordx4 v[140:141], off
	v_lshl_add_u64 v[140:141], v[214:215], 0, s[36:37]
	s_add_i32 m0, s38, 0x2000
	s_nop 0
	global_load_lds_dwordx4 v[140:141], off
	s_mov_b32 m0, s64
	v_lshl_add_u64 v[140:141], v[216:217], 0, s[36:37]
	global_load_lds_dwordx4 v[140:141], off
	v_lshl_add_u64 v[140:141], v[224:225], 0, s[36:37]
	s_mov_b32 m0, s65
	s_nop 0
	global_load_lds_dwordx4 v[140:141], off
	s_waitcnt vmcnt(4)
	s_waitcnt lgkmcnt(0)
	s_barrier
; __device__ __forceinline__ unsigned cvt_pk_bf16(float lo, float hi) { unsigned r; asm("v_cvt_pk_bf16_f32 %0, %1, %2" : "=v"(r) : "v"(lo), "v"(hi)); return r; }
; #define PG8_STAGE(bufoff, gbase, voff) do { _Pragma("unroll") for (int _i = 0; _i < 2; ++_i) \
;         __builtin_amdgcn_global_load_lds((const unsigned*)((const char*)(gbase) + (voff)[_i]), (LAS unsigned*)(lds + (bufoff) + ldsw + _i * 8192), 16, 0, 0); } while (0)
; #define PG8_MMA(ai, bj, At, Bt) do { __builtin_amdgcn_s_setprio(1); _Pragma("unroll") for (int m = 0; m < 4; ++m) _Pragma("unroll") for (int n = 0; n < 2; ++n) _Pragma("unroll") for (int k = 0; k < 2; ++k) \
;         acc[ai][bj][m][n] = __builtin_amdgcn_mfma_f32_16x16x32_bf16(Bt[n][k], At[m][k], acc[ai][bj][m][n], 0, 0, 0); __builtin_amdgcn_s_setprio(0); } while (0)
; #define PG8_WAIT_V(n) asm volatile("s_waitcnt vmcnt(" #n ")" ::: "memory")
; #define PG8_BAR __builtin_amdgcn_s_barrier()
;     __device__ __forceinline__ void operator()(const f32x4 (&acc)[2][2][4][2], const Unit& u, int wr, int wc, int fr, int fq) const {
;         const int row0 = u.pm * BM + wr * 64 + fr, col0 = u.pn * BM + wc * 32 + 8 * fq;
; #pragma unroll
;         for (int ai = 0; ai < 2; ++ai)
; #pragma unroll
;             for (int m = 0; m < 4; ++m) { bf16_t* rowp = O + (size_t)(row0 + ai * HALF + m * 16) * ldc + col0;
; #pragma unroll
;                 for (int bj = 0; bj < 2; ++bj) { f32x4 v0 = acc[ai][bj][m][0], v1 = acc[ai][bj][m][1];
;                     if (ACT == 1) {
; #pragma unroll
;                         for (int j = 0; j < 4; ++j) { float a = fmaxf(v0[j], 0.f), b = fmaxf(v1[j], 0.f); v0[j] = a * a; v1[j] = b * b; } }
;                     u32x4 w; w.x = cvt_pk_bf16(v0[0], v0[1]); w.y = cvt_pk_bf16(v0[2], v0[3]); w.z = cvt_pk_bf16(v1[0], v1[1]); w.w = cvt_pk_bf16(v1[2], v1[3]);
;                     if (ACT == 1) __builtin_nontemporal_store(w, (u32x4*)(rowp + bj * HALF));
;                     else *(u32x4*)(rowp + bj * HALF) = w; } }
; template <class Epi, class Sched>
; __device__ __forceinline__ void gemm_phase(LAS unsigned char* lds, const Gemm g, const Sched& S, const Epi& E) {
;     ...
;             PG8_BAR; PG8_WAIT_L(0); PG8_MMA(1, 0, At, B0); PG8_BAR; PG8_SCHED;
;             PG8_STAGE(PG8_SB(1, 1), b3 + hstep, voffB);
;             PG8_WAIT_V(6); PG8_BAR; PG8_MMA(1, 1, At, B1); PG8_BAR;
;         }
;         E(acc, cur, wr, wc, fr, fq);
	s_setprio 1
	v_mfma_f32_16x16x32_bf16 v[62:65], v[146:149], v[164:167], v[62:65]
	v_mfma_f32_16x16x32_bf16 v[58:61], v[154:157], v[164:167], v[58:61]
	v_mfma_f32_16x16x32_bf16 v[46:49], v[146:149], v[172:175], v[46:49]
	v_mfma_f32_16x16x32_bf16 v[42:45], v[154:157], v[172:175], v[42:45]
	v_mfma_f32_16x16x32_bf16 v[30:33], v[146:149], v[180:183], v[30:33]
	v_mfma_f32_16x16x32_bf16 v[26:29], v[154:157], v[180:183], v[26:29]
	v_mfma_f32_16x16x32_bf16 v[14:17], v[146:149], v[188:191], v[14:17]
	v_mfma_f32_16x16x32_bf16 v[10:13], v[154:157], v[188:191], v[10:13]
	v_mfma_f32_16x16x32_bf16 v[62:65], v[150:153], v[168:171], v[62:65]
	v_mfma_f32_16x16x32_bf16 v[58:61], v[160:163], v[168:171], v[58:61]
	v_mfma_f32_16x16x32_bf16 v[46:49], v[150:153], v[176:179], v[46:49]
	v_mfma_f32_16x16x32_bf16 v[42:45], v[160:163], v[176:179], v[42:45]
	v_mfma_f32_16x16x32_bf16 v[30:33], v[150:153], v[184:187], v[30:33]
	v_mfma_f32_16x16x32_bf16 v[26:29], v[160:163], v[184:187], v[26:29]
	v_mfma_f32_16x16x32_bf16 v[14:17], v[150:153], v[192:195], v[14:17]
	v_mfma_f32_16x16x32_bf16 v[10:13], v[160:163], v[192:195], v[10:13]
	s_add_u32 s38, s48, 0x80080
	s_addc_u32 s39, s49, 0
	s_add_i32 s48, s50, s56
	v_lshl_add_u64 v[140:141], s[38:39], 0, v[0:1]
	s_mov_b32 m0, s48
	s_nop 0
	global_load_lds_dwordx4 v[140:141], off
	v_lshl_add_u64 v[140:141], s[38:39], 0, v[130:131]
	s_add_i32 m0, s48, 0x2000
	s_nop 0
	global_load_lds_dwordx4 v[140:141], off
	v_mfma_f32_16x16x32_bf16 v[54:57], v[196:199], v[164:167], v[54:57]
	v_mfma_f32_16x16x32_bf16 v[50:53], v[204:207], v[164:167], v[50:53]
	v_mfma_f32_16x16x32_bf16 v[38:41], v[196:199], v[172:175], v[38:41]
	v_mfma_f32_16x16x32_bf16 v[34:37], v[204:207], v[172:175], v[34:37]
	v_mfma_f32_16x16x32_bf16 v[22:25], v[196:199], v[180:183], v[22:25]
	v_mfma_f32_16x16x32_bf16 v[18:21], v[204:207], v[180:183], v[18:21]
	v_mfma_f32_16x16x32_bf16 v[6:9], v[196:199], v[188:191], v[6:9]
	v_mfma_f32_16x16x32_bf16 v[2:5], v[204:207], v[188:191], v[2:5]
	v_mfma_f32_16x16x32_bf16 v[54:57], v[200:203], v[168:171], v[54:57]
	v_mfma_f32_16x16x32_bf16 v[50:53], v[210:213], v[168:171], v[50:53]
	v_mfma_f32_16x16x32_bf16 v[38:41], v[200:203], v[176:179], v[38:41]
	v_mfma_f32_16x16x32_bf16 v[34:37], v[210:213], v[176:179], v[34:37]
	v_mfma_f32_16x16x32_bf16 v[22:25], v[200:203], v[184:187], v[22:25]
	v_mfma_f32_16x16x32_bf16 v[18:21], v[210:213], v[184:187], v[18:21]
	v_mfma_f32_16x16x32_bf16 v[6:9], v[200:203], v[192:195], v[6:9]
	v_mfma_f32_16x16x32_bf16 v[2:5], v[210:213], v[192:195], v[2:5]
	s_setprio 0
	s_add_i32 s73, s73, 2
	s_add_u32 s71, s71, 0x100
	s_addc_u32 s72, s72, 0
	s_add_u32 s46, s46, 0x100
	s_addc_u32 s47, s47, 0
	s_cmp_gt_u32 s73, 29
	s_barrier
	s_cbranch_scc0 .LBB0_73
	v_lshl_add_u32 v146, s8, 8, v142
	v_max_f32_e32 v122, v122, v122
	v_ashrrev_i32_e32 v147, 31, v146
	v_max_f32_e32 v122, 0, v122
	v_max_f32_e32 v123, v123, v123
	v_max_f32_e32 v124, v124, v124
	v_lshl_or_b32 v140, s68, 8, v144
	v_lshlrev_b64 v[148:149], 14, v[146:147]
	v_mul_f32_e32 v147, v122, v122
	v_max_f32_e32 v122, v127, v127
	v_max_f32_e32 v123, 0, v123
	v_max_f32_e32 v124, 0, v124
	v_ashrrev_i32_e32 v141, 31, v140
	v_max_f32_e32 v126, v126, v126
	v_max_f32_e32 v122, 0, v122
	v_mul_f32_e32 v127, v123, v123
	v_max_f32_e32 v123, v128, v128
	v_mul_f32_e32 v128, v124, v124
	v_max_f32_e32 v124, v129, v129
	v_max_f32_e32 v125, v125, v125
	v_lshl_add_u64 v[148:149], s[24:25], 0, v[148:149]
	v_lshlrev_b64 v[150:151], 1, v[140:141]
	v_max_f32_e32 v126, 0, v126
	v_mul_f32_e32 v122, v122, v122
	v_max_f32_e32 v123, 0, v123
	v_max_f32_e32 v124, 0, v124
	v_max_f32_e32 v125, 0, v125
	v_max_f32_e32 v114, v114, v114
	v_lshl_add_u64 v[140:141], v[148:149], 0, v[150:151]
	v_mul_f32_e32 v126, v126, v126
	v_mul_f32_e32 v123, v123, v123
	v_mul_f32_e32 v124, v124, v124
	v_mul_f32_e32 v125, v125, v125
	v_cvt_pk_bf16_f32 v122, v126, v122
	v_max_f32_e32 v114, 0, v114
	v_max_f32_e32 v115, v115, v115
	v_max_f32_e32 v116, v116, v116
	v_cvt_pk_bf16_f32 v123, v123, v124
	v_cvt_pk_bf16_f32 v124, v147, v127
	v_cvt_pk_bf16_f32 v125, v128, v125
	global_store_dwordx4 v[140:141], v[122:125], off nt
	v_max_f32_e32 v115, 0, v115
	v_max_f32_e32 v116, 0, v116
	v_mul_f32_e32 v122, v114, v114
	v_max_f32_e32 v114, v119, v119
	v_max_f32_e32 v118, v118, v118
	v_max_f32_e32 v114, 0, v114
	v_mul_f32_e32 v119, v115, v115
	v_max_f32_e32 v115, v120, v120
	v_mul_f32_e32 v120, v116, v116
	v_max_f32_e32 v116, v121, v121
	v_max_f32_e32 v117, v117, v117
	v_max_f32_e32 v118, 0, v118
	v_mul_f32_e32 v114, v114, v114
	v_max_f32_e32 v115, 0, v115
	v_max_f32_e32 v116, 0, v116
	v_max_f32_e32 v117, 0, v117
	v_mul_f32_e32 v118, v118, v118
	v_mul_f32_e32 v115, v115, v115
	v_mul_f32_e32 v116, v116, v116
	v_mul_f32_e32 v117, v117, v117
	v_cvt_pk_bf16_f32 v114, v118, v114
	v_max_f32_e32 v106, v106, v106
	v_cvt_pk_bf16_f32 v115, v115, v116
	v_cvt_pk_bf16_f32 v116, v122, v119
	v_cvt_pk_bf16_f32 v117, v120, v117
	global_store_dwordx4 v[140:141], v[114:117], off offset:256 nt
	v_max_f32_e32 v106, 0, v106
	v_max_f32_e32 v107, v107, v107
	v_or_b32_e32 v114, 16, v146
	v_max_f32_e32 v108, v108, v108
	v_ashrrev_i32_e32 v115, 31, v114
	v_mul_f32_e32 v116, v106, v106
	v_max_f32_e32 v106, v111, v111
	v_max_f32_e32 v107, 0, v107
	v_max_f32_e32 v108, 0, v108
	v_lshlrev_b64 v[114:115], 14, v[114:115]
	v_max_f32_e32 v110, v110, v110
	v_max_f32_e32 v106, 0, v106
	v_mul_f32_e32 v111, v107, v107
	v_max_f32_e32 v107, v112, v112
	v_mul_f32_e32 v112, v108, v108
	v_max_f32_e32 v108, v113, v113
	v_max_f32_e32 v109, v109, v109
	v_lshl_add_u64 v[114:115], s[24:25], 0, v[114:115]
	v_max_f32_e32 v110, 0, v110
	v_mul_f32_e32 v106, v106, v106
; __device__ __forceinline__ unsigned cvt_pk_bf16(float lo, float hi) { unsigned r; asm("v_cvt_pk_bf16_f32 %0, %1, %2" : "=v"(r) : "v"(lo), "v"(hi)); return r; }
;     __device__ __forceinline__ void operator()(const f32x4 (&acc)[2][2][4][2], const Unit& u, int wr, int wc, int fr, int fq) const {
;         const int row0 = u.pm * BM + wr * 64 + fr, col0 = u.pn * BM + wc * 32 + 8 * fq;
; #pragma unroll
;         for (int ai = 0; ai < 2; ++ai)
; #pragma unroll
;             for (int m = 0; m < 4; ++m) { bf16_t* rowp = O + (size_t)(row0 + ai * HALF + m * 16) * ldc + col0;
; #pragma unroll
;                 for (int bj = 0; bj < 2; ++bj) { f32x4 v0 = acc[ai][bj][m][0], v1 = acc[ai][bj][m][1];
;                     if (ACT == 1) {
; #pragma unroll
;                         for (int j = 0; j < 4; ++j) { float a = fmaxf(v0[j], 0.f), b = fmaxf(v1[j], 0.f); v0[j] = a * a; v1[j] = b * b; } }
;                     u32x4 w; w.x = cvt_pk_bf16(v0[0], v0[1]); w.y = cvt_pk_bf16(v0[2], v0[3]); w.z = cvt_pk_bf16(v1[0], v1[1]); w.w = cvt_pk_bf16(v1[2], v1[3]);
;                     if (ACT == 1) __builtin_nontemporal_store(w, (u32x4*)(rowp + bj * HALF));
;                     else *(u32x4*)(rowp + bj * HALF) = w; } }
	v_max_f32_e32 v107, 0, v107
	v_max_f32_e32 v108, 0, v108
	v_max_f32_e32 v109, 0, v109
	v_max_f32_e32 v98, v98, v98
	v_lshl_add_u64 v[114:115], v[114:115], 0, v[150:151]
	v_mul_f32_e32 v110, v110, v110
	v_mul_f32_e32 v107, v107, v107
	v_mul_f32_e32 v108, v108, v108
	v_mul_f32_e32 v109, v109, v109
	v_cvt_pk_bf16_f32 v106, v110, v106
	v_max_f32_e32 v98, 0, v98
	v_max_f32_e32 v99, v99, v99
	v_max_f32_e32 v100, v100, v100
	v_cvt_pk_bf16_f32 v107, v107, v108
	v_cvt_pk_bf16_f32 v108, v116, v111
	v_cvt_pk_bf16_f32 v109, v112, v109
	global_store_dwordx4 v[114:115], v[106:109], off nt
	v_max_f32_e32 v99, 0, v99
	v_max_f32_e32 v100, 0, v100
	v_mul_f32_e32 v106, v98, v98
	v_max_f32_e32 v98, v103, v103
	v_max_f32_e32 v102, v102, v102
	v_max_f32_e32 v98, 0, v98
	v_mul_f32_e32 v103, v99, v99
	v_max_f32_e32 v99, v104, v104
	v_mul_f32_e32 v104, v100, v100
	v_max_f32_e32 v100, v105, v105
	v_max_f32_e32 v101, v101, v101
	v_max_f32_e32 v102, 0, v102
	v_mul_f32_e32 v98, v98, v98
	v_max_f32_e32 v99, 0, v99
	v_max_f32_e32 v100, 0, v100
	v_max_f32_e32 v101, 0, v101
	v_mul_f32_e32 v102, v102, v102
	v_mul_f32_e32 v99, v99, v99
	v_mul_f32_e32 v100, v100, v100
	v_mul_f32_e32 v101, v101, v101
	v_cvt_pk_bf16_f32 v98, v102, v98
	v_max_f32_e32 v90, v90, v90
	v_cvt_pk_bf16_f32 v99, v99, v100
	v_cvt_pk_bf16_f32 v100, v106, v103
	v_cvt_pk_bf16_f32 v101, v104, v101
	global_store_dwordx4 v[114:115], v[98:101], off offset:256 nt
	v_max_f32_e32 v90, 0, v90
	v_max_f32_e32 v91, v91, v91
	v_or_b32_e32 v98, 32, v146
	v_max_f32_e32 v92, v92, v92
	v_ashrrev_i32_e32 v99, 31, v98
	v_mul_f32_e32 v100, v90, v90
	v_max_f32_e32 v90, v95, v95
	v_max_f32_e32 v91, 0, v91
	v_max_f32_e32 v92, 0, v92
	v_lshlrev_b64 v[98:99], 14, v[98:99]
	v_max_f32_e32 v94, v94, v94
	v_max_f32_e32 v90, 0, v90
	v_mul_f32_e32 v95, v91, v91
	v_max_f32_e32 v91, v96, v96
	v_mul_f32_e32 v96, v92, v92
	v_max_f32_e32 v92, v97, v97
	v_max_f32_e32 v93, v93, v93
	v_lshl_add_u64 v[98:99], s[24:25], 0, v[98:99]
	v_max_f32_e32 v94, 0, v94
	v_mul_f32_e32 v90, v90, v90
	v_max_f32_e32 v91, 0, v91
	v_max_f32_e32 v92, 0, v92
	v_max_f32_e32 v93, 0, v93
	v_max_f32_e32 v82, v82, v82
	v_lshl_add_u64 v[98:99], v[98:99], 0, v[150:151]
	v_mul_f32_e32 v94, v94, v94
	v_mul_f32_e32 v91, v91, v91
	v_mul_f32_e32 v92, v92, v92
	v_mul_f32_e32 v93, v93, v93
	v_cvt_pk_bf16_f32 v90, v94, v90
	v_max_f32_e32 v82, 0, v82
	v_max_f32_e32 v83, v83, v83
	v_max_f32_e32 v84, v84, v84
	v_cvt_pk_bf16_f32 v91, v91, v92
	v_cvt_pk_bf16_f32 v92, v100, v95
	v_cvt_pk_bf16_f32 v93, v96, v93
	global_store_dwordx4 v[98:99], v[90:93], off nt
	v_max_f32_e32 v83, 0, v83
	v_max_f32_e32 v84, 0, v84
	v_mul_f32_e32 v90, v82, v82
	v_max_f32_e32 v82, v87, v87
	v_max_f32_e32 v86, v86, v86
	v_max_f32_e32 v82, 0, v82
	v_mul_f32_e32 v87, v83, v83
	v_max_f32_e32 v83, v88, v88
	v_mul_f32_e32 v88, v84, v84
	v_max_f32_e32 v84, v89, v89
	v_max_f32_e32 v85, v85, v85
	v_max_f32_e32 v86, 0, v86
	v_mul_f32_e32 v82, v82, v82
	v_max_f32_e32 v83, 0, v83
	v_max_f32_e32 v84, 0, v84
	v_max_f32_e32 v85, 0, v85
	v_mul_f32_e32 v86, v86, v86
	v_mul_f32_e32 v83, v83, v83
	v_mul_f32_e32 v84, v84, v84
	v_mul_f32_e32 v85, v85, v85
	v_cvt_pk_bf16_f32 v82, v86, v82
	v_max_f32_e32 v74, v74, v74
	v_cvt_pk_bf16_f32 v83, v83, v84
	v_cvt_pk_bf16_f32 v84, v90, v87
	v_cvt_pk_bf16_f32 v85, v88, v85
	global_store_dwordx4 v[98:99], v[82:85], off offset:256 nt
	v_max_f32_e32 v74, 0, v74
	v_max_f32_e32 v75, v75, v75
	v_or_b32_e32 v82, 48, v146
	v_max_f32_e32 v76, v76, v76
	v_ashrrev_i32_e32 v83, 31, v82
	v_mul_f32_e32 v84, v74, v74
	v_max_f32_e32 v74, v79, v79
	v_max_f32_e32 v75, 0, v75
	v_max_f32_e32 v76, 0, v76
	v_lshlrev_b64 v[82:83], 14, v[82:83]
	v_max_f32_e32 v78, v78, v78
	v_max_f32_e32 v74, 0, v74
	v_mul_f32_e32 v79, v75, v75
	v_max_f32_e32 v75, v80, v80
	v_mul_f32_e32 v80, v76, v76
	v_max_f32_e32 v76, v81, v81
	v_max_f32_e32 v77, v77, v77
	v_lshl_add_u64 v[82:83], s[24:25], 0, v[82:83]
	v_max_f32_e32 v78, 0, v78
	v_mul_f32_e32 v74, v74, v74
	v_max_f32_e32 v75, 0, v75
	v_max_f32_e32 v76, 0, v76
	v_max_f32_e32 v77, 0, v77
	v_max_f32_e32 v66, v66, v66
	v_max_f32_e32 v67, v67, v67
	v_max_f32_e32 v68, v68, v68
	v_lshl_add_u64 v[82:83], v[82:83], 0, v[150:151]
	v_mul_f32_e32 v78, v78, v78
	v_mul_f32_e32 v75, v75, v75
	v_mul_f32_e32 v76, v76, v76
	v_mul_f32_e32 v77, v77, v77
	v_cvt_pk_bf16_f32 v74, v78, v74
	v_max_f32_e32 v66, 0, v66
	v_max_f32_e32 v67, 0, v67
	v_max_f32_e32 v68, 0, v68
	v_cvt_pk_bf16_f32 v75, v75, v76
	v_cvt_pk_bf16_f32 v76, v84, v79
	v_cvt_pk_bf16_f32 v77, v80, v77
	global_store_dwordx4 v[82:83], v[74:77], off nt
	v_max_f32_e32 v69, v69, v69
	v_max_f32_e32 v70, v70, v70
	v_mul_f32_e32 v74, v66, v66
	v_max_f32_e32 v66, v71, v71
	v_mul_f32_e32 v71, v67, v67
	v_max_f32_e32 v67, v72, v72
	v_mul_f32_e32 v72, v68, v68
	v_max_f32_e32 v68, v73, v73
	v_max_f32_e32 v67, 0, v67
	v_max_f32_e32 v68, 0, v68
	v_max_f32_e32 v66, 0, v66
	v_mul_f32_e32 v67, v67, v67
	v_max_f32_e32 v69, 0, v69
	v_mul_f32_e32 v68, v68, v68
	v_max_f32_e32 v58, v58, v58
	v_max_f32_e32 v70, 0, v70
	v_mul_f32_e32 v66, v66, v66
	v_mul_f32_e32 v69, v69, v69
	v_cvt_pk_bf16_f32 v67, v67, v68
	v_cvt_pk_bf16_f32 v68, v74, v71
	v_max_f32_e32 v58, 0, v58
	v_max_f32_e32 v59, v59, v59
	v_max_f32_e32 v60, v60, v60
	v_mul_f32_e32 v70, v70, v70
	v_cvt_pk_bf16_f32 v66, v70, v66
	v_cvt_pk_bf16_f32 v69, v72, v69
	global_store_dwordx4 v[82:83], v[66:69], off offset:256 nt
	v_max_f32_e32 v62, v62, v62
	v_max_f32_e32 v59, 0, v59
	v_mul_f32_e32 v68, v58, v58
	v_max_f32_e32 v58, v63, v63
	v_max_f32_e32 v60, 0, v60
	v_max_f32_e32 v62, 0, v62
	v_max_f32_e32 v58, 0, v58
	v_mul_f32_e32 v63, v59, v59
	v_max_f32_e32 v59, v64, v64
	v_mul_f32_e32 v64, v60, v60
; __device__ __forceinline__ unsigned cvt_pk_bf16(float lo, float hi) { unsigned r; asm("v_cvt_pk_bf16_f32 %0, %1, %2" : "=v"(r) : "v"(lo), "v"(hi)); return r; }
;     __device__ __forceinline__ void operator()(const f32x4 (&acc)[2][2][4][2], const Unit& u, int wr, int wc, int fr, int fq) const {
;         const int row0 = u.pm * BM + wr * 64 + fr, col0 = u.pn * BM + wc * 32 + 8 * fq;
; #pragma unroll
;         for (int ai = 0; ai < 2; ++ai)
; #pragma unroll
;             for (int m = 0; m < 4; ++m) { bf16_t* rowp = O + (size_t)(row0 + ai * HALF + m * 16) * ldc + col0;
; #pragma unroll
;                 for (int bj = 0; bj < 2; ++bj) { f32x4 v0 = acc[ai][bj][m][0], v1 = acc[ai][bj][m][1];
;                     if (ACT == 1) {
; #pragma unroll
;                         for (int j = 0; j < 4; ++j) { float a = fmaxf(v0[j], 0.f), b = fmaxf(v1[j], 0.f); v0[j] = a * a; v1[j] = b * b; } }
;                     u32x4 w; w.x = cvt_pk_bf16(v0[0], v0[1]); w.y = cvt_pk_bf16(v0[2], v0[3]); w.z = cvt_pk_bf16(v1[0], v1[1]); w.w = cvt_pk_bf16(v1[2], v1[3]);
;                     if (ACT == 1) __builtin_nontemporal_store(w, (u32x4*)(rowp + bj * HALF));
;                     else *(u32x4*)(rowp + bj * HALF) = w; } }
	v_max_f32_e32 v60, v65, v65
	v_mul_f32_e32 v62, v62, v62
	v_mul_f32_e32 v58, v58, v58
	v_max_f32_e32 v59, 0, v59
	v_max_f32_e32 v60, 0, v60
	v_max_f32_e32 v61, v61, v61
	s_mov_b32 s8, 0x200000
	v_mul_f32_e32 v59, v59, v59
	v_max_f32_e32 v61, 0, v61
	v_mul_f32_e32 v60, v60, v60
	v_cvt_pk_bf16_f32 v58, v62, v58
	v_add_co_u32_e32 v62, vcc, s8, v140
	v_max_f32_e32 v50, v50, v50
	v_max_f32_e32 v51, v51, v51
	v_max_f32_e32 v52, v52, v52
	v_mul_f32_e32 v61, v61, v61
	v_cvt_pk_bf16_f32 v59, v59, v60
	v_cvt_pk_bf16_f32 v60, v68, v63
	v_addc_co_u32_e32 v63, vcc, 0, v141, vcc
	v_max_f32_e32 v50, 0, v50
	v_max_f32_e32 v51, 0, v51
	v_max_f32_e32 v52, 0, v52
	v_cvt_pk_bf16_f32 v61, v64, v61
	global_store_dwordx4 v[62:63], v[58:61], off nt
	v_max_f32_e32 v53, v53, v53
	s_mov_b64 s[38:39], 0x200000
	v_mul_f32_e32 v58, v50, v50
	v_max_f32_e32 v50, v55, v55
	v_mul_f32_e32 v55, v51, v51
	v_max_f32_e32 v51, v56, v56
	v_mul_f32_e32 v56, v52, v52
	v_max_f32_e32 v52, v57, v57
	v_max_f32_e32 v51, 0, v51
	v_max_f32_e32 v52, 0, v52
	v_max_f32_e32 v54, v54, v54
	v_max_f32_e32 v50, 0, v50
	v_mul_f32_e32 v51, v51, v51
	v_max_f32_e32 v53, 0, v53
	v_mul_f32_e32 v52, v52, v52
	v_max_f32_e32 v42, v42, v42
	v_lshl_add_u64 v[66:67], v[140:141], 0, s[38:39]
	v_max_f32_e32 v54, 0, v54
	v_mul_f32_e32 v50, v50, v50
	v_mul_f32_e32 v53, v53, v53
	v_cvt_pk_bf16_f32 v51, v51, v52
	v_cvt_pk_bf16_f32 v52, v58, v55
	v_max_f32_e32 v42, 0, v42
	v_max_f32_e32 v43, v43, v43
	v_max_f32_e32 v44, v44, v44
	v_mul_f32_e32 v54, v54, v54
	v_cvt_pk_bf16_f32 v50, v54, v50
	v_cvt_pk_bf16_f32 v53, v56, v53
	global_store_dwordx4 v[66:67], v[50:53], off offset:256 nt
	v_max_f32_e32 v46, v46, v46
	v_max_f32_e32 v43, 0, v43
	v_mul_f32_e32 v52, v42, v42
	v_max_f32_e32 v42, v47, v47
	v_max_f32_e32 v44, 0, v44
	v_max_f32_e32 v46, 0, v46
	v_max_f32_e32 v42, 0, v42
	v_mul_f32_e32 v47, v43, v43
	v_max_f32_e32 v43, v48, v48
	v_mul_f32_e32 v48, v44, v44
	v_max_f32_e32 v44, v49, v49
	v_mul_f32_e32 v46, v46, v46
	v_mul_f32_e32 v42, v42, v42
	v_max_f32_e32 v43, 0, v43
	v_max_f32_e32 v44, 0, v44
	v_max_f32_e32 v45, v45, v45
	s_mov_b32 s8, 0x240000
	v_mul_f32_e32 v43, v43, v43
	v_max_f32_e32 v45, 0, v45
	v_mul_f32_e32 v44, v44, v44
	v_cvt_pk_bf16_f32 v42, v46, v42
	v_add_co_u32_e32 v46, vcc, s8, v140
	v_max_f32_e32 v34, v34, v34
	v_max_f32_e32 v35, v35, v35
	v_max_f32_e32 v36, v36, v36
	v_mul_f32_e32 v45, v45, v45
	v_cvt_pk_bf16_f32 v43, v43, v44
	v_cvt_pk_bf16_f32 v44, v52, v47
	v_addc_co_u32_e32 v47, vcc, 0, v141, vcc
	v_max_f32_e32 v34, 0, v34
	v_max_f32_e32 v35, 0, v35
	v_max_f32_e32 v36, 0, v36
	v_cvt_pk_bf16_f32 v45, v48, v45
	global_store_dwordx4 v[46:47], v[42:45], off nt
	v_max_f32_e32 v37, v37, v37
	s_mov_b64 s[38:39], 0x240000
	v_mul_f32_e32 v42, v34, v34
	v_max_f32_e32 v34, v39, v39
	v_mul_f32_e32 v39, v35, v35
	v_max_f32_e32 v35, v40, v40
	v_mul_f32_e32 v40, v36, v36
	v_max_f32_e32 v36, v41, v41
	v_max_f32_e32 v35, 0, v35
	v_max_f32_e32 v36, 0, v36
	v_max_f32_e32 v38, v38, v38
	v_max_f32_e32 v34, 0, v34
	v_mul_f32_e32 v35, v35, v35
	v_max_f32_e32 v37, 0, v37
	v_mul_f32_e32 v36, v36, v36
	v_max_f32_e32 v26, v26, v26
	v_lshl_add_u64 v[50:51], v[140:141], 0, s[38:39]
	v_max_f32_e32 v38, 0, v38
	v_mul_f32_e32 v34, v34, v34
	v_mul_f32_e32 v37, v37, v37
	v_cvt_pk_bf16_f32 v35, v35, v36
	v_cvt_pk_bf16_f32 v36, v42, v39
	v_max_f32_e32 v26, 0, v26
	v_max_f32_e32 v27, v27, v27
	v_max_f32_e32 v28, v28, v28
	v_mul_f32_e32 v38, v38, v38
	v_cvt_pk_bf16_f32 v34, v38, v34
	v_cvt_pk_bf16_f32 v37, v40, v37
	global_store_dwordx4 v[50:51], v[34:37], off offset:256 nt
	v_max_f32_e32 v30, v30, v30
	v_max_f32_e32 v27, 0, v27
	v_mul_f32_e32 v36, v26, v26
	v_max_f32_e32 v26, v31, v31
	v_max_f32_e32 v28, 0, v28
	v_max_f32_e32 v30, 0, v30
; __device__ __forceinline__ unsigned cvt_pk_bf16(float lo, float hi) { unsigned r; asm("v_cvt_pk_bf16_f32 %0, %1, %2" : "=v"(r) : "v"(lo), "v"(hi)); return r; }
; #define PG8_WAIT_V(n) asm volatile("s_waitcnt vmcnt(" #n ")" ::: "memory")
; #define PG8_BAR __builtin_amdgcn_s_barrier()
;     __device__ __forceinline__ void operator()(const f32x4 (&acc)[2][2][4][2], const Unit& u, int wr, int wc, int fr, int fq) const {
;         const int row0 = u.pm * BM + wr * 64 + fr, col0 = u.pn * BM + wc * 32 + 8 * fq;
; #pragma unroll
;         for (int ai = 0; ai < 2; ++ai)
; #pragma unroll
;             for (int m = 0; m < 4; ++m) { bf16_t* rowp = O + (size_t)(row0 + ai * HALF + m * 16) * ldc + col0;
; #pragma unroll
;                 for (int bj = 0; bj < 2; ++bj) { f32x4 v0 = acc[ai][bj][m][0], v1 = acc[ai][bj][m][1];
;                     if (ACT == 1) {
; #pragma unroll
;                         for (int j = 0; j < 4; ++j) { float a = fmaxf(v0[j], 0.f), b = fmaxf(v1[j], 0.f); v0[j] = a * a; v1[j] = b * b; } }
;                     u32x4 w; w.x = cvt_pk_bf16(v0[0], v0[1]); w.y = cvt_pk_bf16(v0[2], v0[3]); w.z = cvt_pk_bf16(v1[0], v1[1]); w.w = cvt_pk_bf16(v1[2], v1[3]);
;                     if (ACT == 1) __builtin_nontemporal_store(w, (u32x4*)(rowp + bj * HALF));
;                     else *(u32x4*)(rowp + bj * HALF) = w; } }
; template <class Epi, class Sched>
; __device__ __forceinline__ void gemm_phase(LAS unsigned char* lds, const Gemm g, const Sched& S, const Epi& E) {
;     ...
;         E(acc, cur, wr, wc, fr, fq);
;         if (!has_next) break;
; #pragma unroll
;         for (int a = 0; a < 2; ++a)
; #pragma unroll
;             for (int b = 0; b < 2; ++b)
; #pragma unroll
;                 for (int m = 0; m < 4; ++m)
; #pragma unroll
;                     for (int n = 0; n < 2; ++n) acc[a][b][m][n] = (f32x4){0.f, 0.f, 0.f, 0.f};
;         cur = nxt; cA = nA; cB = nB; ++ui;
;     }
;     PG8_WAIT_V(0);
;     if (wr == 0) PG8_BAR;
;     PG8_BAR;
	v_max_f32_e32 v26, 0, v26
	v_mul_f32_e32 v31, v27, v27
	v_max_f32_e32 v27, v32, v32
	v_mul_f32_e32 v32, v28, v28
	v_max_f32_e32 v28, v33, v33
	v_mul_f32_e32 v30, v30, v30
	v_mul_f32_e32 v26, v26, v26
	v_max_f32_e32 v27, 0, v27
	v_max_f32_e32 v28, 0, v28
	v_max_f32_e32 v29, v29, v29
	s_mov_b32 s8, 0x280000
	v_mul_f32_e32 v27, v27, v27
	v_max_f32_e32 v29, 0, v29
	v_mul_f32_e32 v28, v28, v28
	v_cvt_pk_bf16_f32 v26, v30, v26
	v_add_co_u32_e32 v30, vcc, s8, v140
	v_max_f32_e32 v18, v18, v18
	v_max_f32_e32 v19, v19, v19
	v_max_f32_e32 v20, v20, v20
	v_mul_f32_e32 v29, v29, v29
	v_cvt_pk_bf16_f32 v27, v27, v28
	v_cvt_pk_bf16_f32 v28, v36, v31
	v_addc_co_u32_e32 v31, vcc, 0, v141, vcc
	v_max_f32_e32 v18, 0, v18
	v_max_f32_e32 v19, 0, v19
	v_max_f32_e32 v20, 0, v20
	v_cvt_pk_bf16_f32 v29, v32, v29
	global_store_dwordx4 v[30:31], v[26:29], off nt
	v_max_f32_e32 v21, v21, v21
	s_mov_b64 s[38:39], 0x280000
	v_mul_f32_e32 v26, v18, v18
	v_max_f32_e32 v18, v23, v23
	v_mul_f32_e32 v23, v19, v19
	v_max_f32_e32 v19, v24, v24
	v_mul_f32_e32 v24, v20, v20
	v_max_f32_e32 v20, v25, v25
	v_max_f32_e32 v19, 0, v19
	v_max_f32_e32 v20, 0, v20
	v_max_f32_e32 v22, v22, v22
	v_max_f32_e32 v18, 0, v18
	v_mul_f32_e32 v19, v19, v19
	v_max_f32_e32 v21, 0, v21
	v_mul_f32_e32 v20, v20, v20
	v_max_f32_e32 v10, v10, v10
	v_lshl_add_u64 v[34:35], v[140:141], 0, s[38:39]
	v_max_f32_e32 v22, 0, v22
	v_mul_f32_e32 v18, v18, v18
	v_mul_f32_e32 v21, v21, v21
	v_cvt_pk_bf16_f32 v19, v19, v20
	v_cvt_pk_bf16_f32 v20, v26, v23
	v_max_f32_e32 v10, 0, v10
	v_max_f32_e32 v11, v11, v11
	v_max_f32_e32 v12, v12, v12
	v_mul_f32_e32 v22, v22, v22
	v_cvt_pk_bf16_f32 v18, v22, v18
	v_cvt_pk_bf16_f32 v21, v24, v21
	global_store_dwordx4 v[34:35], v[18:21], off offset:256 nt
	v_max_f32_e32 v14, v14, v14
	v_max_f32_e32 v11, 0, v11
	v_mul_f32_e32 v20, v10, v10
	v_max_f32_e32 v10, v15, v15
	v_max_f32_e32 v12, 0, v12
	v_max_f32_e32 v14, 0, v14
	v_max_f32_e32 v10, 0, v10
	v_mul_f32_e32 v15, v11, v11
	v_max_f32_e32 v11, v16, v16
	v_mul_f32_e32 v16, v12, v12
	v_max_f32_e32 v12, v17, v17
	v_mul_f32_e32 v14, v14, v14
	v_mul_f32_e32 v10, v10, v10
	v_max_f32_e32 v11, 0, v11
	v_max_f32_e32 v12, 0, v12
	v_max_f32_e32 v13, v13, v13
	s_mov_b32 s8, 0x2c0000
	v_mul_f32_e32 v11, v11, v11
	v_max_f32_e32 v13, 0, v13
	v_mul_f32_e32 v12, v12, v12
	v_cvt_pk_bf16_f32 v10, v14, v10
	v_add_co_u32_e32 v14, vcc, s8, v140
	v_max_f32_e32 v2, v2, v2
	v_max_f32_e32 v3, v3, v3
	v_max_f32_e32 v4, v4, v4
	v_mul_f32_e32 v13, v13, v13
	v_cvt_pk_bf16_f32 v11, v11, v12
	v_cvt_pk_bf16_f32 v12, v20, v15
	v_addc_co_u32_e32 v15, vcc, 0, v141, vcc
	v_max_f32_e32 v2, 0, v2
	v_max_f32_e32 v3, 0, v3
	v_max_f32_e32 v4, 0, v4
	v_cvt_pk_bf16_f32 v13, v16, v13
	global_store_dwordx4 v[14:15], v[10:13], off nt
	v_max_f32_e32 v5, v5, v5
	s_mov_b64 s[38:39], 0x2c0000
	v_mul_f32_e32 v10, v2, v2
	v_max_f32_e32 v2, v7, v7
	v_mul_f32_e32 v7, v3, v3
	v_max_f32_e32 v3, v8, v8
	v_mul_f32_e32 v8, v4, v4
	v_max_f32_e32 v4, v9, v9
	v_max_f32_e32 v6, v6, v6
	v_max_f32_e32 v2, 0, v2
	v_max_f32_e32 v3, 0, v3
	v_max_f32_e32 v4, 0, v4
	v_max_f32_e32 v5, 0, v5
	v_lshl_add_u64 v[18:19], v[140:141], 0, s[38:39]
	v_max_f32_e32 v6, 0, v6
	v_mul_f32_e32 v2, v2, v2
	v_mul_f32_e32 v3, v3, v3
	v_mul_f32_e32 v4, v4, v4
	v_mul_f32_e32 v5, v5, v5
	s_and_b64 vcc, exec, s[40:41]
	s_mov_b32 s68, s26
	s_mov_b32 s8, s28
	s_mov_b64 s[46:47], s[44:45]
	s_mov_b64 s[48:49], s[42:43]
	v_mul_f32_e32 v6, v6, v6
	v_cvt_pk_bf16_f32 v2, v6, v2
	v_cvt_pk_bf16_f32 v3, v3, v4
	v_cvt_pk_bf16_f32 v4, v10, v7
	v_cvt_pk_bf16_f32 v5, v8, v5
	global_store_dwordx4 v[18:19], v[2:5], off offset:256 nt
	s_cbranch_vccz .LBB0_70
	s_waitcnt vmcnt(0)
	s_cmpk_gt_u32 s52, 0xff
	s_cbranch_scc1 .LBB0_77
	s_barrier

; #define PG8_STAGE(bufoff, gbase, voff) do { _Pragma("unroll") for (int _i = 0; _i < 2; ++_i) \
;         __builtin_amdgcn_global_load_lds((const unsigned*)((const char*)(gbase) + (voff)[_i]), (LAS unsigned*)(lds + (bufoff) + ldsw + _i * 8192), 16, 0, 0); } while (0)
; #define PG8_LDA(dst, b, h) do { _Pragma("unroll") for (int m = 0; m < 4; ++m) _Pragma("unroll") for (int k = 0; k < 2; ++k) dst[m][k] = *(const LAS bf16x8*)(lds + PG8_SA(b, h) + aoff + m * 2048 + k * 1024); } while (0)
; #define PG8_LDB(dst, b, h) do { _Pragma("unroll") for (int n = 0; n < 2; ++n) _Pragma("unroll") for (int k = 0; k < 2; ++k) dst[n][k] = *(const LAS bf16x8*)(lds + PG8_SB(b, h) + boff + n * 2048 + k * 1024); } while (0)
; #define PG8_MMA(ai, bj, At, Bt) do { __builtin_amdgcn_s_setprio(1); _Pragma("unroll") for (int m = 0; m < 4; ++m) _Pragma("unroll") for (int n = 0; n < 2; ++n) _Pragma("unroll") for (int k = 0; k < 2; ++k) \
;         acc[ai][bj][m][n] = __builtin_amdgcn_mfma_f32_16x16x32_bf16(Bt[n][k], At[m][k], acc[ai][bj][m][n], 0, 0, 0); __builtin_amdgcn_s_setprio(0); } while (0)
; #define PG8_WAIT_V(n) asm volatile("s_waitcnt vmcnt(" #n ")" ::: "memory")
; #define PG8_WAIT_L(n) asm volatile("s_waitcnt lgkmcnt(" #n ")" ::: "memory")
; template <class Epi, class Sched>
; __device__ __forceinline__ void gemm_phase(LAS unsigned char* lds, const Gemm g, const Sched& S, const Epi& E) {
;     ...
;         for (int t = 0; t < nt; t += 2) {
;             const bool last = (t == nt - 2);
;             const char* a1 = cA + (size_t)(t + 1) * kstep;
;             const char* a2 = last ? nA : cA + (size_t)(t + 2) * kstep; const char* b2 = last ? nB : cB + (size_t)(t + 2) * kstep;
;             const char* a3 = a2 + kstep; const char* b3 = b2 + kstep;
;             PG8_LDB(B0, 0, 0); PG8_SCHED; PG8_LDA(At, 0, 0); PG8_STAGE(PG8_SA(1, 1), a1 + hstep, voffA);
;             PG8_WAIT_L(8); PG8_BAR; PG8_WAIT_L(0); PG8_MMA(0, 0, At, B0); PG8_BAR; PG8_SCHED;
;             PG8_LDB(B1, 0, 1); PG8_STAGE(PG8_SB(0, 0), b2, voffB);
;             PG8_BAR; PG8_WAIT_L(0); PG8_MMA(0, 1, At, B1); PG8_BAR;
;             PG8_LDA(At, 0, 1); PG8_STAGE(PG8_SA(0, 0), a2, voffA);
;             PG8_BAR; PG8_WAIT_L(0); PG8_MMA(1, 0, At, B0); PG8_BAR; PG8_SCHED;
;             PG8_STAGE(PG8_SB(0, 1), b2 + hstep, voffB);
;             PG8_WAIT_V(6); PG8_BAR; PG8_MMA(1, 1, At, B1); PG8_BAR;
.LBB0_99:
	s_add_i32 s38, 0, 0x10000
	v_add_u32_e32 v110, s38, v169
	ds_read_b128 v[98:101], v110
	ds_read_b128 v[102:105], v110 offset:1024
	ds_read_b128 v[106:109], v110 offset:2048
	ds_read_b128 v[110:113], v110 offset:3072
	ds_read_b128 v[152:155], v171
	ds_read_b128 v[160:163], v171 offset:1024
	ds_read_b128 v[164:167], v171 offset:2048
	ds_read_b128 v[172:175], v171 offset:3072
	ds_read_b128 v[176:179], v171 offset:4096
	ds_read_b128 v[180:183], v171 offset:5120
	ds_read_b128 v[184:187], v171 offset:6144
	ds_read_b128 v[188:191], v171 offset:7168
	s_add_i32 s39, 0, 0x14000
	v_add_u32_e32 v156, s39, v169
	ds_read_b128 v[192:195], v156
	ds_read_b128 v[196:199], v156 offset:1024
	ds_read_b128 v[200:203], v156 offset:2048
	ds_read_b128 v[204:207], v156 offset:3072
	s_add_u32 s56, s28, 0x100
	s_addc_u32 s57, s29, 0
	s_cmp_eq_u32 s81, 28
	s_cselect_b32 s61, s51, s57
	s_cselect_b32 s60, s77, s56
	s_cselect_b32 s59, s49, s80
	s_cselect_b32 s58, s78, s79
	v_lshl_add_u64 v[156:157], s[28:29], 0, v[150:151]
	s_add_i32 m0, s9, 0xc000
	s_nop 0
	global_load_lds_dwordx4 v[156:157], off
	v_lshl_add_u64 v[156:157], s[28:29], 0, v[148:149]
	s_add_i32 m0, s9, 0xe000
	s_nop 0
	global_load_lds_dwordx4 v[156:157], off
	s_waitcnt lgkmcnt(4)
	s_barrier
	s_waitcnt lgkmcnt(0)
	s_setprio 1
	v_mfma_f32_16x16x32_bf16 v[142:145], v[98:101], v[152:155], v[142:145]
	v_mfma_f32_16x16x32_bf16 v[138:141], v[106:109], v[152:155], v[138:141]
	v_mfma_f32_16x16x32_bf16 v[126:129], v[98:101], v[164:167], v[126:129]
	v_mfma_f32_16x16x32_bf16 v[122:125], v[106:109], v[164:167], v[122:125]
	v_mfma_f32_16x16x32_bf16 v[94:97], v[98:101], v[176:179], v[94:97]
	v_mfma_f32_16x16x32_bf16 v[90:93], v[106:109], v[176:179], v[90:93]
	v_mfma_f32_16x16x32_bf16 v[86:89], v[98:101], v[184:187], v[86:89]
	v_mfma_f32_16x16x32_bf16 v[82:85], v[106:109], v[184:187], v[82:85]
	v_mfma_f32_16x16x32_bf16 v[142:145], v[102:105], v[160:163], v[142:145]
	v_mfma_f32_16x16x32_bf16 v[138:141], v[110:113], v[160:163], v[138:141]
	v_mfma_f32_16x16x32_bf16 v[126:129], v[102:105], v[172:175], v[126:129]
	v_mfma_f32_16x16x32_bf16 v[122:125], v[110:113], v[172:175], v[122:125]
	v_mfma_f32_16x16x32_bf16 v[94:97], v[102:105], v[180:183], v[94:97]
	v_mfma_f32_16x16x32_bf16 v[90:93], v[110:113], v[180:183], v[90:93]
	v_mfma_f32_16x16x32_bf16 v[86:89], v[102:105], v[188:191], v[86:89]
	v_mfma_f32_16x16x32_bf16 v[82:85], v[110:113], v[188:191], v[82:85]
	v_mfma_f32_16x16x32_bf16 v[134:137], v[192:195], v[152:155], v[134:137]
	v_mfma_f32_16x16x32_bf16 v[130:133], v[200:203], v[152:155], v[130:133]
	v_mfma_f32_16x16x32_bf16 v[118:121], v[192:195], v[164:167], v[118:121]
	v_mfma_f32_16x16x32_bf16 v[114:117], v[200:203], v[164:167], v[114:117]
	v_mfma_f32_16x16x32_bf16 v[78:81], v[192:195], v[176:179], v[78:81]
	v_mfma_f32_16x16x32_bf16 v[74:77], v[200:203], v[176:179], v[74:77]
	v_mfma_f32_16x16x32_bf16 v[70:73], v[192:195], v[184:187], v[70:73]
	v_mfma_f32_16x16x32_bf16 v[66:69], v[200:203], v[184:187], v[66:69]
	v_mfma_f32_16x16x32_bf16 v[134:137], v[196:199], v[160:163], v[134:137]
	v_mfma_f32_16x16x32_bf16 v[130:133], v[204:207], v[160:163], v[130:133]
	v_mfma_f32_16x16x32_bf16 v[118:121], v[196:199], v[172:175], v[118:121]
	v_mfma_f32_16x16x32_bf16 v[114:117], v[204:207], v[172:175], v[114:117]
	v_mfma_f32_16x16x32_bf16 v[78:81], v[196:199], v[180:183], v[78:81]
	v_mfma_f32_16x16x32_bf16 v[74:77], v[204:207], v[180:183], v[74:77]
	v_mfma_f32_16x16x32_bf16 v[70:73], v[196:199], v[188:191], v[70:73]
	v_mfma_f32_16x16x32_bf16 v[66:69], v[204:207], v[188:191], v[66:69]
	s_setprio 0
	s_barrier
	ds_read_b128 v[152:155], v171 offset:16384
	ds_read_b128 v[160:163], v171 offset:17408
	ds_read_b128 v[164:167], v171 offset:18432
	ds_read_b128 v[172:175], v171 offset:19456
	ds_read_b128 v[176:179], v171 offset:20480
	ds_read_b128 v[180:183], v171 offset:21504
	ds_read_b128 v[184:187], v171 offset:22528
	ds_read_b128 v[188:191], v171 offset:23552
	s_add_i32 s28, s38, s67
	v_lshl_add_u64 v[156:157], s[58:59], 0, v[0:1]
	s_mov_b32 m0, s28
	v_lshl_add_u64 v[210:211], s[58:59], 0, v[146:147]
	global_load_lds_dwordx4 v[156:157], off
	s_add_i32 m0, s28, 0x2000
	s_nop 0
	global_load_lds_dwordx4 v[210:211], off
	s_mov_b32 m0, s9
	v_lshl_add_u64 v[212:213], s[60:61], 0, v[0:1]
	global_load_lds_dwordx4 v[212:213], off
	v_lshl_add_u64 v[214:215], s[60:61], 0, v[146:147]
	s_mov_b32 m0, s68
	s_nop 0
	global_load_lds_dwordx4 v[214:215], off
	s_waitcnt vmcnt(4)
	s_waitcnt lgkmcnt(0)
	s_barrier
	s_setprio 1
	v_mfma_f32_16x16x32_bf16 v[62:65], v[98:101], v[152:155], v[62:65]
	v_mfma_f32_16x16x32_bf16 v[58:61], v[106:109], v[152:155], v[58:61]
	v_mfma_f32_16x16x32_bf16 v[46:49], v[98:101], v[164:167], v[46:49]
	v_mfma_f32_16x16x32_bf16 v[42:45], v[106:109], v[164:167], v[42:45]
	v_mfma_f32_16x16x32_bf16 v[30:33], v[98:101], v[176:179], v[30:33]
	v_mfma_f32_16x16x32_bf16 v[26:29], v[106:109], v[176:179], v[26:29]
	v_mfma_f32_16x16x32_bf16 v[22:25], v[98:101], v[184:187], v[22:25]
	v_mfma_f32_16x16x32_bf16 v[18:21], v[106:109], v[184:187], v[18:21]
	v_mfma_f32_16x16x32_bf16 v[62:65], v[102:105], v[160:163], v[62:65]
	v_mfma_f32_16x16x32_bf16 v[58:61], v[110:113], v[160:163], v[58:61]
	v_mfma_f32_16x16x32_bf16 v[46:49], v[102:105], v[172:175], v[46:49]
	v_mfma_f32_16x16x32_bf16 v[42:45], v[110:113], v[172:175], v[42:45]
	v_mfma_f32_16x16x32_bf16 v[30:33], v[102:105], v[180:183], v[30:33]
	v_mfma_f32_16x16x32_bf16 v[26:29], v[110:113], v[180:183], v[26:29]
	v_mfma_f32_16x16x32_bf16 v[22:25], v[102:105], v[188:191], v[22:25]
	v_mfma_f32_16x16x32_bf16 v[18:21], v[110:113], v[188:191], v[18:21]
	v_mfma_f32_16x16x32_bf16 v[54:57], v[192:195], v[152:155], v[54:57]
	v_mfma_f32_16x16x32_bf16 v[50:53], v[200:203], v[152:155], v[50:53]
	v_mfma_f32_16x16x32_bf16 v[38:41], v[192:195], v[164:167], v[38:41]
	v_mfma_f32_16x16x32_bf16 v[34:37], v[200:203], v[164:167], v[34:37]
	v_mfma_f32_16x16x32_bf16 v[14:17], v[192:195], v[176:179], v[14:17]
	v_mfma_f32_16x16x32_bf16 v[10:13], v[200:203], v[176:179], v[10:13]
	v_mfma_f32_16x16x32_bf16 v[6:9], v[192:195], v[184:187], v[6:9]
	v_mfma_f32_16x16x32_bf16 v[2:5], v[200:203], v[184:187], v[2:5]
	v_mfma_f32_16x16x32_bf16 v[54:57], v[196:199], v[160:163], v[54:57]
	v_mfma_f32_16x16x32_bf16 v[50:53], v[204:207], v[160:163], v[50:53]
	v_mfma_f32_16x16x32_bf16 v[38:41], v[196:199], v[172:175], v[38:41]
	v_mfma_f32_16x16x32_bf16 v[34:37], v[204:207], v[172:175], v[34:37]
	v_mfma_f32_16x16x32_bf16 v[14:17], v[196:199], v[180:183], v[14:17]
	v_mfma_f32_16x16x32_bf16 v[10:13], v[204:207], v[180:183], v[10:13]
	v_mfma_f32_16x16x32_bf16 v[6:9], v[196:199], v[188:191], v[6:9]
	v_mfma_f32_16x16x32_bf16 v[2:5], v[204:207], v[188:191], v[2:5]
	s_setprio 0
	s_barrier
; #define PG8_STAGE(bufoff, gbase, voff) do { _Pragma("unroll") for (int _i = 0; _i < 2; ++_i) \
;         __builtin_amdgcn_global_load_lds((const unsigned*)((const char*)(gbase) + (voff)[_i]), (LAS unsigned*)(lds + (bufoff) + ldsw + _i * 8192), 16, 0, 0); } while (0)
; #define PG8_LDA(dst, b, h) do { _Pragma("unroll") for (int m = 0; m < 4; ++m) _Pragma("unroll") for (int k = 0; k < 2; ++k) dst[m][k] = *(const LAS bf16x8*)(lds + PG8_SA(b, h) + aoff + m * 2048 + k * 1024); } while (0)
; #define PG8_LDB(dst, b, h) do { _Pragma("unroll") for (int n = 0; n < 2; ++n) _Pragma("unroll") for (int k = 0; k < 2; ++k) dst[n][k] = *(const LAS bf16x8*)(lds + PG8_SB(b, h) + boff + n * 2048 + k * 1024); } while (0)
; #define PG8_MMA(ai, bj, At, Bt) do { __builtin_amdgcn_s_setprio(1); _Pragma("unroll") for (int m = 0; m < 4; ++m) _Pragma("unroll") for (int n = 0; n < 2; ++n) _Pragma("unroll") for (int k = 0; k < 2; ++k) \
;         acc[ai][bj][m][n] = __builtin_amdgcn_mfma_f32_16x16x32_bf16(Bt[n][k], At[m][k], acc[ai][bj][m][n], 0, 0, 0); __builtin_amdgcn_s_setprio(0); } while (0)
; #define PG8_WAIT_L(n) asm volatile("s_waitcnt lgkmcnt(" #n ")" ::: "memory")
; #define PG8_BAR __builtin_amdgcn_s_barrier()
; #define PG8_SCHED __builtin_amdgcn_sched_barrier(0)
; template <class Epi, class Sched>
; __device__ __forceinline__ void gemm_phase(LAS unsigned char* lds, const Gemm g, const Sched& S, const Epi& E) {
;     ...
;             PG8_LDB(B0, 1, 0); PG8_SCHED; PG8_LDA(At, 1, 0); PG8_STAGE(PG8_SA(0, 1), a2 + hstep, voffA);
;             PG8_WAIT_L(8); PG8_BAR; PG8_WAIT_L(0); PG8_MMA(0, 0, At, B0); PG8_BAR; PG8_SCHED;
;             PG8_LDB(B1, 1, 1); PG8_STAGE(PG8_SB(1, 0), b3, voffB);
;             PG8_BAR; PG8_WAIT_L(0); PG8_MMA(0, 1, At, B1); PG8_BAR;
	s_add_u32 s28, s58, 0x80000
	s_addc_u32 s29, s59, 0
	s_add_i32 s38, s39, s67
	v_lshl_add_u64 v[98:99], s[28:29], 0, v[0:1]
	s_mov_b32 m0, s38
	s_nop 0
	global_load_lds_dwordx4 v[98:99], off
	v_lshl_add_u64 v[98:99], s[28:29], 0, v[146:147]
	s_add_i32 m0, s38, 0x2000
	s_nop 0
	global_load_lds_dwordx4 v[98:99], off
	s_add_u32 s28, s60, 0x80000
	s_addc_u32 s29, s61, 0
	s_mov_b32 m0, s69
	v_lshl_add_u64 v[192:193], s[28:29], 0, v[0:1]
	global_load_lds_dwordx4 v[192:193], off
	v_lshl_add_u64 v[192:193], s[28:29], 0, v[146:147]
	s_mov_b32 m0, s70
	s_nop 0
	global_load_lds_dwordx4 v[192:193], off
	s_add_i32 s38, 0, 0x18000
	v_add_u32_e32 v110, s38, v169
	ds_read_b128 v[98:101], v110
	ds_read_b128 v[102:105], v110 offset:1024
	ds_read_b128 v[106:109], v110 offset:2048
	ds_read_b128 v[110:113], v110 offset:3072
	ds_read_b128 v[152:155], v171 offset:32768
	ds_read_b128 v[160:163], v171 offset:33792
	ds_read_b128 v[164:167], v171 offset:34816
	ds_read_b128 v[172:175], v171 offset:35840
	ds_read_b128 v[176:179], v171 offset:36864
	ds_read_b128 v[180:183], v171 offset:37888
	ds_read_b128 v[184:187], v171 offset:38912
	ds_read_b128 v[188:191], v171 offset:39936
	s_add_i32 s39, 0, 0x1c000
	v_add_u32_e32 v204, s39, v169
	ds_read_b128 v[192:195], v204
	ds_read_b128 v[196:199], v204 offset:1024
	ds_read_b128 v[200:203], v204 offset:2048
	ds_read_b128 v[204:207], v204 offset:3072
	s_waitcnt lgkmcnt(4)
	s_barrier
	s_waitcnt lgkmcnt(0)
	s_setprio 1
	v_mfma_f32_16x16x32_bf16 v[142:145], v[98:101], v[152:155], v[142:145]
	v_mfma_f32_16x16x32_bf16 v[138:141], v[106:109], v[152:155], v[138:141]
	v_mfma_f32_16x16x32_bf16 v[126:129], v[98:101], v[164:167], v[126:129]
	v_mfma_f32_16x16x32_bf16 v[122:125], v[106:109], v[164:167], v[122:125]
	v_mfma_f32_16x16x32_bf16 v[94:97], v[98:101], v[176:179], v[94:97]
	v_mfma_f32_16x16x32_bf16 v[90:93], v[106:109], v[176:179], v[90:93]
	v_mfma_f32_16x16x32_bf16 v[86:89], v[98:101], v[184:187], v[86:89]
	v_mfma_f32_16x16x32_bf16 v[82:85], v[106:109], v[184:187], v[82:85]
	v_mfma_f32_16x16x32_bf16 v[142:145], v[102:105], v[160:163], v[142:145]
	v_mfma_f32_16x16x32_bf16 v[138:141], v[110:113], v[160:163], v[138:141]
	v_mfma_f32_16x16x32_bf16 v[126:129], v[102:105], v[172:175], v[126:129]
	v_mfma_f32_16x16x32_bf16 v[122:125], v[110:113], v[172:175], v[122:125]
	v_mfma_f32_16x16x32_bf16 v[94:97], v[102:105], v[180:183], v[94:97]
	v_mfma_f32_16x16x32_bf16 v[90:93], v[110:113], v[180:183], v[90:93]
	v_mfma_f32_16x16x32_bf16 v[86:89], v[102:105], v[188:191], v[86:89]
	v_mfma_f32_16x16x32_bf16 v[82:85], v[110:113], v[188:191], v[82:85]
	v_mfma_f32_16x16x32_bf16 v[134:137], v[192:195], v[152:155], v[134:137]
	v_mfma_f32_16x16x32_bf16 v[130:133], v[200:203], v[152:155], v[130:133]
	v_mfma_f32_16x16x32_bf16 v[118:121], v[192:195], v[164:167], v[118:121]
	v_mfma_f32_16x16x32_bf16 v[114:117], v[200:203], v[164:167], v[114:117]
	v_mfma_f32_16x16x32_bf16 v[78:81], v[192:195], v[176:179], v[78:81]
	v_mfma_f32_16x16x32_bf16 v[74:77], v[200:203], v[176:179], v[74:77]
	v_mfma_f32_16x16x32_bf16 v[70:73], v[192:195], v[184:187], v[70:73]
	v_mfma_f32_16x16x32_bf16 v[66:69], v[200:203], v[184:187], v[66:69]
	v_mfma_f32_16x16x32_bf16 v[134:137], v[196:199], v[160:163], v[134:137]
	v_mfma_f32_16x16x32_bf16 v[130:133], v[204:207], v[160:163], v[130:133]
	v_mfma_f32_16x16x32_bf16 v[118:121], v[196:199], v[172:175], v[118:121]
	v_mfma_f32_16x16x32_bf16 v[114:117], v[204:207], v[172:175], v[114:117]
	v_mfma_f32_16x16x32_bf16 v[78:81], v[196:199], v[180:183], v[78:81]
	v_mfma_f32_16x16x32_bf16 v[74:77], v[204:207], v[180:183], v[74:77]
	v_mfma_f32_16x16x32_bf16 v[70:73], v[196:199], v[188:191], v[70:73]
	v_mfma_f32_16x16x32_bf16 v[66:69], v[204:207], v[188:191], v[66:69]
	s_setprio 0
	s_barrier
; #define PG8_STAGE(bufoff, gbase, voff) do { _Pragma("unroll") for (int _i = 0; _i < 2; ++_i) \
;         __builtin_amdgcn_global_load_lds((const unsigned*)((const char*)(gbase) + (voff)[_i]), (LAS unsigned*)(lds + (bufoff) + ldsw + _i * 8192), 16, 0, 0); } while (0)
; #define PG8_LDA(dst, b, h) do { _Pragma("unroll") for (int m = 0; m < 4; ++m) _Pragma("unroll") for (int k = 0; k < 2; ++k) dst[m][k] = *(const LAS bf16x8*)(lds + PG8_SA(b, h) + aoff + m * 2048 + k * 1024); } while (0)
; #define PG8_LDB(dst, b, h) do { _Pragma("unroll") for (int n = 0; n < 2; ++n) _Pragma("unroll") for (int k = 0; k < 2; ++k) dst[n][k] = *(const LAS bf16x8*)(lds + PG8_SB(b, h) + boff + n * 2048 + k * 1024); } while (0)
; #define PG8_MMA(ai, bj, At, Bt) do { __builtin_amdgcn_s_setprio(1); _Pragma("unroll") for (int m = 0; m < 4; ++m) _Pragma("unroll") for (int n = 0; n < 2; ++n) _Pragma("unroll") for (int k = 0; k < 2; ++k) \
;         acc[ai][bj][m][n] = __builtin_amdgcn_mfma_f32_16x16x32_bf16(Bt[n][k], At[m][k], acc[ai][bj][m][n], 0, 0, 0); __builtin_amdgcn_s_setprio(0); } while (0)
; #define PG8_BAR __builtin_amdgcn_s_barrier()
;     __device__ __forceinline__ void operator()(const f32x4 (&acc)[2][2][4][2], const Unit& u, int wr, int wc, int fr, int fq) const {
;         const bool lat = u.pm < 64; const int r = lat ? (u.pm >> 3) : 8;
;         const float* s = lat ? src_lat : src_ctx; float* d = lat ? dst_lat : dst_ctx;
;         const int row0 = (lat ? u.pm : u.pm - 64) * BM + wr * 64 + fr, col0 = u.pn * BM + wc * 32 + 4 * fq;
; template <class Epi, class Sched>
; __device__ __forceinline__ void gemm_phase(LAS unsigned char* lds, const Gemm g, const Sched& S, const Epi& E) {
;     ...
;             PG8_LDB(B0, 1, 0); PG8_SCHED; PG8_LDA(At, 1, 0); PG8_STAGE(PG8_SA(0, 1), a2 + hstep, voffA);
;             PG8_WAIT_L(8); PG8_BAR; PG8_WAIT_L(0); PG8_MMA(0, 0, At, B0); PG8_BAR; PG8_SCHED;
;             PG8_LDB(B1, 1, 1); PG8_STAGE(PG8_SB(1, 0), b3, voffB);
;             PG8_BAR; PG8_WAIT_L(0); PG8_MMA(0, 1, At, B1); PG8_BAR;
;             PG8_LDA(At, 1, 1); PG8_STAGE(PG8_SA(1, 0), a3, voffA);
;             PG8_BAR; PG8_WAIT_L(0); PG8_MMA(1, 0, At, B0); PG8_BAR; PG8_SCHED;
;             PG8_STAGE(PG8_SB(1, 1), b3 + hstep, voffB);
;             PG8_WAIT_V(6); PG8_BAR; PG8_MMA(1, 1, At, B1); PG8_BAR;
;         }
;         E(acc, cur, wr, wc, fr, fq);
;         if (!has_next) break;
	ds_read_b128 v[152:155], v171 offset:49152
	ds_read_b128 v[160:163], v171 offset:50176
	ds_read_b128 v[164:167], v171 offset:51200
	ds_read_b128 v[172:175], v171 offset:52224
	ds_read_b128 v[176:179], v171 offset:53248
	ds_read_b128 v[180:183], v171 offset:54272
	ds_read_b128 v[184:187], v171 offset:55296
	ds_read_b128 v[188:191], v171 offset:56320
	s_add_i32 s28, s38, s67
	v_lshl_add_u64 v[156:157], v[156:157], 0, s[36:37]
	s_mov_b32 m0, s28
	s_nop 0
	global_load_lds_dwordx4 v[156:157], off
	v_lshl_add_u64 v[156:157], v[210:211], 0, s[36:37]
	s_add_i32 m0, s28, 0x2000
	s_nop 0
	global_load_lds_dwordx4 v[156:157], off
	s_mov_b32 m0, s72
	v_lshl_add_u64 v[156:157], v[212:213], 0, s[36:37]
	global_load_lds_dwordx4 v[156:157], off
	v_lshl_add_u64 v[156:157], v[214:215], 0, s[36:37]
	s_mov_b32 m0, s73
	s_nop 0
	global_load_lds_dwordx4 v[156:157], off
	s_waitcnt vmcnt(4)
	s_waitcnt lgkmcnt(0)
	s_barrier
	s_setprio 1
	v_mfma_f32_16x16x32_bf16 v[62:65], v[98:101], v[152:155], v[62:65]
	v_mfma_f32_16x16x32_bf16 v[58:61], v[106:109], v[152:155], v[58:61]
	v_mfma_f32_16x16x32_bf16 v[46:49], v[98:101], v[164:167], v[46:49]
	v_mfma_f32_16x16x32_bf16 v[42:45], v[106:109], v[164:167], v[42:45]
	v_mfma_f32_16x16x32_bf16 v[30:33], v[98:101], v[176:179], v[30:33]
	v_mfma_f32_16x16x32_bf16 v[26:29], v[106:109], v[176:179], v[26:29]
	v_mfma_f32_16x16x32_bf16 v[22:25], v[98:101], v[184:187], v[22:25]
	v_mfma_f32_16x16x32_bf16 v[18:21], v[106:109], v[184:187], v[18:21]
	v_mfma_f32_16x16x32_bf16 v[62:65], v[102:105], v[160:163], v[62:65]
	v_mfma_f32_16x16x32_bf16 v[58:61], v[110:113], v[160:163], v[58:61]
	v_mfma_f32_16x16x32_bf16 v[46:49], v[102:105], v[172:175], v[46:49]
	v_mfma_f32_16x16x32_bf16 v[42:45], v[110:113], v[172:175], v[42:45]
	v_mfma_f32_16x16x32_bf16 v[30:33], v[102:105], v[180:183], v[30:33]
	v_mfma_f32_16x16x32_bf16 v[26:29], v[110:113], v[180:183], v[26:29]
	v_mfma_f32_16x16x32_bf16 v[22:25], v[102:105], v[188:191], v[22:25]
	v_mfma_f32_16x16x32_bf16 v[18:21], v[110:113], v[188:191], v[18:21]
	s_add_u32 s28, s58, 0x80080
	s_addc_u32 s29, s59, 0
	s_add_i32 s38, s39, s67
	v_lshl_add_u64 v[98:99], s[28:29], 0, v[0:1]
	s_mov_b32 m0, s38
	s_nop 0
	global_load_lds_dwordx4 v[98:99], off
	v_lshl_add_u64 v[98:99], s[28:29], 0, v[146:147]
	s_add_i32 m0, s38, 0x2000
	s_nop 0
	global_load_lds_dwordx4 v[98:99], off
	v_mfma_f32_16x16x32_bf16 v[54:57], v[192:195], v[152:155], v[54:57]
	v_mfma_f32_16x16x32_bf16 v[50:53], v[200:203], v[152:155], v[50:53]
	v_mfma_f32_16x16x32_bf16 v[38:41], v[192:195], v[164:167], v[38:41]
	v_mfma_f32_16x16x32_bf16 v[34:37], v[200:203], v[164:167], v[34:37]
	v_mfma_f32_16x16x32_bf16 v[14:17], v[192:195], v[176:179], v[14:17]
	v_mfma_f32_16x16x32_bf16 v[10:13], v[200:203], v[176:179], v[10:13]
	v_mfma_f32_16x16x32_bf16 v[6:9], v[192:195], v[184:187], v[6:9]
	v_mfma_f32_16x16x32_bf16 v[2:5], v[200:203], v[184:187], v[2:5]
	v_mfma_f32_16x16x32_bf16 v[54:57], v[196:199], v[160:163], v[54:57]
	v_mfma_f32_16x16x32_bf16 v[50:53], v[204:207], v[160:163], v[50:53]
	v_mfma_f32_16x16x32_bf16 v[38:41], v[196:199], v[172:175], v[38:41]
	v_mfma_f32_16x16x32_bf16 v[34:37], v[204:207], v[172:175], v[34:37]
	v_mfma_f32_16x16x32_bf16 v[14:17], v[196:199], v[180:183], v[14:17]
	v_mfma_f32_16x16x32_bf16 v[10:13], v[204:207], v[180:183], v[10:13]
	v_mfma_f32_16x16x32_bf16 v[6:9], v[196:199], v[188:191], v[6:9]
	v_mfma_f32_16x16x32_bf16 v[2:5], v[204:207], v[188:191], v[2:5]
	s_setprio 0
	s_add_i32 s81, s81, 2
	s_add_u32 s79, s79, 0x100
	s_addc_u32 s80, s80, 0
	s_cmp_gt_u32 s81, 29
	s_mov_b64 s[28:29], s[56:57]
	s_barrier
	s_cbranch_scc0 .LBB0_99
	s_cmp_lt_i32 s8, 64
	s_cselect_b64 s[58:59], -1, 0
	s_cmp_gt_i32 s8, 63
	s_cbranch_scc0 .LBB0_90
	s_mov_b64 s[60:61], 0x18000
	s_mov_b64 s[28:29], s[46:47]
	s_mov_b64 s[56:57], s[24:25]
	s_branch .LBB0_91

; #define PG8_STAGE(bufoff, gbase, voff) do { _Pragma("unroll") for (int _i = 0; _i < 2; ++_i) \
;         __builtin_amdgcn_global_load_lds((const unsigned*)((const char*)(gbase) + (voff)[_i]), (LAS unsigned*)(lds + (bufoff) + ldsw + _i * 8192), 16, 0, 0); } while (0)
; #define PG8_LDA(dst, b, h) do { _Pragma("unroll") for (int m = 0; m < 4; ++m) _Pragma("unroll") for (int k = 0; k < 2; ++k) dst[m][k] = *(const LAS bf16x8*)(lds + PG8_SA(b, h) + aoff + m * 2048 + k * 1024); } while (0)
; #define PG8_LDB(dst, b, h) do { _Pragma("unroll") for (int n = 0; n < 2; ++n) _Pragma("unroll") for (int k = 0; k < 2; ++k) dst[n][k] = *(const LAS bf16x8*)(lds + PG8_SB(b, h) + boff + n * 2048 + k * 1024); } while (0)
; #define PG8_MMA(ai, bj, At, Bt) do { __builtin_amdgcn_s_setprio(1); _Pragma("unroll") for (int m = 0; m < 4; ++m) _Pragma("unroll") for (int n = 0; n < 2; ++n) _Pragma("unroll") for (int k = 0; k < 2; ++k) \
;         acc[ai][bj][m][n] = __builtin_amdgcn_mfma_f32_16x16x32_bf16(Bt[n][k], At[m][k], acc[ai][bj][m][n], 0, 0, 0); __builtin_amdgcn_s_setprio(0); } while (0)
; #define PG8_WAIT_V(n) asm volatile("s_waitcnt vmcnt(" #n ")" ::: "memory")
; #define PG8_WAIT_L(n) asm volatile("s_waitcnt lgkmcnt(" #n ")" ::: "memory")
; template <class Epi, class Sched>
; __device__ __forceinline__ void gemm_phase(LAS unsigned char* lds, const Gemm g, const Sched& S, const Epi& E) {
;     ...
;         for (int t = 0; t < nt; t += 2) {
;             const bool last = (t == nt - 2);
;             const char* a1 = cA + (size_t)(t + 1) * kstep;
;             const char* a2 = last ? nA : cA + (size_t)(t + 2) * kstep; const char* b2 = last ? nB : cB + (size_t)(t + 2) * kstep;
;             const char* a3 = a2 + kstep; const char* b3 = b2 + kstep;
;             PG8_LDB(B0, 0, 0); PG8_SCHED; PG8_LDA(At, 0, 0); PG8_STAGE(PG8_SA(1, 1), a1 + hstep, voffA);
;             PG8_WAIT_L(8); PG8_BAR; PG8_WAIT_L(0); PG8_MMA(0, 0, At, B0); PG8_BAR; PG8_SCHED;
;             PG8_LDB(B1, 0, 1); PG8_STAGE(PG8_SB(0, 0), b2, voffB);
;             PG8_BAR; PG8_WAIT_L(0); PG8_MMA(0, 1, At, B1); PG8_BAR;
;             PG8_LDA(At, 0, 1); PG8_STAGE(PG8_SA(0, 0), a2, voffA);
;             PG8_BAR; PG8_WAIT_L(0); PG8_MMA(1, 0, At, B0); PG8_BAR; PG8_SCHED;
;             PG8_STAGE(PG8_SB(0, 1), b2 + hstep, voffB);
;             PG8_WAIT_V(6); PG8_BAR; PG8_MMA(1, 1, At, B1); PG8_BAR;
.LBB0_113:
	s_add_u32 s54, s52, 0x100
	s_addc_u32 s55, s53, 0
	s_cmp_eq_u32 s73, 4
	s_cselect_b32 s59, s11, s55
	s_cselect_b32 s58, s29, s54
	s_cselect_b32 s57, s41, s72
	s_cselect_b32 s56, s45, s71
	v_lshl_add_u64 v[156:157], s[52:53], 0, v[134:135]
	s_add_i32 m0, s25, 0xc000
	s_nop 0
	global_load_lds_dwordx4 v[156:157], off
	v_lshl_add_u64 v[156:157], s[52:53], 0, v[132:133]
	s_add_i32 m0, s25, 0xe000
	s_nop 0
	global_load_lds_dwordx4 v[156:157], off
	s_add_i32 s38, 0, 0x10000
	v_add_u32_e32 v152, s38, v137
	ds_read_b128 v[140:143], v152
	ds_read_b128 v[144:147], v152 offset:1024
	ds_read_b128 v[148:151], v152 offset:2048
	ds_read_b128 v[152:155], v152 offset:3072
	ds_read_b128 v[160:163], v139
	ds_read_b128 v[164:167], v139 offset:1024
	ds_read_b128 v[168:171], v139 offset:2048
	ds_read_b128 v[172:175], v139 offset:3072
	ds_read_b128 v[176:179], v139 offset:4096
	ds_read_b128 v[180:183], v139 offset:5120
	ds_read_b128 v[184:187], v139 offset:6144
	ds_read_b128 v[188:191], v139 offset:7168
	s_add_i32 s52, 0, 0x14000
	v_add_u32_e32 v156, s52, v137
	ds_read_b128 v[192:195], v156
	ds_read_b128 v[196:199], v156 offset:1024
	ds_read_b128 v[200:203], v156 offset:2048
	ds_read_b128 v[204:207], v156 offset:3072
	s_waitcnt lgkmcnt(4)
	s_barrier
	s_waitcnt lgkmcnt(0)
	s_setprio 1
	v_mfma_f32_16x16x32_bf16 v[126:129], v[140:143], v[160:163], v[126:129]
	v_mfma_f32_16x16x32_bf16 v[122:125], v[148:151], v[160:163], v[122:125]
	v_mfma_f32_16x16x32_bf16 v[118:121], v[140:143], v[168:171], v[118:121]
	v_mfma_f32_16x16x32_bf16 v[114:117], v[148:151], v[168:171], v[114:117]
	v_mfma_f32_16x16x32_bf16 v[106:109], v[140:143], v[176:179], v[106:109]
	v_mfma_f32_16x16x32_bf16 v[98:101], v[148:151], v[176:179], v[98:101]
	v_mfma_f32_16x16x32_bf16 v[90:93], v[140:143], v[184:187], v[90:93]
	v_mfma_f32_16x16x32_bf16 v[82:85], v[148:151], v[184:187], v[82:85]
	v_mfma_f32_16x16x32_bf16 v[126:129], v[144:147], v[164:167], v[126:129]
	v_mfma_f32_16x16x32_bf16 v[122:125], v[152:155], v[164:167], v[122:125]
	v_mfma_f32_16x16x32_bf16 v[118:121], v[144:147], v[172:175], v[118:121]
	v_mfma_f32_16x16x32_bf16 v[114:117], v[152:155], v[172:175], v[114:117]
	v_mfma_f32_16x16x32_bf16 v[106:109], v[144:147], v[180:183], v[106:109]
	v_mfma_f32_16x16x32_bf16 v[98:101], v[152:155], v[180:183], v[98:101]
	v_mfma_f32_16x16x32_bf16 v[90:93], v[144:147], v[188:191], v[90:93]
	v_mfma_f32_16x16x32_bf16 v[82:85], v[152:155], v[188:191], v[82:85]
	v_mfma_f32_16x16x32_bf16 v[110:113], v[192:195], v[160:163], v[110:113]
	v_mfma_f32_16x16x32_bf16 v[102:105], v[200:203], v[160:163], v[102:105]
	v_mfma_f32_16x16x32_bf16 v[94:97], v[192:195], v[168:171], v[94:97]
	v_mfma_f32_16x16x32_bf16 v[86:89], v[200:203], v[168:171], v[86:89]
	v_mfma_f32_16x16x32_bf16 v[78:81], v[192:195], v[176:179], v[78:81]
	v_mfma_f32_16x16x32_bf16 v[74:77], v[200:203], v[176:179], v[74:77]
	v_mfma_f32_16x16x32_bf16 v[70:73], v[192:195], v[184:187], v[70:73]
	v_mfma_f32_16x16x32_bf16 v[66:69], v[200:203], v[184:187], v[66:69]
	v_mfma_f32_16x16x32_bf16 v[110:113], v[196:199], v[164:167], v[110:113]
	v_mfma_f32_16x16x32_bf16 v[102:105], v[204:207], v[164:167], v[102:105]
	v_mfma_f32_16x16x32_bf16 v[94:97], v[196:199], v[172:175], v[94:97]
	v_mfma_f32_16x16x32_bf16 v[86:89], v[204:207], v[172:175], v[86:89]
	v_mfma_f32_16x16x32_bf16 v[78:81], v[196:199], v[180:183], v[78:81]
	v_mfma_f32_16x16x32_bf16 v[74:77], v[204:207], v[180:183], v[74:77]
	v_mfma_f32_16x16x32_bf16 v[70:73], v[196:199], v[188:191], v[70:73]
	v_mfma_f32_16x16x32_bf16 v[66:69], v[204:207], v[188:191], v[66:69]
	s_setprio 0
	s_barrier
	ds_read_b128 v[160:163], v139 offset:16384
	ds_read_b128 v[164:167], v139 offset:17408
	ds_read_b128 v[168:171], v139 offset:18432
	ds_read_b128 v[172:175], v139 offset:19456
	ds_read_b128 v[176:179], v139 offset:20480
	ds_read_b128 v[180:183], v139 offset:21504
	ds_read_b128 v[184:187], v139 offset:22528
	ds_read_b128 v[188:191], v139 offset:23552
	s_add_i32 s38, s38, s65
	v_lshl_add_u64 v[156:157], s[56:57], 0, v[0:1]
	s_mov_b32 m0, s38
	v_lshl_add_u64 v[210:211], s[56:57], 0, v[130:131]
	global_load_lds_dwordx4 v[156:157], off
	s_add_i32 m0, s38, 0x2000
	s_nop 0
	global_load_lds_dwordx4 v[210:211], off
	s_mov_b32 m0, s25
	v_lshl_add_u64 v[212:213], s[58:59], 0, v[0:1]
	global_load_lds_dwordx4 v[212:213], off
	v_lshl_add_u64 v[214:215], s[58:59], 0, v[130:131]
	s_mov_b32 m0, s27
	s_nop 0
	global_load_lds_dwordx4 v[214:215], off
	s_waitcnt vmcnt(4)
	s_waitcnt lgkmcnt(0)
	s_barrier
	s_setprio 1
	v_mfma_f32_16x16x32_bf16 v[62:65], v[140:143], v[160:163], v[62:65]
	v_mfma_f32_16x16x32_bf16 v[58:61], v[148:151], v[160:163], v[58:61]
	v_mfma_f32_16x16x32_bf16 v[54:57], v[140:143], v[168:171], v[54:57]
	v_mfma_f32_16x16x32_bf16 v[50:53], v[148:151], v[168:171], v[50:53]
	v_mfma_f32_16x16x32_bf16 v[38:41], v[140:143], v[176:179], v[38:41]
	v_mfma_f32_16x16x32_bf16 v[34:37], v[148:151], v[176:179], v[34:37]
	v_mfma_f32_16x16x32_bf16 v[22:25], v[140:143], v[184:187], v[22:25]
	v_mfma_f32_16x16x32_bf16 v[18:21], v[148:151], v[184:187], v[18:21]
	v_mfma_f32_16x16x32_bf16 v[62:65], v[144:147], v[164:167], v[62:65]
	v_mfma_f32_16x16x32_bf16 v[58:61], v[152:155], v[164:167], v[58:61]
	v_mfma_f32_16x16x32_bf16 v[54:57], v[144:147], v[172:175], v[54:57]
	v_mfma_f32_16x16x32_bf16 v[50:53], v[152:155], v[172:175], v[50:53]
	v_mfma_f32_16x16x32_bf16 v[38:41], v[144:147], v[180:183], v[38:41]
	v_mfma_f32_16x16x32_bf16 v[34:37], v[152:155], v[180:183], v[34:37]
	v_mfma_f32_16x16x32_bf16 v[22:25], v[144:147], v[188:191], v[22:25]
	v_mfma_f32_16x16x32_bf16 v[18:21], v[152:155], v[188:191], v[18:21]
	v_mfma_f32_16x16x32_bf16 v[46:49], v[192:195], v[160:163], v[46:49]
	v_mfma_f32_16x16x32_bf16 v[42:45], v[200:203], v[160:163], v[42:45]
	v_mfma_f32_16x16x32_bf16 v[30:33], v[192:195], v[168:171], v[30:33]
	v_mfma_f32_16x16x32_bf16 v[26:29], v[200:203], v[168:171], v[26:29]
	v_mfma_f32_16x16x32_bf16 v[14:17], v[192:195], v[176:179], v[14:17]
	v_mfma_f32_16x16x32_bf16 v[10:13], v[200:203], v[176:179], v[10:13]
	v_mfma_f32_16x16x32_bf16 v[6:9], v[192:195], v[184:187], v[6:9]
	v_mfma_f32_16x16x32_bf16 v[2:5], v[200:203], v[184:187], v[2:5]
	v_mfma_f32_16x16x32_bf16 v[46:49], v[196:199], v[164:167], v[46:49]
	v_mfma_f32_16x16x32_bf16 v[42:45], v[204:207], v[164:167], v[42:45]
	v_mfma_f32_16x16x32_bf16 v[30:33], v[196:199], v[172:175], v[30:33]
	v_mfma_f32_16x16x32_bf16 v[26:29], v[204:207], v[172:175], v[26:29]
	v_mfma_f32_16x16x32_bf16 v[14:17], v[196:199], v[180:183], v[14:17]
	v_mfma_f32_16x16x32_bf16 v[10:13], v[204:207], v[180:183], v[10:13]
	v_mfma_f32_16x16x32_bf16 v[6:9], v[196:199], v[188:191], v[6:9]
	v_mfma_f32_16x16x32_bf16 v[2:5], v[204:207], v[188:191], v[2:5]
	s_setprio 0
	s_barrier
; #define PG8_STAGE(bufoff, gbase, voff) do { _Pragma("unroll") for (int _i = 0; _i < 2; ++_i) \
;         __builtin_amdgcn_global_load_lds((const unsigned*)((const char*)(gbase) + (voff)[_i]), (LAS unsigned*)(lds + (bufoff) + ldsw + _i * 8192), 16, 0, 0); } while (0)
; #define PG8_LDA(dst, b, h) do { _Pragma("unroll") for (int m = 0; m < 4; ++m) _Pragma("unroll") for (int k = 0; k < 2; ++k) dst[m][k] = *(const LAS bf16x8*)(lds + PG8_SA(b, h) + aoff + m * 2048 + k * 1024); } while (0)
; #define PG8_LDB(dst, b, h) do { _Pragma("unroll") for (int n = 0; n < 2; ++n) _Pragma("unroll") for (int k = 0; k < 2; ++k) dst[n][k] = *(const LAS bf16x8*)(lds + PG8_SB(b, h) + boff + n * 2048 + k * 1024); } while (0)
; #define PG8_MMA(ai, bj, At, Bt) do { __builtin_amdgcn_s_setprio(1); _Pragma("unroll") for (int m = 0; m < 4; ++m) _Pragma("unroll") for (int n = 0; n < 2; ++n) _Pragma("unroll") for (int k = 0; k < 2; ++k) \
;         acc[ai][bj][m][n] = __builtin_amdgcn_mfma_f32_16x16x32_bf16(Bt[n][k], At[m][k], acc[ai][bj][m][n], 0, 0, 0); __builtin_amdgcn_s_setprio(0); } while (0)
; #define PG8_WAIT_V(n) asm volatile("s_waitcnt vmcnt(" #n ")" ::: "memory")
; #define PG8_WAIT_L(n) asm volatile("s_waitcnt lgkmcnt(" #n ")" ::: "memory")
; #define PG8_BAR __builtin_amdgcn_s_barrier()
; #define PG8_SCHED __builtin_amdgcn_sched_barrier(0)
; template <class Epi, class Sched>
; __device__ __forceinline__ void gemm_phase(LAS unsigned char* lds, const Gemm g, const Sched& S, const Epi& E) {
;     ...
;             PG8_LDA(At, 0, 1); PG8_STAGE(PG8_SA(0, 0), a2, voffA);
;             PG8_BAR; PG8_WAIT_L(0); PG8_MMA(1, 0, At, B0); PG8_BAR; PG8_SCHED;
;             PG8_STAGE(PG8_SB(0, 1), b2 + hstep, voffB);
;             PG8_WAIT_V(6); PG8_BAR; PG8_MMA(1, 1, At, B1); PG8_BAR;
;             PG8_LDB(B0, 1, 0); PG8_SCHED; PG8_LDA(At, 1, 0); PG8_STAGE(PG8_SA(0, 1), a2 + hstep, voffA);
;             PG8_WAIT_L(8); PG8_BAR; PG8_WAIT_L(0); PG8_MMA(0, 0, At, B0); PG8_BAR; PG8_SCHED;
;             PG8_LDB(B1, 1, 1); PG8_STAGE(PG8_SB(1, 0), b3, voffB);
;             PG8_BAR; PG8_WAIT_L(0); PG8_MMA(0, 1, At, B1); PG8_BAR;
;             PG8_LDA(At, 1, 1); PG8_STAGE(PG8_SA(1, 0), a3, voffA);
	s_add_u32 s38, s56, 0x80000
	s_addc_u32 s39, s57, 0
	s_add_i32 s52, s52, s65
	v_lshl_add_u64 v[140:141], s[38:39], 0, v[0:1]
	s_mov_b32 m0, s52
	s_nop 0
	global_load_lds_dwordx4 v[140:141], off
	v_lshl_add_u64 v[140:141], s[38:39], 0, v[130:131]
	s_add_i32 m0, s52, 0x2000
	s_nop 0
	global_load_lds_dwordx4 v[140:141], off
	s_add_u32 s38, s58, 0x80000
	s_addc_u32 s39, s59, 0
	s_mov_b32 m0, s66
	v_lshl_add_u64 v[192:193], s[38:39], 0, v[0:1]
	global_load_lds_dwordx4 v[192:193], off
	v_lshl_add_u64 v[192:193], s[38:39], 0, v[130:131]
	s_mov_b32 m0, s67
	s_nop 0
	global_load_lds_dwordx4 v[192:193], off
	s_add_i32 s52, 0, 0x18000
	v_add_u32_e32 v152, s52, v137
	ds_read_b128 v[140:143], v152
	ds_read_b128 v[144:147], v152 offset:1024
	ds_read_b128 v[148:151], v152 offset:2048
	ds_read_b128 v[152:155], v152 offset:3072
	ds_read_b128 v[160:163], v139 offset:32768
	ds_read_b128 v[164:167], v139 offset:33792
	ds_read_b128 v[168:171], v139 offset:34816
	ds_read_b128 v[172:175], v139 offset:35840
	ds_read_b128 v[176:179], v139 offset:36864
	ds_read_b128 v[180:183], v139 offset:37888
	ds_read_b128 v[184:187], v139 offset:38912
	ds_read_b128 v[188:191], v139 offset:39936
	s_add_i32 s53, 0, 0x1c000
	v_add_u32_e32 v204, s53, v137
	ds_read_b128 v[192:195], v204
	ds_read_b128 v[196:199], v204 offset:1024
	ds_read_b128 v[200:203], v204 offset:2048
	ds_read_b128 v[204:207], v204 offset:3072
	s_waitcnt lgkmcnt(4)
	s_barrier
	s_waitcnt lgkmcnt(0)
	s_setprio 1
	v_mfma_f32_16x16x32_bf16 v[126:129], v[140:143], v[160:163], v[126:129]
	v_mfma_f32_16x16x32_bf16 v[122:125], v[148:151], v[160:163], v[122:125]
	v_mfma_f32_16x16x32_bf16 v[118:121], v[140:143], v[168:171], v[118:121]
	v_mfma_f32_16x16x32_bf16 v[114:117], v[148:151], v[168:171], v[114:117]
	v_mfma_f32_16x16x32_bf16 v[106:109], v[140:143], v[176:179], v[106:109]
	v_mfma_f32_16x16x32_bf16 v[98:101], v[148:151], v[176:179], v[98:101]
	v_mfma_f32_16x16x32_bf16 v[90:93], v[140:143], v[184:187], v[90:93]
	v_mfma_f32_16x16x32_bf16 v[82:85], v[148:151], v[184:187], v[82:85]
	v_mfma_f32_16x16x32_bf16 v[126:129], v[144:147], v[164:167], v[126:129]
	v_mfma_f32_16x16x32_bf16 v[122:125], v[152:155], v[164:167], v[122:125]
	v_mfma_f32_16x16x32_bf16 v[118:121], v[144:147], v[172:175], v[118:121]
	v_mfma_f32_16x16x32_bf16 v[114:117], v[152:155], v[172:175], v[114:117]
	v_mfma_f32_16x16x32_bf16 v[106:109], v[144:147], v[180:183], v[106:109]
	v_mfma_f32_16x16x32_bf16 v[98:101], v[152:155], v[180:183], v[98:101]
	v_mfma_f32_16x16x32_bf16 v[90:93], v[144:147], v[188:191], v[90:93]
	v_mfma_f32_16x16x32_bf16 v[82:85], v[152:155], v[188:191], v[82:85]
	v_mfma_f32_16x16x32_bf16 v[110:113], v[192:195], v[160:163], v[110:113]
	v_mfma_f32_16x16x32_bf16 v[102:105], v[200:203], v[160:163], v[102:105]
	v_mfma_f32_16x16x32_bf16 v[94:97], v[192:195], v[168:171], v[94:97]
	v_mfma_f32_16x16x32_bf16 v[86:89], v[200:203], v[168:171], v[86:89]
	v_mfma_f32_16x16x32_bf16 v[78:81], v[192:195], v[176:179], v[78:81]
	v_mfma_f32_16x16x32_bf16 v[74:77], v[200:203], v[176:179], v[74:77]
	v_mfma_f32_16x16x32_bf16 v[70:73], v[192:195], v[184:187], v[70:73]
	v_mfma_f32_16x16x32_bf16 v[66:69], v[200:203], v[184:187], v[66:69]
	v_mfma_f32_16x16x32_bf16 v[110:113], v[196:199], v[164:167], v[110:113]
	v_mfma_f32_16x16x32_bf16 v[102:105], v[204:207], v[164:167], v[102:105]
	v_mfma_f32_16x16x32_bf16 v[94:97], v[196:199], v[172:175], v[94:97]
	v_mfma_f32_16x16x32_bf16 v[86:89], v[204:207], v[172:175], v[86:89]
	v_mfma_f32_16x16x32_bf16 v[78:81], v[196:199], v[180:183], v[78:81]
	v_mfma_f32_16x16x32_bf16 v[74:77], v[204:207], v[180:183], v[74:77]
	v_mfma_f32_16x16x32_bf16 v[70:73], v[196:199], v[188:191], v[70:73]
	v_mfma_f32_16x16x32_bf16 v[66:69], v[204:207], v[188:191], v[66:69]
	s_setprio 0
	s_barrier
	ds_read_b128 v[160:163], v139 offset:49152
	ds_read_b128 v[164:167], v139 offset:50176
	ds_read_b128 v[168:171], v139 offset:51200
	ds_read_b128 v[172:175], v139 offset:52224
	ds_read_b128 v[176:179], v139 offset:53248
	ds_read_b128 v[180:183], v139 offset:54272
	ds_read_b128 v[184:187], v139 offset:55296
	ds_read_b128 v[188:191], v139 offset:56320
	s_add_i32 s38, s52, s65
	v_lshl_add_u64 v[156:157], v[156:157], 0, s[36:37]
	s_mov_b32 m0, s38
	s_nop 0
	global_load_lds_dwordx4 v[156:157], off
	v_lshl_add_u64 v[156:157], v[210:211], 0, s[36:37]
	s_add_i32 m0, s38, 0x2000
	s_nop 0
	global_load_lds_dwordx4 v[156:157], off
	s_mov_b32 m0, s68
	v_lshl_add_u64 v[156:157], v[212:213], 0, s[36:37]
	global_load_lds_dwordx4 v[156:157], off
	v_lshl_add_u64 v[156:157], v[214:215], 0, s[36:37]
	s_mov_b32 m0, s69
	s_nop 0
	global_load_lds_dwordx4 v[156:157], off
	s_waitcnt vmcnt(4)
	s_waitcnt lgkmcnt(0)
	s_barrier
; #define PG8_STAGE(bufoff, gbase, voff) do { _Pragma("unroll") for (int _i = 0; _i < 2; ++_i) \
;         __builtin_amdgcn_global_load_lds((const unsigned*)((const char*)(gbase) + (voff)[_i]), (LAS unsigned*)(lds + (bufoff) + ldsw + _i * 8192), 16, 0, 0); } while (0)
; #define PG8_LDA(dst, b, h) do { _Pragma("unroll") for (int m = 0; m < 4; ++m) _Pragma("unroll") for (int k = 0; k < 2; ++k) dst[m][k] = *(const LAS bf16x8*)(lds + PG8_SA(b, h) + aoff + m * 2048 + k * 1024); } while (0)
; #define PG8_MMA(ai, bj, At, Bt) do { __builtin_amdgcn_s_setprio(1); _Pragma("unroll") for (int m = 0; m < 4; ++m) _Pragma("unroll") for (int n = 0; n < 2; ++n) _Pragma("unroll") for (int k = 0; k < 2; ++k) \
;         acc[ai][bj][m][n] = __builtin_amdgcn_mfma_f32_16x16x32_bf16(Bt[n][k], At[m][k], acc[ai][bj][m][n], 0, 0, 0); __builtin_amdgcn_s_setprio(0); } while (0)
; #define PG8_WAIT_V(n) asm volatile("s_waitcnt vmcnt(" #n ")" ::: "memory")
; #define PG8_WAIT_L(n) asm volatile("s_waitcnt lgkmcnt(" #n ")" ::: "memory")
; #define PG8_BAR __builtin_amdgcn_s_barrier()
; #define PG8_SCHED __builtin_amdgcn_sched_barrier(0)
;     __device__ __forceinline__ void operator()(const f32x4 (&acc)[2][2][4][2], const Unit& u, int wr, int wc, int fr, int fq) const {
;         const int row0 = u.pm * BM + wr * 64 + fr, col0 = u.pn * BM + wc * 32 + 4 * fq;
;         float* base = part + (size_t)u.ks * Mp * ldc;
; #pragma unroll
;         for (int ai = 0; ai < 2; ++ai)
; #pragma unroll
;             for (int m = 0; m < 4; ++m) { float* rowp = base + (size_t)(row0 + ai * HALF + m * 16) * ldc + col0;
; #pragma unroll
;                 for (int bj = 0; bj < 2; ++bj)
; #pragma unroll
;                     for (int n = 0; n < 2; ++n) *(f32x4*)(rowp + bj * HALF + n * 16) = acc[ai][bj][m][n]; }
;     }
; template <class Epi, class Sched>
; __device__ __forceinline__ void gemm_phase(LAS unsigned char* lds, const Gemm g, const Sched& S, const Epi& E) {
;     ...
;             PG8_LDA(At, 1, 1); PG8_STAGE(PG8_SA(1, 0), a3, voffA);
;             PG8_BAR; PG8_WAIT_L(0); PG8_MMA(1, 0, At, B0); PG8_BAR; PG8_SCHED;
;             PG8_STAGE(PG8_SB(1, 1), b3 + hstep, voffB);
;             PG8_WAIT_V(6); PG8_BAR; PG8_MMA(1, 1, At, B1); PG8_BAR;
;         }
;         E(acc, cur, wr, wc, fr, fq);
;         if (!has_next) break;
	s_setprio 1
	v_mfma_f32_16x16x32_bf16 v[62:65], v[140:143], v[160:163], v[62:65]
	v_mfma_f32_16x16x32_bf16 v[58:61], v[148:151], v[160:163], v[58:61]
	v_mfma_f32_16x16x32_bf16 v[54:57], v[140:143], v[168:171], v[54:57]
	v_mfma_f32_16x16x32_bf16 v[50:53], v[148:151], v[168:171], v[50:53]
	v_mfma_f32_16x16x32_bf16 v[38:41], v[140:143], v[176:179], v[38:41]
	v_mfma_f32_16x16x32_bf16 v[34:37], v[148:151], v[176:179], v[34:37]
	v_mfma_f32_16x16x32_bf16 v[22:25], v[140:143], v[184:187], v[22:25]
	v_mfma_f32_16x16x32_bf16 v[18:21], v[148:151], v[184:187], v[18:21]
	v_mfma_f32_16x16x32_bf16 v[62:65], v[144:147], v[164:167], v[62:65]
	v_mfma_f32_16x16x32_bf16 v[58:61], v[152:155], v[164:167], v[58:61]
	v_mfma_f32_16x16x32_bf16 v[54:57], v[144:147], v[172:175], v[54:57]
	v_mfma_f32_16x16x32_bf16 v[50:53], v[152:155], v[172:175], v[50:53]
	v_mfma_f32_16x16x32_bf16 v[38:41], v[144:147], v[180:183], v[38:41]
	v_mfma_f32_16x16x32_bf16 v[34:37], v[152:155], v[180:183], v[34:37]
	v_mfma_f32_16x16x32_bf16 v[22:25], v[144:147], v[188:191], v[22:25]
	v_mfma_f32_16x16x32_bf16 v[18:21], v[152:155], v[188:191], v[18:21]
	s_add_u32 s38, s56, 0x80080
	s_addc_u32 s39, s57, 0
	s_add_i32 s52, s53, s65
	v_lshl_add_u64 v[140:141], s[38:39], 0, v[0:1]
	s_mov_b32 m0, s52
	s_nop 0
	global_load_lds_dwordx4 v[140:141], off
	v_lshl_add_u64 v[140:141], s[38:39], 0, v[130:131]
	s_add_i32 m0, s52, 0x2000
	s_nop 0
	global_load_lds_dwordx4 v[140:141], off
	v_mfma_f32_16x16x32_bf16 v[46:49], v[192:195], v[160:163], v[46:49]
	v_mfma_f32_16x16x32_bf16 v[42:45], v[200:203], v[160:163], v[42:45]
	v_mfma_f32_16x16x32_bf16 v[30:33], v[192:195], v[168:171], v[30:33]
	v_mfma_f32_16x16x32_bf16 v[26:29], v[200:203], v[168:171], v[26:29]
	v_mfma_f32_16x16x32_bf16 v[14:17], v[192:195], v[176:179], v[14:17]
	v_mfma_f32_16x16x32_bf16 v[10:13], v[200:203], v[176:179], v[10:13]
	v_mfma_f32_16x16x32_bf16 v[6:9], v[192:195], v[184:187], v[6:9]
	v_mfma_f32_16x16x32_bf16 v[2:5], v[200:203], v[184:187], v[2:5]
	v_mfma_f32_16x16x32_bf16 v[46:49], v[196:199], v[164:167], v[46:49]
	v_mfma_f32_16x16x32_bf16 v[42:45], v[204:207], v[164:167], v[42:45]
	v_mfma_f32_16x16x32_bf16 v[30:33], v[196:199], v[172:175], v[30:33]
	v_mfma_f32_16x16x32_bf16 v[26:29], v[204:207], v[172:175], v[26:29]
	v_mfma_f32_16x16x32_bf16 v[14:17], v[196:199], v[180:183], v[14:17]
	v_mfma_f32_16x16x32_bf16 v[10:13], v[204:207], v[180:183], v[10:13]
	v_mfma_f32_16x16x32_bf16 v[6:9], v[196:199], v[188:191], v[6:9]
	v_mfma_f32_16x16x32_bf16 v[2:5], v[204:207], v[188:191], v[2:5]
	s_setprio 0
	s_add_i32 s73, s73, 2
	s_add_u32 s71, s71, 0x100
	s_addc_u32 s72, s72, 0
	s_cmp_gt_u32 s73, 5
	s_mov_b64 s[52:53], s[54:55]
	s_barrier
	s_cbranch_scc0 .LBB0_113
	s_ashr_i32 s11, s10, 31
	s_lshl_b64 s[10:11], s[10:11], 24
	v_lshl_or_b32 v140, s26, 8, v138
	s_add_u32 s10, s8, s10
	v_lshl_add_u32 v142, s24, 8, v136
	s_addc_u32 s11, s9, s11
	v_ashrrev_i32_e32 v141, 31, v140
	v_ashrrev_i32_e32 v143, 31, v142
	v_lshl_add_u64 v[140:141], v[140:141], 2, s[10:11]
	v_lshlrev_b64 v[144:145], 13, v[142:143]
	v_lshl_add_u64 v[144:145], v[140:141], 0, v[144:145]
	global_store_dwordx4 v[144:145], v[126:129], off
	global_store_dwordx4 v[144:145], v[122:125], off offset:64
	global_store_dwordx4 v[144:145], v[110:113], off offset:512
	global_store_dwordx4 v[144:145], v[102:105], off offset:576
	s_mov_b64 s[10:11], 0x100000
	s_mov_b32 s26, s40
	v_or_b32_e32 v102, 16, v142
	v_ashrrev_i32_e32 v103, 31, v102
	v_lshlrev_b64 v[102:103], 13, v[102:103]
	v_lshl_add_u64 v[102:103], v[140:141], 0, v[102:103]
	global_store_dwordx4 v[102:103], v[118:121], off
	global_store_dwordx4 v[102:103], v[114:117], off offset:64
	global_store_dwordx4 v[102:103], v[94:97], off offset:512
	global_store_dwordx4 v[102:103], v[86:89], off offset:576
	s_mov_b32 s24, s44
	s_mov_b64 s[54:55], s[50:51]
	v_or_b32_e32 v86, 32, v142
	v_ashrrev_i32_e32 v87, 31, v86
	v_lshlrev_b64 v[86:87], 13, v[86:87]
	v_lshl_add_u64 v[86:87], v[140:141], 0, v[86:87]
	global_store_dwordx4 v[86:87], v[106:109], off
	global_store_dwordx4 v[86:87], v[98:101], off offset:64
	global_store_dwordx4 v[86:87], v[78:81], off offset:512
	global_store_dwordx4 v[86:87], v[74:77], off offset:576
	s_mov_b64 s[52:53], s[48:49]
	s_nop 0
	v_or_b32_e32 v74, 48, v142
	v_ashrrev_i32_e32 v75, 31, v74
	v_lshlrev_b64 v[74:75], 13, v[74:75]
	v_lshl_add_u64 v[74:75], v[140:141], 0, v[74:75]
	global_store_dwordx4 v[74:75], v[90:93], off
	global_store_dwordx4 v[74:75], v[82:85], off offset:64
	global_store_dwordx4 v[74:75], v[70:73], off offset:512
	global_store_dwordx4 v[74:75], v[66:69], off offset:576
	s_nop 1
	v_add_co_u32_e32 v68, vcc, s93, v144
	v_lshl_add_u64 v[66:67], v[144:145], 0, s[10:11]
	s_nop 0
	v_addc_co_u32_e32 v69, vcc, 0, v145, vcc
	s_mov_b64 s[10:11], 0x120000
	global_store_dwordx4 v[68:69], v[62:65], off
	global_store_dwordx4 v[66:67], v[58:61], off offset:64
	global_store_dwordx4 v[66:67], v[46:49], off offset:512
	global_store_dwordx4 v[66:67], v[42:45], off offset:576
	s_nop 1
	v_lshl_add_u64 v[42:43], v[144:145], 0, s[10:11]
	s_mov_b32 s10, 0x120000
	v_add_co_u32_e32 v44, vcc, s10, v144
	s_mov_b64 s[10:11], 0x140000
	s_nop 0
	v_addc_co_u32_e32 v45, vcc, 0, v145, vcc
	global_store_dwordx4 v[44:45], v[54:57], off
	global_store_dwordx4 v[42:43], v[50:53], off offset:64
	global_store_dwordx4 v[42:43], v[30:33], off offset:512
	global_store_dwordx4 v[42:43], v[26:29], off offset:576
	s_nop 1
	v_lshl_add_u64 v[26:27], v[144:145], 0, s[10:11]
	s_mov_b32 s10, 0x140000
	v_add_co_u32_e32 v28, vcc, s10, v144
	s_mov_b64 s[10:11], 0x160000
	s_nop 0
	v_addc_co_u32_e32 v29, vcc, 0, v145, vcc
	global_store_dwordx4 v[28:29], v[38:41], off
	global_store_dwordx4 v[26:27], v[34:37], off offset:64
	global_store_dwordx4 v[26:27], v[14:17], off offset:512
	global_store_dwordx4 v[26:27], v[10:13], off offset:576
	s_nop 1
	v_add_co_u32_e32 v12, vcc, 0x160000, v144
	v_lshl_add_u64 v[10:11], v[144:145], 0, s[10:11]
	s_nop 0
	v_addc_co_u32_e32 v13, vcc, 0, v145, vcc
	s_and_b64 vcc, exec, s[46:47]
	s_mov_b32 s10, s28
	global_store_dwordx4 v[12:13], v[22:25], off
	global_store_dwordx4 v[10:11], v[18:21], off offset:64
	global_store_dwordx4 v[10:11], v[6:9], off offset:512
	global_store_dwordx4 v[10:11], v[2:5], off offset:576
	s_cbranch_vccz .LBB0_110
	s_waitcnt vmcnt(0)
	s_cmpk_gt_u32 s60, 0xff
	s_cbranch_scc1 .LBB0_117
	s_barrier

; #define PG8_STAGE(bufoff, gbase, voff) do { _Pragma("unroll") for (int _i = 0; _i < 2; ++_i) \
;         __builtin_amdgcn_global_load_lds((const unsigned*)((const char*)(gbase) + (voff)[_i]), (LAS unsigned*)(lds + (bufoff) + ldsw + _i * 8192), 16, 0, 0); } while (0)
; #define PG8_LDA(dst, b, h) do { _Pragma("unroll") for (int m = 0; m < 4; ++m) _Pragma("unroll") for (int k = 0; k < 2; ++k) dst[m][k] = *(const LAS bf16x8*)(lds + PG8_SA(b, h) + aoff + m * 2048 + k * 1024); } while (0)
; #define PG8_LDB(dst, b, h) do { _Pragma("unroll") for (int n = 0; n < 2; ++n) _Pragma("unroll") for (int k = 0; k < 2; ++k) dst[n][k] = *(const LAS bf16x8*)(lds + PG8_SB(b, h) + boff + n * 2048 + k * 1024); } while (0)
; #define PG8_MMA(ai, bj, At, Bt) do { __builtin_amdgcn_s_setprio(1); _Pragma("unroll") for (int m = 0; m < 4; ++m) _Pragma("unroll") for (int n = 0; n < 2; ++n) _Pragma("unroll") for (int k = 0; k < 2; ++k) \
;         acc[ai][bj][m][n] = __builtin_amdgcn_mfma_f32_16x16x32_bf16(Bt[n][k], At[m][k], acc[ai][bj][m][n], 0, 0, 0); __builtin_amdgcn_s_setprio(0); } while (0)
; #define PG8_WAIT_V(n) asm volatile("s_waitcnt vmcnt(" #n ")" ::: "memory")
; #define PG8_WAIT_L(n) asm volatile("s_waitcnt lgkmcnt(" #n ")" ::: "memory")
; template <class Epi, class Sched>
; __device__ __forceinline__ void gemm_phase(LAS unsigned char* lds, const Gemm g, const Sched& S, const Epi& E) {
;     ...
;         for (int t = 0; t < nt; t += 2) {
;             const bool last = (t == nt - 2);
;             const char* a1 = cA + (size_t)(t + 1) * kstep;
;             const char* a2 = last ? nA : cA + (size_t)(t + 2) * kstep; const char* b2 = last ? nB : cB + (size_t)(t + 2) * kstep;
;             const char* a3 = a2 + kstep; const char* b3 = b2 + kstep;
;             PG8_LDB(B0, 0, 0); PG8_SCHED; PG8_LDA(At, 0, 0); PG8_STAGE(PG8_SA(1, 1), a1 + hstep, voffA);
;             PG8_WAIT_L(8); PG8_BAR; PG8_WAIT_L(0); PG8_MMA(0, 0, At, B0); PG8_BAR; PG8_SCHED;
;             PG8_LDB(B1, 0, 1); PG8_STAGE(PG8_SB(0, 0), b2, voffB);
;             PG8_BAR; PG8_WAIT_L(0); PG8_MMA(0, 1, At, B1); PG8_BAR;
;             PG8_LDA(At, 0, 1); PG8_STAGE(PG8_SA(0, 0), a2, voffA);
;             PG8_BAR; PG8_WAIT_L(0); PG8_MMA(1, 0, At, B0); PG8_BAR; PG8_SCHED;
;             PG8_STAGE(PG8_SB(0, 1), b2 + hstep, voffB);
;             PG8_WAIT_V(6); PG8_BAR; PG8_MMA(1, 1, At, B1); PG8_BAR;
.LBB0_354:
	s_add_u32 s38, s50, 0xfff80080
	s_addc_u32 s39, s51, -1
	s_cmp_eq_u32 s70, 28
	s_cselect_b32 s55, s9, s39
	s_cselect_b32 s54, s66, s38
	s_cselect_b32 s53, s43, s69
	s_cselect_b32 s52, s67, s68
	v_lshl_add_u64 v[156:157], s[50:51], 0, v[138:139]
	s_add_i32 m0, s29, 0xc000
	s_nop 0
	global_load_lds_dwordx4 v[156:157], off
	v_lshl_add_u64 v[156:157], s[50:51], 0, v[136:137]
	s_add_i32 m0, s29, 0xe000
	s_nop 0
	global_load_lds_dwordx4 v[156:157], off
	s_add_i32 s71, 0, 0x10000
	v_add_u32_e32 v156, s71, v145
	ds_read_b128 v[140:143], v156
	ds_read_b128 v[148:151], v156 offset:1024
	ds_read_b128 v[152:155], v156 offset:2048
	ds_read_b128 v[160:163], v156 offset:3072
	ds_read_b128 v[164:167], v147
	ds_read_b128 v[168:171], v147 offset:1024
	ds_read_b128 v[172:175], v147 offset:2048
	ds_read_b128 v[176:179], v147 offset:3072
	ds_read_b128 v[180:183], v147 offset:4096
	ds_read_b128 v[184:187], v147 offset:5120
	ds_read_b128 v[188:191], v147 offset:6144
	ds_read_b128 v[192:195], v147 offset:7168
	s_add_i32 s38, 0, 0x14000
	v_add_u32_e32 v156, s38, v145
	ds_read_b128 v[196:199], v156
	ds_read_b128 v[200:203], v156 offset:1024
	ds_read_b128 v[204:207], v156 offset:2048
	ds_read_b128 v[210:213], v156 offset:3072
	s_waitcnt lgkmcnt(4)
	s_barrier
	s_waitcnt lgkmcnt(0)
	s_setprio 1
	v_mfma_f32_16x16x32_bf16 v[126:129], v[140:143], v[164:167], v[126:129]
	v_mfma_f32_16x16x32_bf16 v[122:125], v[152:155], v[164:167], v[122:125]
	v_mfma_f32_16x16x32_bf16 v[118:121], v[140:143], v[172:175], v[118:121]
	v_mfma_f32_16x16x32_bf16 v[110:113], v[152:155], v[172:175], v[110:113]
	v_mfma_f32_16x16x32_bf16 v[102:105], v[140:143], v[180:183], v[102:105]
	v_mfma_f32_16x16x32_bf16 v[94:97], v[152:155], v[180:183], v[94:97]
	v_mfma_f32_16x16x32_bf16 v[86:89], v[140:143], v[188:191], v[86:89]
	v_mfma_f32_16x16x32_bf16 v[78:81], v[152:155], v[188:191], v[78:81]
	v_mfma_f32_16x16x32_bf16 v[126:129], v[148:151], v[168:171], v[126:129]
	v_mfma_f32_16x16x32_bf16 v[122:125], v[160:163], v[168:171], v[122:125]
	v_mfma_f32_16x16x32_bf16 v[118:121], v[148:151], v[176:179], v[118:121]
	v_mfma_f32_16x16x32_bf16 v[110:113], v[160:163], v[176:179], v[110:113]
	v_mfma_f32_16x16x32_bf16 v[102:105], v[148:151], v[184:187], v[102:105]
	v_mfma_f32_16x16x32_bf16 v[94:97], v[160:163], v[184:187], v[94:97]
	v_mfma_f32_16x16x32_bf16 v[86:89], v[148:151], v[192:195], v[86:89]
	v_mfma_f32_16x16x32_bf16 v[78:81], v[160:163], v[192:195], v[78:81]
	v_mfma_f32_16x16x32_bf16 v[114:117], v[196:199], v[164:167], v[114:117]
	v_mfma_f32_16x16x32_bf16 v[106:109], v[204:207], v[164:167], v[106:109]
	v_mfma_f32_16x16x32_bf16 v[98:101], v[196:199], v[172:175], v[98:101]
	v_mfma_f32_16x16x32_bf16 v[90:93], v[204:207], v[172:175], v[90:93]
	v_mfma_f32_16x16x32_bf16 v[82:85], v[196:199], v[180:183], v[82:85]
	v_mfma_f32_16x16x32_bf16 v[74:77], v[204:207], v[180:183], v[74:77]
	v_mfma_f32_16x16x32_bf16 v[70:73], v[196:199], v[188:191], v[70:73]
	v_mfma_f32_16x16x32_bf16 v[66:69], v[204:207], v[188:191], v[66:69]
	v_mfma_f32_16x16x32_bf16 v[114:117], v[200:203], v[168:171], v[114:117]
	v_mfma_f32_16x16x32_bf16 v[106:109], v[210:213], v[168:171], v[106:109]
	v_mfma_f32_16x16x32_bf16 v[98:101], v[200:203], v[176:179], v[98:101]
	v_mfma_f32_16x16x32_bf16 v[90:93], v[210:213], v[176:179], v[90:93]
	v_mfma_f32_16x16x32_bf16 v[82:85], v[200:203], v[184:187], v[82:85]
	v_mfma_f32_16x16x32_bf16 v[74:77], v[210:213], v[184:187], v[74:77]
	v_mfma_f32_16x16x32_bf16 v[70:73], v[200:203], v[192:195], v[70:73]
	v_mfma_f32_16x16x32_bf16 v[66:69], v[210:213], v[192:195], v[66:69]
	s_setprio 0
	s_barrier
	ds_read_b128 v[164:167], v147 offset:16384
	ds_read_b128 v[168:171], v147 offset:17408
	ds_read_b128 v[172:175], v147 offset:18432
	ds_read_b128 v[176:179], v147 offset:19456
	ds_read_b128 v[180:183], v147 offset:20480
	ds_read_b128 v[184:187], v147 offset:21504
	ds_read_b128 v[188:191], v147 offset:22528
	ds_read_b128 v[192:195], v147 offset:23552
	s_add_i32 s39, s71, s56
	v_lshl_add_u64 v[156:157], s[52:53], 0, v[0:1]
	s_mov_b32 m0, s39
	v_lshl_add_u64 v[214:215], s[52:53], 0, v[134:135]
	global_load_lds_dwordx4 v[156:157], off
	s_add_i32 m0, s39, 0x2000
	s_nop 0
	global_load_lds_dwordx4 v[214:215], off
	s_mov_b32 m0, s29
	v_lshl_add_u64 v[216:217], s[54:55], 0, v[130:131]
	global_load_lds_dwordx4 v[216:217], off
	v_lshl_add_u64 v[224:225], s[54:55], 0, v[132:133]
	s_mov_b32 m0, s41
	s_nop 0
	global_load_lds_dwordx4 v[224:225], off
	s_waitcnt vmcnt(4)
	s_waitcnt lgkmcnt(0)
	s_barrier
	s_setprio 1
	v_mfma_f32_16x16x32_bf16 v[62:65], v[140:143], v[164:167], v[62:65]
	v_mfma_f32_16x16x32_bf16 v[58:61], v[152:155], v[164:167], v[58:61]
	v_mfma_f32_16x16x32_bf16 v[54:57], v[140:143], v[172:175], v[54:57]
	v_mfma_f32_16x16x32_bf16 v[46:49], v[152:155], v[172:175], v[46:49]
	v_mfma_f32_16x16x32_bf16 v[38:41], v[140:143], v[180:183], v[38:41]
	v_mfma_f32_16x16x32_bf16 v[30:33], v[152:155], v[180:183], v[30:33]
	v_mfma_f32_16x16x32_bf16 v[22:25], v[140:143], v[188:191], v[22:25]
	v_mfma_f32_16x16x32_bf16 v[14:17], v[152:155], v[188:191], v[14:17]
	v_mfma_f32_16x16x32_bf16 v[62:65], v[148:151], v[168:171], v[62:65]
	v_mfma_f32_16x16x32_bf16 v[58:61], v[160:163], v[168:171], v[58:61]
	v_mfma_f32_16x16x32_bf16 v[54:57], v[148:151], v[176:179], v[54:57]
	v_mfma_f32_16x16x32_bf16 v[46:49], v[160:163], v[176:179], v[46:49]
	v_mfma_f32_16x16x32_bf16 v[38:41], v[148:151], v[184:187], v[38:41]
	v_mfma_f32_16x16x32_bf16 v[30:33], v[160:163], v[184:187], v[30:33]
	v_mfma_f32_16x16x32_bf16 v[22:25], v[148:151], v[192:195], v[22:25]
	v_mfma_f32_16x16x32_bf16 v[14:17], v[160:163], v[192:195], v[14:17]
	v_mfma_f32_16x16x32_bf16 v[50:53], v[196:199], v[164:167], v[50:53]
	v_mfma_f32_16x16x32_bf16 v[42:45], v[204:207], v[164:167], v[42:45]
	v_mfma_f32_16x16x32_bf16 v[34:37], v[196:199], v[172:175], v[34:37]
	v_mfma_f32_16x16x32_bf16 v[26:29], v[204:207], v[172:175], v[26:29]
	v_mfma_f32_16x16x32_bf16 v[18:21], v[196:199], v[180:183], v[18:21]
	v_mfma_f32_16x16x32_bf16 v[10:13], v[204:207], v[180:183], v[10:13]
	v_mfma_f32_16x16x32_bf16 v[6:9], v[196:199], v[188:191], v[6:9]
	v_mfma_f32_16x16x32_bf16 v[2:5], v[204:207], v[188:191], v[2:5]
	v_mfma_f32_16x16x32_bf16 v[50:53], v[200:203], v[168:171], v[50:53]
	v_mfma_f32_16x16x32_bf16 v[42:45], v[210:213], v[168:171], v[42:45]
	v_mfma_f32_16x16x32_bf16 v[34:37], v[200:203], v[176:179], v[34:37]
	v_mfma_f32_16x16x32_bf16 v[26:29], v[210:213], v[176:179], v[26:29]
	v_mfma_f32_16x16x32_bf16 v[18:21], v[200:203], v[184:187], v[18:21]
	v_mfma_f32_16x16x32_bf16 v[10:13], v[210:213], v[184:187], v[10:13]
	v_mfma_f32_16x16x32_bf16 v[6:9], v[200:203], v[192:195], v[6:9]
	v_mfma_f32_16x16x32_bf16 v[2:5], v[210:213], v[192:195], v[2:5]
	s_setprio 0
	s_barrier
; #define PG8_STAGE(bufoff, gbase, voff) do { _Pragma("unroll") for (int _i = 0; _i < 2; ++_i) \
;         __builtin_amdgcn_global_load_lds((const unsigned*)((const char*)(gbase) + (voff)[_i]), (LAS unsigned*)(lds + (bufoff) + ldsw + _i * 8192), 16, 0, 0); } while (0)
; #define PG8_LDA(dst, b, h) do { _Pragma("unroll") for (int m = 0; m < 4; ++m) _Pragma("unroll") for (int k = 0; k < 2; ++k) dst[m][k] = *(const LAS bf16x8*)(lds + PG8_SA(b, h) + aoff + m * 2048 + k * 1024); } while (0)
; #define PG8_LDB(dst, b, h) do { _Pragma("unroll") for (int n = 0; n < 2; ++n) _Pragma("unroll") for (int k = 0; k < 2; ++k) dst[n][k] = *(const LAS bf16x8*)(lds + PG8_SB(b, h) + boff + n * 2048 + k * 1024); } while (0)
; #define PG8_MMA(ai, bj, At, Bt) do { __builtin_amdgcn_s_setprio(1); _Pragma("unroll") for (int m = 0; m < 4; ++m) _Pragma("unroll") for (int n = 0; n < 2; ++n) _Pragma("unroll") for (int k = 0; k < 2; ++k) \
;         acc[ai][bj][m][n] = __builtin_amdgcn_mfma_f32_16x16x32_bf16(Bt[n][k], At[m][k], acc[ai][bj][m][n], 0, 0, 0); __builtin_amdgcn_s_setprio(0); } while (0)
; #define PG8_WAIT_V(n) asm volatile("s_waitcnt vmcnt(" #n ")" ::: "memory")
; #define PG8_WAIT_L(n) asm volatile("s_waitcnt lgkmcnt(" #n ")" ::: "memory")
; #define PG8_BAR __builtin_amdgcn_s_barrier()
; #define PG8_SCHED __builtin_amdgcn_sched_barrier(0)
; template <class Epi, class Sched>
; __device__ __forceinline__ void gemm_phase(LAS unsigned char* lds, const Gemm g, const Sched& S, const Epi& E) {
;     ...
;             PG8_LDA(At, 0, 1); PG8_STAGE(PG8_SA(0, 0), a2, voffA);
;             PG8_BAR; PG8_WAIT_L(0); PG8_MMA(1, 0, At, B0); PG8_BAR; PG8_SCHED;
;             PG8_STAGE(PG8_SB(0, 1), b2 + hstep, voffB);
;             PG8_WAIT_V(6); PG8_BAR; PG8_MMA(1, 1, At, B1); PG8_BAR;
;             PG8_LDB(B0, 1, 0); PG8_SCHED; PG8_LDA(At, 1, 0); PG8_STAGE(PG8_SA(0, 1), a2 + hstep, voffA);
;             PG8_WAIT_L(8); PG8_BAR; PG8_WAIT_L(0); PG8_MMA(0, 0, At, B0); PG8_BAR; PG8_SCHED;
;             PG8_LDB(B1, 1, 1); PG8_STAGE(PG8_SB(1, 0), b3, voffB);
;             PG8_BAR; PG8_WAIT_L(0); PG8_MMA(0, 1, At, B1); PG8_BAR;
;             PG8_LDA(At, 1, 1); PG8_STAGE(PG8_SA(1, 0), a3, voffA);
	s_add_u32 s72, s52, 0x80000
	s_addc_u32 s73, s53, 0
	s_add_i32 s38, s38, s56
	v_lshl_add_u64 v[140:141], s[72:73], 0, v[0:1]
	s_mov_b32 m0, s38
	s_nop 0
	global_load_lds_dwordx4 v[140:141], off
	v_lshl_add_u64 v[140:141], s[72:73], 0, v[134:135]
	s_add_i32 m0, s38, 0x2000
	s_nop 0
	global_load_lds_dwordx4 v[140:141], off
	s_add_u32 s54, s54, 0x80000
	s_addc_u32 s55, s55, 0
	s_mov_b32 m0, s57
	v_lshl_add_u64 v[196:197], s[54:55], 0, v[130:131]
	global_load_lds_dwordx4 v[196:197], off
	v_lshl_add_u64 v[196:197], s[54:55], 0, v[132:133]
	s_mov_b32 m0, s58
	s_nop 0
	global_load_lds_dwordx4 v[196:197], off
	s_add_i32 s38, 0, 0x18000
	v_add_u32_e32 v160, s38, v145
	ds_read_b128 v[140:143], v160
	ds_read_b128 v[148:151], v160 offset:1024
	ds_read_b128 v[152:155], v160 offset:2048
	ds_read_b128 v[160:163], v160 offset:3072
	ds_read_b128 v[164:167], v147 offset:32768
	ds_read_b128 v[168:171], v147 offset:33792
	ds_read_b128 v[172:175], v147 offset:34816
	ds_read_b128 v[176:179], v147 offset:35840
	ds_read_b128 v[180:183], v147 offset:36864
	ds_read_b128 v[184:187], v147 offset:37888
	ds_read_b128 v[188:191], v147 offset:38912
	ds_read_b128 v[192:195], v147 offset:39936
	s_add_i32 s39, 0, 0x1c000
	v_add_u32_e32 v210, s39, v145
	ds_read_b128 v[196:199], v210
	ds_read_b128 v[200:203], v210 offset:1024
	ds_read_b128 v[204:207], v210 offset:2048
	ds_read_b128 v[210:213], v210 offset:3072
	s_waitcnt lgkmcnt(4)
	s_barrier
	s_waitcnt lgkmcnt(0)
	s_setprio 1
	v_mfma_f32_16x16x32_bf16 v[126:129], v[140:143], v[164:167], v[126:129]
	v_mfma_f32_16x16x32_bf16 v[122:125], v[152:155], v[164:167], v[122:125]
	v_mfma_f32_16x16x32_bf16 v[118:121], v[140:143], v[172:175], v[118:121]
	v_mfma_f32_16x16x32_bf16 v[110:113], v[152:155], v[172:175], v[110:113]
	v_mfma_f32_16x16x32_bf16 v[102:105], v[140:143], v[180:183], v[102:105]
	v_mfma_f32_16x16x32_bf16 v[94:97], v[152:155], v[180:183], v[94:97]
	v_mfma_f32_16x16x32_bf16 v[86:89], v[140:143], v[188:191], v[86:89]
	v_mfma_f32_16x16x32_bf16 v[78:81], v[152:155], v[188:191], v[78:81]
	v_mfma_f32_16x16x32_bf16 v[126:129], v[148:151], v[168:171], v[126:129]
	v_mfma_f32_16x16x32_bf16 v[122:125], v[160:163], v[168:171], v[122:125]
	v_mfma_f32_16x16x32_bf16 v[118:121], v[148:151], v[176:179], v[118:121]
	v_mfma_f32_16x16x32_bf16 v[110:113], v[160:163], v[176:179], v[110:113]
	v_mfma_f32_16x16x32_bf16 v[102:105], v[148:151], v[184:187], v[102:105]
	v_mfma_f32_16x16x32_bf16 v[94:97], v[160:163], v[184:187], v[94:97]
	v_mfma_f32_16x16x32_bf16 v[86:89], v[148:151], v[192:195], v[86:89]
	v_mfma_f32_16x16x32_bf16 v[78:81], v[160:163], v[192:195], v[78:81]
	v_mfma_f32_16x16x32_bf16 v[114:117], v[196:199], v[164:167], v[114:117]
	v_mfma_f32_16x16x32_bf16 v[106:109], v[204:207], v[164:167], v[106:109]
	v_mfma_f32_16x16x32_bf16 v[98:101], v[196:199], v[172:175], v[98:101]
	v_mfma_f32_16x16x32_bf16 v[90:93], v[204:207], v[172:175], v[90:93]
	v_mfma_f32_16x16x32_bf16 v[82:85], v[196:199], v[180:183], v[82:85]
	v_mfma_f32_16x16x32_bf16 v[74:77], v[204:207], v[180:183], v[74:77]
	v_mfma_f32_16x16x32_bf16 v[70:73], v[196:199], v[188:191], v[70:73]
	v_mfma_f32_16x16x32_bf16 v[66:69], v[204:207], v[188:191], v[66:69]
	v_mfma_f32_16x16x32_bf16 v[114:117], v[200:203], v[168:171], v[114:117]
	v_mfma_f32_16x16x32_bf16 v[106:109], v[210:213], v[168:171], v[106:109]
	v_mfma_f32_16x16x32_bf16 v[98:101], v[200:203], v[176:179], v[98:101]
	v_mfma_f32_16x16x32_bf16 v[90:93], v[210:213], v[176:179], v[90:93]
	v_mfma_f32_16x16x32_bf16 v[82:85], v[200:203], v[184:187], v[82:85]
	v_mfma_f32_16x16x32_bf16 v[74:77], v[210:213], v[184:187], v[74:77]
	v_mfma_f32_16x16x32_bf16 v[70:73], v[200:203], v[192:195], v[70:73]
	v_mfma_f32_16x16x32_bf16 v[66:69], v[210:213], v[192:195], v[66:69]
	s_setprio 0
	s_barrier
	ds_read_b128 v[164:167], v147 offset:49152
	ds_read_b128 v[168:171], v147 offset:50176
	ds_read_b128 v[172:175], v147 offset:51200
	ds_read_b128 v[176:179], v147 offset:52224
	ds_read_b128 v[180:183], v147 offset:53248
	ds_read_b128 v[184:187], v147 offset:54272
	ds_read_b128 v[188:191], v147 offset:55296
	ds_read_b128 v[192:195], v147 offset:56320
	s_add_i32 s38, s38, s56
	v_lshl_add_u64 v[156:157], v[156:157], 0, s[36:37]
	s_mov_b32 m0, s38
	s_nop 0
	global_load_lds_dwordx4 v[156:157], off
	v_lshl_add_u64 v[156:157], v[214:215], 0, s[36:37]
	s_add_i32 m0, s38, 0x2000
	s_nop 0
	global_load_lds_dwordx4 v[156:157], off
	s_mov_b32 m0, s59
	v_lshl_add_u64 v[156:157], v[216:217], 0, s[36:37]
	global_load_lds_dwordx4 v[156:157], off
	v_lshl_add_u64 v[156:157], v[224:225], 0, s[36:37]
	s_mov_b32 m0, s60
	s_nop 0
	global_load_lds_dwordx4 v[156:157], off
	s_waitcnt vmcnt(4)
	s_waitcnt lgkmcnt(0)
	s_barrier
; #define PG8_STAGE(bufoff, gbase, voff) do { _Pragma("unroll") for (int _i = 0; _i < 2; ++_i) \
;         __builtin_amdgcn_global_load_lds((const unsigned*)((const char*)(gbase) + (voff)[_i]), (LAS unsigned*)(lds + (bufoff) + ldsw + _i * 8192), 16, 0, 0); } while (0)
; #define PG8_LDA(dst, b, h) do { _Pragma("unroll") for (int m = 0; m < 4; ++m) _Pragma("unroll") for (int k = 0; k < 2; ++k) dst[m][k] = *(const LAS bf16x8*)(lds + PG8_SA(b, h) + aoff + m * 2048 + k * 1024); } while (0)
; #define PG8_LDB(dst, b, h) do { _Pragma("unroll") for (int n = 0; n < 2; ++n) _Pragma("unroll") for (int k = 0; k < 2; ++k) dst[n][k] = *(const LAS bf16x8*)(lds + PG8_SB(b, h) + boff + n * 2048 + k * 1024); } while (0)
; #define PG8_MMA(ai, bj, At, Bt) do { __builtin_amdgcn_s_setprio(1); _Pragma("unroll") for (int m = 0; m < 4; ++m) _Pragma("unroll") for (int n = 0; n < 2; ++n) _Pragma("unroll") for (int k = 0; k < 2; ++k) \
;         acc[ai][bj][m][n] = __builtin_amdgcn_mfma_f32_16x16x32_bf16(Bt[n][k], At[m][k], acc[ai][bj][m][n], 0, 0, 0); __builtin_amdgcn_s_setprio(0); } while (0)
; #define PG8_WAIT_V(n) asm volatile("s_waitcnt vmcnt(" #n ")" ::: "memory")
; #define PG8_WAIT_L(n) asm volatile("s_waitcnt lgkmcnt(" #n ")" ::: "memory")
; #define PG8_BAR __builtin_amdgcn_s_barrier()
; #define PG8_SCHED __builtin_amdgcn_sched_barrier(0)
; template <class Epi, class Sched>
; __device__ __forceinline__ void gemm_phase(LAS unsigned char* lds, const Gemm g, const Sched& S, const Epi& E) {
;     ...
;             PG8_LDB(B1, 1, 1); PG8_STAGE(PG8_SB(1, 0), b3, voffB);
;             PG8_BAR; PG8_WAIT_L(0); PG8_MMA(0, 1, At, B1); PG8_BAR;
;             PG8_LDA(At, 1, 1); PG8_STAGE(PG8_SA(1, 0), a3, voffA);
;             PG8_BAR; PG8_WAIT_L(0); PG8_MMA(1, 0, At, B0); PG8_BAR; PG8_SCHED;
;             PG8_STAGE(PG8_SB(1, 1), b3 + hstep, voffB);
;             PG8_WAIT_V(6); PG8_BAR; PG8_MMA(1, 1, At, B1); PG8_BAR;
;         }
	s_setprio 1
	v_mfma_f32_16x16x32_bf16 v[62:65], v[140:143], v[164:167], v[62:65]
	v_mfma_f32_16x16x32_bf16 v[58:61], v[152:155], v[164:167], v[58:61]
	v_mfma_f32_16x16x32_bf16 v[54:57], v[140:143], v[172:175], v[54:57]
	v_mfma_f32_16x16x32_bf16 v[46:49], v[152:155], v[172:175], v[46:49]
	v_mfma_f32_16x16x32_bf16 v[38:41], v[140:143], v[180:183], v[38:41]
	v_mfma_f32_16x16x32_bf16 v[30:33], v[152:155], v[180:183], v[30:33]
	v_mfma_f32_16x16x32_bf16 v[22:25], v[140:143], v[188:191], v[22:25]
	v_mfma_f32_16x16x32_bf16 v[14:17], v[152:155], v[188:191], v[14:17]
	v_mfma_f32_16x16x32_bf16 v[62:65], v[148:151], v[168:171], v[62:65]
	v_mfma_f32_16x16x32_bf16 v[58:61], v[160:163], v[168:171], v[58:61]
	v_mfma_f32_16x16x32_bf16 v[54:57], v[148:151], v[176:179], v[54:57]
	v_mfma_f32_16x16x32_bf16 v[46:49], v[160:163], v[176:179], v[46:49]
	v_mfma_f32_16x16x32_bf16 v[38:41], v[148:151], v[184:187], v[38:41]
	v_mfma_f32_16x16x32_bf16 v[30:33], v[160:163], v[184:187], v[30:33]
	v_mfma_f32_16x16x32_bf16 v[22:25], v[148:151], v[192:195], v[22:25]
	v_mfma_f32_16x16x32_bf16 v[14:17], v[160:163], v[192:195], v[14:17]
	s_add_u32 s52, s52, 0x80080
	s_addc_u32 s53, s53, 0
	s_add_i32 s38, s39, s56
	v_lshl_add_u64 v[140:141], s[52:53], 0, v[0:1]
	s_mov_b32 m0, s38
	s_nop 0
	global_load_lds_dwordx4 v[140:141], off
	v_lshl_add_u64 v[140:141], s[52:53], 0, v[134:135]
	s_add_i32 m0, s38, 0x2000
	s_nop 0
	global_load_lds_dwordx4 v[140:141], off
	v_mfma_f32_16x16x32_bf16 v[50:53], v[196:199], v[164:167], v[50:53]
	v_mfma_f32_16x16x32_bf16 v[42:45], v[204:207], v[164:167], v[42:45]
	v_mfma_f32_16x16x32_bf16 v[34:37], v[196:199], v[172:175], v[34:37]
	v_mfma_f32_16x16x32_bf16 v[26:29], v[204:207], v[172:175], v[26:29]
	v_mfma_f32_16x16x32_bf16 v[18:21], v[196:199], v[180:183], v[18:21]
	v_mfma_f32_16x16x32_bf16 v[10:13], v[204:207], v[180:183], v[10:13]
	v_mfma_f32_16x16x32_bf16 v[6:9], v[196:199], v[188:191], v[6:9]
	v_mfma_f32_16x16x32_bf16 v[2:5], v[204:207], v[188:191], v[2:5]
	v_mfma_f32_16x16x32_bf16 v[50:53], v[200:203], v[168:171], v[50:53]
	v_mfma_f32_16x16x32_bf16 v[42:45], v[210:213], v[168:171], v[42:45]
	v_mfma_f32_16x16x32_bf16 v[34:37], v[200:203], v[176:179], v[34:37]
	v_mfma_f32_16x16x32_bf16 v[26:29], v[210:213], v[176:179], v[26:29]
	v_mfma_f32_16x16x32_bf16 v[18:21], v[200:203], v[184:187], v[18:21]
	v_mfma_f32_16x16x32_bf16 v[10:13], v[210:213], v[184:187], v[10:13]
	v_mfma_f32_16x16x32_bf16 v[6:9], v[200:203], v[192:195], v[6:9]
	v_mfma_f32_16x16x32_bf16 v[2:5], v[210:213], v[192:195], v[2:5]
	s_setprio 0
	s_add_i32 s70, s70, 2
	s_add_u32 s68, s68, 0x100
	s_addc_u32 s69, s69, 0
	s_add_u32 s50, s50, 0x100
	s_addc_u32 s51, s51, 0
	s_cmp_gt_u32 s70, 29
	s_barrier
	s_cbranch_scc0 .LBB0_354
; __device__ __forceinline__ unsigned cvt_pk_bf16(float lo, float hi) { unsigned r; asm("v_cvt_pk_bf16_f32 %0, %1, %2" : "=v"(r) : "v"(lo), "v"(hi)); return r; }
;     __device__ __forceinline__ void operator()(const f32x4 (&acc)[2][2][4][2], const Unit& u, int wr, int wc, int fr, int fq) const {
;         const int row0 = u.pm * BM + wr * 64 + fr, col0 = u.pn * BM + wc * 32 + 8 * fq;
; #pragma unroll
;         for (int ai = 0; ai < 2; ++ai)
; #pragma unroll
;             for (int m = 0; m < 4; ++m) { bf16_t* rowp = O + (size_t)(row0 + ai * HALF + m * 16) * ldc + col0;
; #pragma unroll
;                 for (int bj = 0; bj < 2; ++bj) { f32x4 v0 = acc[ai][bj][m][0], v1 = acc[ai][bj][m][1];
;                     if (ACT == 1) {
; #pragma unroll
;                         for (int j = 0; j < 4; ++j) { float a = fmaxf(v0[j], 0.f), b = fmaxf(v1[j], 0.f); v0[j] = a * a; v1[j] = b * b; } }
;                     u32x4 w; w.x = cvt_pk_bf16(v0[0], v0[1]); w.y = cvt_pk_bf16(v0[2], v0[3]); w.z = cvt_pk_bf16(v1[0], v1[1]); w.w = cvt_pk_bf16(v1[2], v1[3]);
;                     if (ACT == 1) __builtin_nontemporal_store(w, (u32x4*)(rowp + bj * HALF));
;                     else *(u32x4*)(rowp + bj * HALF) = w; } }
;     }
; template <class Epi, class Sched>
; __device__ __forceinline__ void gemm_phase(LAS unsigned char* lds, const Gemm g, const Sched& S, const Epi& E) {
;     ...
;         E(acc, cur, wr, wc, fr, fq);
;         if (!has_next) break;
; #pragma unroll
;         for (int a = 0; a < 2; ++a)
; #pragma unroll
;             for (int b = 0; b < 2; ++b)
; #pragma unroll
;                 for (int m = 0; m < 4; ++m)
; #pragma unroll
;                     for (int n = 0; n < 2; ++n) acc[a][b][m][n] = (f32x4){0.f, 0.f, 0.f, 0.f};
;         cur = nxt; cA = nA; cB = nB; ++ui;
	s_load_dwordx2 s[50:51], s[0:1], 0xc0
	v_lshl_add_u32 v150, s28, 8, v144
	v_lshl_or_b32 v142, s40, 8, v146
	v_ashrrev_i32_e32 v143, 31, v142
	v_cvt_pk_bf16_f32 v70, v70, v71
	s_waitcnt lgkmcnt(0)
	v_mov_b64_e32 v[140:141], s[50:51]
	v_cvt_pk_bf16_f32 v71, v72, v73
	v_cvt_pk_bf16_f32 v72, v66, v67
	v_add_u32_e32 v66, 0x80, v150
	v_mad_i64_i32 v[148:149], s[50:51], v150, s17, v[140:141]
	v_lshlrev_b64 v[142:143], 1, v[142:143]
	v_cvt_pk_bf16_f32 v114, v114, v115
	v_cvt_pk_bf16_f32 v115, v116, v117
	v_cvt_pk_bf16_f32 v116, v106, v107
	v_or_b32_e32 v106, 16, v150
	v_mad_i64_i32 v[66:67], s[50:51], v66, s17, v[140:141]
	v_cvt_pk_bf16_f32 v50, v50, v51
	v_cvt_pk_bf16_f32 v51, v52, v53
	v_cvt_pk_bf16_f32 v52, v42, v43
	v_add_u32_e32 v42, 0x90, v150
	v_lshl_add_u64 v[148:149], v[148:149], 0, v[142:143]
	v_mad_i64_i32 v[106:107], s[50:51], v106, s17, v[140:141]
	v_cvt_pk_bf16_f32 v98, v98, v99
	v_cvt_pk_bf16_f32 v99, v100, v101
	v_cvt_pk_bf16_f32 v100, v90, v91
	v_or_b32_e32 v90, 32, v150
	v_lshl_add_u64 v[66:67], v[66:67], 0, v[142:143]
	v_mad_i64_i32 v[42:43], s[50:51], v42, s17, v[140:141]
	v_cvt_pk_bf16_f32 v34, v34, v35
	v_cvt_pk_bf16_f32 v35, v36, v37
	v_cvt_pk_bf16_f32 v36, v26, v27
	v_add_u32_e32 v26, 0xa0, v150
	v_cvt_pk_bf16_f32 v117, v108, v109
	global_store_dwordx4 v[148:149], v[114:117], off offset:256
	v_mad_i64_i32 v[90:91], s[50:51], v90, s17, v[140:141]
	s_nop 0
	v_lshl_add_u64 v[114:115], v[106:107], 0, v[142:143]
	v_cvt_pk_bf16_f32 v82, v82, v83
	v_cvt_pk_bf16_f32 v83, v84, v85
	v_cvt_pk_bf16_f32 v84, v74, v75
	v_or_b32_e32 v74, 48, v150
	v_cvt_pk_bf16_f32 v53, v44, v45
	global_store_dwordx4 v[66:67], v[50:53], off offset:256
	v_mad_i64_i32 v[26:27], s[50:51], v26, s17, v[140:141]
	s_nop 0
	v_lshl_add_u64 v[50:51], v[42:43], 0, v[142:143]
	v_cvt_pk_bf16_f32 v18, v18, v19
	v_cvt_pk_bf16_f32 v19, v20, v21
	v_cvt_pk_bf16_f32 v20, v10, v11
	v_add_u32_e32 v10, 0xb0, v150
	v_cvt_pk_bf16_f32 v101, v92, v93
	global_store_dwordx4 v[114:115], v[98:101], off offset:256
	v_mad_i64_i32 v[74:75], s[50:51], v74, s17, v[140:141]
	s_nop 0
	v_lshl_add_u64 v[98:99], v[90:91], 0, v[142:143]
	v_cvt_pk_bf16_f32 v37, v28, v29
	global_store_dwordx4 v[50:51], v[34:37], off offset:256
	v_mad_i64_i32 v[10:11], s[50:51], v10, s17, v[140:141]
	s_nop 0
	v_lshl_add_u64 v[34:35], v[26:27], 0, v[142:143]
	v_cvt_pk_bf16_f32 v85, v76, v77
	global_store_dwordx4 v[98:99], v[82:85], off offset:256
	v_cvt_pk_bf16_f32 v21, v12, v13
	global_store_dwordx4 v[34:35], v[18:21], off offset:256
	s_and_b64 vcc, exec, s[46:47]
	v_lshl_add_u64 v[82:83], v[74:75], 0, v[142:143]
	v_lshl_add_u64 v[18:19], v[10:11], 0, v[142:143]
	s_mov_b32 s40, s42
	s_mov_b32 s28, s8
	s_mov_b32 s43, s42
	s_mov_b32 s46, s8
	s_mov_b64 s[50:51], s[48:49]
	s_mov_b64 s[52:53], s[44:45]
	v_cvt_pk_bf16_f32 v126, v126, v127
	v_cvt_pk_bf16_f32 v127, v128, v129
	v_cvt_pk_bf16_f32 v128, v122, v123
	v_cvt_pk_bf16_f32 v129, v124, v125
	global_store_dwordx4 v[148:149], v[126:129], off
	v_cvt_pk_bf16_f32 v106, v118, v119
	v_cvt_pk_bf16_f32 v107, v120, v121
	v_cvt_pk_bf16_f32 v108, v110, v111
	v_cvt_pk_bf16_f32 v109, v112, v113
	global_store_dwordx4 v[114:115], v[106:109], off
	v_cvt_pk_bf16_f32 v90, v102, v103
	v_cvt_pk_bf16_f32 v91, v104, v105
	v_cvt_pk_bf16_f32 v92, v94, v95
	v_cvt_pk_bf16_f32 v93, v96, v97
	global_store_dwordx4 v[98:99], v[90:93], off
	v_cvt_pk_bf16_f32 v74, v86, v87
	v_cvt_pk_bf16_f32 v75, v88, v89
	v_cvt_pk_bf16_f32 v76, v78, v79
	v_cvt_pk_bf16_f32 v77, v80, v81
	global_store_dwordx4 v[82:83], v[74:77], off
	v_cvt_pk_bf16_f32 v73, v68, v69
	global_store_dwordx4 v[82:83], v[70:73], off offset:256
	v_cvt_pk_bf16_f32 v62, v62, v63
	v_cvt_pk_bf16_f32 v63, v64, v65
	v_cvt_pk_bf16_f32 v64, v58, v59
	v_cvt_pk_bf16_f32 v65, v60, v61
	global_store_dwordx4 v[66:67], v[62:65], off
	v_cvt_pk_bf16_f32 v42, v54, v55
	v_cvt_pk_bf16_f32 v43, v56, v57
	v_cvt_pk_bf16_f32 v44, v46, v47
	v_cvt_pk_bf16_f32 v45, v48, v49
	global_store_dwordx4 v[50:51], v[42:45], off
	v_cvt_pk_bf16_f32 v26, v38, v39
	v_cvt_pk_bf16_f32 v27, v40, v41
	v_cvt_pk_bf16_f32 v28, v30, v31
	v_cvt_pk_bf16_f32 v29, v32, v33
	global_store_dwordx4 v[34:35], v[26:29], off
	v_cvt_pk_bf16_f32 v10, v22, v23
	v_cvt_pk_bf16_f32 v11, v24, v25
	v_cvt_pk_bf16_f32 v12, v14, v15
	v_cvt_pk_bf16_f32 v13, v16, v17
	global_store_dwordx4 v[18:19], v[10:13], off
	v_cvt_pk_bf16_f32 v6, v6, v7
	v_cvt_pk_bf16_f32 v7, v8, v9
	v_cvt_pk_bf16_f32 v8, v2, v3
	v_cvt_pk_bf16_f32 v9, v4, v5
	global_store_dwordx4 v[18:19], v[6:9], off offset:256
	s_cbranch_vccz .LBB0_346
	s_waitcnt vmcnt(0)
	s_cmpk_gt_u32 s25, 0xff
	s_cbranch_scc1 .LBB0_358
	s_barrier
